# priority A/B: K-loop flips inverted (priority raised for the loading part, lowered for the MFMA cluster)
# baseline (speedup 1.0000x reference)
; #define LDA(dst, b, h) for (int m = 0; m < 4; ++m) for (int k = 0; k < 2; ++k) \
;     dst[m][k] = *reinterpret_cast<const bf16x8*>((char*)SA(b, h) + lds_byte(wr * 64 + m * 16 + fr, k * 32 + fq * 8))
; #define LDB(dst, b, h) for (int n = 0; n < 2; ++n) for (int k = 0; k < 2; ++k) \
;     dst[n][k] = *reinterpret_cast<const bf16x8*>((char*)SB(b, h) + lds_byte(wc * 32 + n * 16 + fr, k * 32 + fq * 8))
; #define MMA(ai, bj, At_, Bt_) do { __builtin_amdgcn_s_setprio(1); \
;     for (int m = 0; m < 4; ++m) for (int n = 0; n < 2; ++n) for (int k = 0; k < 2; ++k) \
;       acc[ai][bj][m][n] = MFMA16(Bt_[n][k], At_[m][k], acc[ai][bj][m][n]); \
;     __builtin_amdgcn_s_setprio(0); } while (0)
; #define WAIT_L(n) asm volatile("s_waitcnt lgkmcnt(" #n ")" ::: "memory")
; #define BAR __builtin_amdgcn_s_barrier()
; #define SCHED __builtin_amdgcn_sched_barrier(0)
; template <int PART  , bool SYNC_FIRST = true>
; __device__ __forceinline__ void kloop_t(const u16* __restrict__ A, int lda, const u16* __restrict__ Bt, int ldb, int K, Acc& acc, const int wv) {
;     ...
;     LDB(B0, 0, 0); SCHED; LDA(At, 0, 0); STAGE(SA(1, 1), A, lda, HALF, t + 1);
;     WAIT_L(8); BAR; WAIT_L(0); MMA(0, 0, At, B0); BAR; SCHED;
;     LDB(B1, 0, 1); STAGE(SB(0, 0), Bt, ldb, 0, t + 2);
;     BAR; WAIT_L(0); MMA(0, 1, At, B1); BAR;
;     LDA(At, 0, 1); STAGE(SA(0, 0), A, lda, 0, t + 2);
.LBB0_193:
	v_add_u32_e32 v157, v149, v153
	v_add_u32_e32 v159, v149, v155
	v_add_u32_e32 v158, v149, v154
	ds_read_b128 v[168:171], v157
	ds_read_b128 v[172:175], v158
	v_add_u32_e32 v160, v149, v156
	ds_read_b128 v[176:179], v159
	ds_read_b128 v[180:183], v160
	s_add_u32 s42, s4, s40
	v_mov_b32_e32 v162, v141
	v_mov_b32_e32 v128, v139
	s_addc_u32 s43, s5, s41
	v_add_u32_e32 v161, 0xc000, v144
	ds_read_b128 v[184:187], v130
	ds_read_b128 v[188:191], v131
	ds_read_b128 v[192:195], v132
	ds_read_b128 v[196:199], v133
	ds_read_b128 v[200:203], v134
	ds_read_b128 v[204:207], v135
	ds_read_b128 v[208:211], v137
	ds_read_b128 v[212:215], v138
	v_readfirstlane_b32 s44, v161
	v_lshl_add_u64 v[164:165], s[42:43], 0, v[128:129]
	v_mov_b32_e32 v163, v129
	v_lshl_add_u64 v[164:165], v[164:165], 0, s[14:15]
	s_mov_b32 m0, s44
	v_lshl_add_u64 v[162:163], s[42:43], 0, v[162:163]
	global_load_lds_dwordx4 v[164:165], off
	v_lshl_add_u64 v[164:165], v[162:163], 0, s[14:15]
	v_add_u32_e32 v162, 0xe000, v144
	s_nop 0
	v_readfirstlane_b32 s44, v162
	s_mov_b32 m0, s44
	s_nop 0
	global_load_lds_dwordx4 v[164:165], off
	s_waitcnt lgkmcnt(8)
	s_barrier
	s_waitcnt lgkmcnt(0)
	s_setprio 0
	s_waitcnt lgkmcnt(0)
	v_mfma_f32_16x16x32_bf16 v[124:127], v[168:171], v[184:187], v[124:127]
	v_mfma_f32_16x16x32_bf16 v[120:123], v[176:179], v[184:187], v[120:123]
	v_mfma_f32_16x16x32_bf16 v[116:119], v[168:171], v[192:195], v[116:119]
	v_mfma_f32_16x16x32_bf16 v[112:115], v[176:179], v[192:195], v[112:115]
	v_mfma_f32_16x16x32_bf16 v[108:111], v[168:171], v[200:203], v[108:111]
	v_mfma_f32_16x16x32_bf16 v[104:107], v[176:179], v[200:203], v[104:107]
	v_mfma_f32_16x16x32_bf16 v[100:103], v[168:171], v[208:211], v[100:103]
	v_mfma_f32_16x16x32_bf16 v[96:99], v[176:179], v[208:211], v[96:99]
	v_mfma_f32_16x16x32_bf16 v[124:127], v[172:175], v[188:191], v[124:127]
	v_mfma_f32_16x16x32_bf16 v[120:123], v[180:183], v[188:191], v[120:123]
	v_mfma_f32_16x16x32_bf16 v[116:119], v[172:175], v[196:199], v[116:119]
	v_mfma_f32_16x16x32_bf16 v[112:115], v[180:183], v[196:199], v[112:115]
	v_mfma_f32_16x16x32_bf16 v[108:111], v[172:175], v[204:207], v[108:111]
	v_mfma_f32_16x16x32_bf16 v[104:107], v[180:183], v[204:207], v[104:107]
	v_mfma_f32_16x16x32_bf16 v[100:103], v[172:175], v[212:215], v[100:103]
	v_mfma_f32_16x16x32_bf16 v[96:99], v[180:183], v[212:215], v[96:99]
	s_setprio 1
	s_barrier
	v_add_u32_e32 v163, v150, v153
	v_add_u32_e32 v165, v150, v155
	v_mov_b32_e32 v232, v141
	v_mov_b32_e32 v128, v139
	s_add_u32 s44, s36, s40
	v_add_u32_e32 v164, v150, v154
	ds_read_b128 v[216:219], v163
	ds_read_b128 v[220:223], v164
	v_add_u32_e32 v166, v150, v156
	ds_read_b128 v[224:227], v165
	ds_read_b128 v[228:231], v166
	s_addc_u32 s45, s37, s41
	v_lshl_add_u64 v[234:235], s[44:45], 0, v[128:129]
	v_add_u32_e32 v128, s31, v140
	v_mov_b32_e32 v233, v129
	v_readfirstlane_b32 s53, v128
	v_add_u32_e32 v128, 0x2000, v128
	v_lshl_add_u64 v[234:235], v[234:235], 0, s[16:17]
	s_mov_b32 m0, s53
	v_lshl_add_u64 v[232:233], s[44:45], 0, v[232:233]
	v_readfirstlane_b32 s53, v128
	global_load_lds_dwordx4 v[234:235], off
	v_lshl_add_u64 v[232:233], v[232:233], 0, s[16:17]
	s_mov_b32 m0, s53
	s_nop 0
	global_load_lds_dwordx4 v[232:233], off
	s_barrier
	s_waitcnt lgkmcnt(0)
	s_setprio 0
	s_waitcnt lgkmcnt(0)
	v_mfma_f32_16x16x32_bf16 v[92:95], v[216:219], v[184:187], v[92:95]
	v_mfma_f32_16x16x32_bf16 v[88:91], v[224:227], v[184:187], v[88:91]
	v_mfma_f32_16x16x32_bf16 v[84:87], v[216:219], v[192:195], v[84:87]
	v_mfma_f32_16x16x32_bf16 v[80:83], v[224:227], v[192:195], v[80:83]
	v_mfma_f32_16x16x32_bf16 v[76:79], v[216:219], v[200:203], v[76:79]
	v_mfma_f32_16x16x32_bf16 v[72:75], v[224:227], v[200:203], v[72:75]
	v_mfma_f32_16x16x32_bf16 v[68:71], v[216:219], v[208:211], v[68:71]
	v_mfma_f32_16x16x32_bf16 v[64:67], v[224:227], v[208:211], v[64:67]
	v_mfma_f32_16x16x32_bf16 v[92:95], v[220:223], v[188:191], v[92:95]
	v_mfma_f32_16x16x32_bf16 v[88:91], v[228:231], v[188:191], v[88:91]
	v_mfma_f32_16x16x32_bf16 v[84:87], v[220:223], v[196:199], v[84:87]
	v_mfma_f32_16x16x32_bf16 v[80:83], v[228:231], v[196:199], v[80:83]
	v_mfma_f32_16x16x32_bf16 v[76:79], v[220:223], v[204:207], v[76:79]
	v_mfma_f32_16x16x32_bf16 v[72:75], v[228:231], v[204:207], v[72:75]
	v_mfma_f32_16x16x32_bf16 v[68:71], v[220:223], v[212:215], v[68:71]
	v_mfma_f32_16x16x32_bf16 v[64:67], v[228:231], v[212:215], v[64:67]
	s_setprio 1
	v_mov_b32_e32 v232, v141
	v_mov_b32_e32 v128, v139
	s_barrier
	ds_read_b128 v[184:187], v130 offset:16384
	ds_read_b128 v[188:191], v131 offset:16384
	ds_read_b128 v[192:195], v132 offset:16384
	ds_read_b128 v[196:199], v133 offset:16384
	ds_read_b128 v[200:203], v134 offset:16384
	ds_read_b128 v[204:207], v135 offset:16384
	ds_read_b128 v[208:211], v137 offset:16384
	ds_read_b128 v[212:215], v138 offset:16384
	v_readfirstlane_b32 s53, v144
	v_lshl_add_u64 v[234:235], s[42:43], 0, v[128:129]
	v_mov_b32_e32 v233, v129
	v_add_u32_e32 v128, 0x2000, v144
	v_lshl_add_u64 v[234:235], v[234:235], 0, s[16:17]
	s_mov_b32 m0, s53
	v_lshl_add_u64 v[232:233], s[42:43], 0, v[232:233]
	v_readfirstlane_b32 s53, v128
	global_load_lds_dwordx4 v[234:235], off
	v_lshl_add_u64 v[232:233], v[232:233], 0, s[16:17]
	s_mov_b32 m0, s53
	s_nop 0
	global_load_lds_dwordx4 v[232:233], off
	s_barrier
; #define LDA(dst, b, h) for (int m = 0; m < 4; ++m) for (int k = 0; k < 2; ++k) \
;     dst[m][k] = *reinterpret_cast<const bf16x8*>((char*)SA(b, h) + lds_byte(wr * 64 + m * 16 + fr, k * 32 + fq * 8))
; #define LDB(dst, b, h) for (int n = 0; n < 2; ++n) for (int k = 0; k < 2; ++k) \
;     dst[n][k] = *reinterpret_cast<const bf16x8*>((char*)SB(b, h) + lds_byte(wc * 32 + n * 16 + fr, k * 32 + fq * 8))
; #define MMA(ai, bj, At_, Bt_) do { __builtin_amdgcn_s_setprio(1); \
;     for (int m = 0; m < 4; ++m) for (int n = 0; n < 2; ++n) for (int k = 0; k < 2; ++k) \
;       acc[ai][bj][m][n] = MFMA16(Bt_[n][k], At_[m][k], acc[ai][bj][m][n]); \
;     __builtin_amdgcn_s_setprio(0); } while (0)
; #define WAIT_V(n) asm volatile("s_waitcnt vmcnt(" #n ")" ::: "memory")
; #define WAIT_L(n) asm volatile("s_waitcnt lgkmcnt(" #n ")" ::: "memory")
; #define BAR __builtin_amdgcn_s_barrier()
; #define SCHED __builtin_amdgcn_sched_barrier(0)
; template <int PART  , bool SYNC_FIRST = true>
; __device__ __forceinline__ void kloop_t(const u16* __restrict__ A, int lda, const u16* __restrict__ Bt, int ldb, int K, Acc& acc, const int wv) {
;     ...
;     BAR; WAIT_L(0); MMA(1, 0, At, B0); BAR; SCHED;
;     STAGE(SB(0, 1), Bt, ldb, HALF, t + 2);
;     WAIT_V(6); BAR; MMA(1, 1, At, B1); BAR;
;     LDB(B0, 1, 0); SCHED; LDA(At, 1, 0); STAGE(SA(0, 1), A, lda, HALF, t + 2);
;     WAIT_L(8); BAR; WAIT_L(0); MMA(0, 0, At, B0); BAR; SCHED;
	s_waitcnt lgkmcnt(0)
	s_setprio 0
	s_waitcnt lgkmcnt(0)
	v_mfma_f32_16x16x32_bf16 v[60:63], v[168:171], v[184:187], v[60:63]
	v_mfma_f32_16x16x32_bf16 v[56:59], v[176:179], v[184:187], v[56:59]
	v_mfma_f32_16x16x32_bf16 v[52:55], v[168:171], v[192:195], v[52:55]
	v_mfma_f32_16x16x32_bf16 v[48:51], v[176:179], v[192:195], v[48:51]
	v_mfma_f32_16x16x32_bf16 v[44:47], v[168:171], v[200:203], v[44:47]
	v_mfma_f32_16x16x32_bf16 v[40:43], v[176:179], v[200:203], v[40:43]
	v_mfma_f32_16x16x32_bf16 v[36:39], v[168:171], v[208:211], v[36:39]
	v_mfma_f32_16x16x32_bf16 v[32:35], v[176:179], v[208:211], v[32:35]
	v_mfma_f32_16x16x32_bf16 v[60:63], v[172:175], v[188:191], v[60:63]
	v_mfma_f32_16x16x32_bf16 v[56:59], v[180:183], v[188:191], v[56:59]
	v_mfma_f32_16x16x32_bf16 v[52:55], v[172:175], v[196:199], v[52:55]
	v_mfma_f32_16x16x32_bf16 v[48:51], v[180:183], v[196:199], v[48:51]
	v_mfma_f32_16x16x32_bf16 v[44:47], v[172:175], v[204:207], v[44:47]
	v_mfma_f32_16x16x32_bf16 v[40:43], v[180:183], v[204:207], v[40:43]
	v_mfma_f32_16x16x32_bf16 v[36:39], v[172:175], v[212:215], v[36:39]
	v_mfma_f32_16x16x32_bf16 v[32:35], v[180:183], v[212:215], v[32:35]
	s_setprio 1
	s_barrier
	v_mov_b32_e32 v168, v141
	v_mov_b32_e32 v128, v139
	v_mov_b32_e32 v169, v129
	v_lshl_add_u64 v[170:171], s[44:45], 0, v[128:129]
	v_add_u32_e32 v128, s35, v140
	v_lshl_add_u64 v[170:171], v[170:171], 0, s[18:19]
	v_readfirstlane_b32 s53, v128
	v_add_u32_e32 v128, 0x2000, v128
	s_mov_b32 m0, s53
	v_lshl_add_u64 v[168:169], s[44:45], 0, v[168:169]
	v_readfirstlane_b32 s53, v128
	global_load_lds_dwordx4 v[170:171], off
	v_lshl_add_u64 v[168:169], v[168:169], 0, s[18:19]
	s_mov_b32 m0, s53
	s_nop 0
	global_load_lds_dwordx4 v[168:169], off
	s_waitcnt vmcnt(6)
	s_barrier
	s_setprio 0
	v_mfma_f32_16x16x32_bf16 v[28:31], v[216:219], v[184:187], v[28:31]
	v_mfma_f32_16x16x32_bf16 v[24:27], v[224:227], v[184:187], v[24:27]
	v_mfma_f32_16x16x32_bf16 v[20:23], v[216:219], v[192:195], v[20:23]
	v_mfma_f32_16x16x32_bf16 v[16:19], v[224:227], v[192:195], v[16:19]
	v_mfma_f32_16x16x32_bf16 v[12:15], v[216:219], v[200:203], v[12:15]
	v_mfma_f32_16x16x32_bf16 v[8:11], v[224:227], v[200:203], v[8:11]
	v_mfma_f32_16x16x32_bf16 v[4:7], v[216:219], v[208:211], v[4:7]
	v_mfma_f32_16x16x32_bf16 v[0:3], v[224:227], v[208:211], v[0:3]
	v_mfma_f32_16x16x32_bf16 v[28:31], v[220:223], v[188:191], v[28:31]
	v_mfma_f32_16x16x32_bf16 v[24:27], v[228:231], v[188:191], v[24:27]
	v_mfma_f32_16x16x32_bf16 v[20:23], v[220:223], v[196:199], v[20:23]
	v_mfma_f32_16x16x32_bf16 v[16:19], v[228:231], v[196:199], v[16:19]
	v_mfma_f32_16x16x32_bf16 v[12:15], v[220:223], v[204:207], v[12:15]
	v_mfma_f32_16x16x32_bf16 v[8:11], v[228:231], v[204:207], v[8:11]
	v_mfma_f32_16x16x32_bf16 v[4:7], v[220:223], v[212:215], v[4:7]
	v_mfma_f32_16x16x32_bf16 v[0:3], v[228:231], v[212:215], v[0:3]
	s_setprio 1
	v_add_u32_e32 v167, v151, v153
	v_add_u32_e32 v169, v151, v155
	s_barrier
	v_add_u32_e32 v168, v151, v154
	ds_read_b128 v[176:179], v167
	ds_read_b128 v[180:183], v168
	v_add_u32_e32 v170, v151, v156
	ds_read_b128 v[184:187], v169
	ds_read_b128 v[188:191], v170
	v_mov_b32_e32 v172, v141
	v_mov_b32_e32 v128, v139
	ds_read_b128 v[192:195], v130 offset:32768
	ds_read_b128 v[196:199], v131 offset:32768
	ds_read_b128 v[200:203], v132 offset:32768
	ds_read_b128 v[204:207], v133 offset:32768
	ds_read_b128 v[208:211], v134 offset:32768
	ds_read_b128 v[212:215], v135 offset:32768
	ds_read_b128 v[216:219], v137 offset:32768
	ds_read_b128 v[220:223], v138 offset:32768
	v_mov_b32_e32 v173, v129
	v_lshl_add_u64 v[174:175], s[42:43], 0, v[128:129]
	v_add_u32_e32 v128, 0x4000, v144
	v_lshl_add_u64 v[174:175], v[174:175], 0, s[18:19]
	v_readfirstlane_b32 s53, v128
	v_add_u32_e32 v128, 0x6000, v144
	s_mov_b32 m0, s53
	v_lshl_add_u64 v[172:173], s[42:43], 0, v[172:173]
	v_readfirstlane_b32 s53, v128
	global_load_lds_dwordx4 v[174:175], off
	v_lshl_add_u64 v[172:173], v[172:173], 0, s[18:19]
	s_mov_b32 m0, s53
	s_nop 0
	global_load_lds_dwordx4 v[172:173], off
	s_waitcnt lgkmcnt(8)
	s_barrier
	s_waitcnt lgkmcnt(0)
	s_setprio 0
	s_waitcnt lgkmcnt(0)
	v_mfma_f32_16x16x32_bf16 v[124:127], v[176:179], v[192:195], v[124:127]
	v_mfma_f32_16x16x32_bf16 v[120:123], v[184:187], v[192:195], v[120:123]
	v_mfma_f32_16x16x32_bf16 v[116:119], v[176:179], v[200:203], v[116:119]
	v_mfma_f32_16x16x32_bf16 v[112:115], v[184:187], v[200:203], v[112:115]
	v_mfma_f32_16x16x32_bf16 v[108:111], v[176:179], v[208:211], v[108:111]
	v_mfma_f32_16x16x32_bf16 v[104:107], v[184:187], v[208:211], v[104:107]
	v_mfma_f32_16x16x32_bf16 v[100:103], v[176:179], v[216:219], v[100:103]
	v_mfma_f32_16x16x32_bf16 v[96:99], v[184:187], v[216:219], v[96:99]
	v_mfma_f32_16x16x32_bf16 v[124:127], v[180:183], v[196:199], v[124:127]
	v_mfma_f32_16x16x32_bf16 v[120:123], v[188:191], v[196:199], v[120:123]
	v_mfma_f32_16x16x32_bf16 v[116:119], v[180:183], v[204:207], v[116:119]
	v_mfma_f32_16x16x32_bf16 v[112:115], v[188:191], v[204:207], v[112:115]
	v_mfma_f32_16x16x32_bf16 v[108:111], v[180:183], v[212:215], v[108:111]
	v_mfma_f32_16x16x32_bf16 v[104:107], v[188:191], v[212:215], v[104:107]
	v_mfma_f32_16x16x32_bf16 v[100:103], v[180:183], v[220:223], v[100:103]
	v_mfma_f32_16x16x32_bf16 v[96:99], v[188:191], v[220:223], v[96:99]
	s_setprio 1
	s_barrier
; #define LDA(dst, b, h) for (int m = 0; m < 4; ++m) for (int k = 0; k < 2; ++k) \
;     dst[m][k] = *reinterpret_cast<const bf16x8*>((char*)SA(b, h) + lds_byte(wr * 64 + m * 16 + fr, k * 32 + fq * 8))
; #define LDB(dst, b, h) for (int n = 0; n < 2; ++n) for (int k = 0; k < 2; ++k) \
;     dst[n][k] = *reinterpret_cast<const bf16x8*>((char*)SB(b, h) + lds_byte(wc * 32 + n * 16 + fr, k * 32 + fq * 8))
; #define MMA(ai, bj, At_, Bt_) do { __builtin_amdgcn_s_setprio(1); \
;     for (int m = 0; m < 4; ++m) for (int n = 0; n < 2; ++n) for (int k = 0; k < 2; ++k) \
;       acc[ai][bj][m][n] = MFMA16(Bt_[n][k], At_[m][k], acc[ai][bj][m][n]); \
;     __builtin_amdgcn_s_setprio(0); } while (0)
; #define WAIT_V(n) asm volatile("s_waitcnt vmcnt(" #n ")" ::: "memory")
; #define WAIT_L(n) asm volatile("s_waitcnt lgkmcnt(" #n ")" ::: "memory")
; #define BAR __builtin_amdgcn_s_barrier()
; #define SCHED __builtin_amdgcn_sched_barrier(0)
; template <int PART  , bool SYNC_FIRST = true>
; __device__ __forceinline__ void kloop_t(const u16* __restrict__ A, int lda, const u16* __restrict__ Bt, int ldb, int K, Acc& acc, const int wv) {
;     ...
;     LDB(B1, 1, 1); STAGE(SB(1, 0), Bt, ldb, 0, t + 3);
;     BAR; WAIT_L(0); MMA(0, 1, At, B1); BAR;
;     LDA(At, 1, 1); STAGE(SA(1, 0), A, lda, 0, t + 3);
;     BAR; WAIT_L(0); MMA(1, 0, At, B0); BAR; SCHED;
;     STAGE(SB(1, 1), Bt, ldb, HALF, t + 3);
;     WAIT_V(6); BAR; MMA(1, 1, At, B1); BAR;
	v_add_u32_e32 v171, v152, v153
	v_add_u32_e32 v173, v152, v155
	v_mov_b32_e32 v240, v141
	v_mov_b32_e32 v128, v139
	v_add_u32_e32 v172, v152, v154
	ds_read_b128 v[224:227], v171
	ds_read_b128 v[228:231], v172
	v_add_u32_e32 v174, v152, v156
	ds_read_b128 v[232:235], v173
	ds_read_b128 v[236:239], v174
	v_readfirstlane_b32 s53, v142
	v_lshl_add_u64 v[242:243], s[44:45], 0, v[128:129]
	v_mov_b32_e32 v241, v129
	v_lshl_add_u64 v[242:243], v[242:243], 0, s[20:21]
	s_mov_b32 m0, s53
	v_lshl_add_u64 v[240:241], s[44:45], 0, v[240:241]
	v_readfirstlane_b32 s53, v143
	global_load_lds_dwordx4 v[242:243], off
	v_lshl_add_u64 v[240:241], v[240:241], 0, s[20:21]
	s_mov_b32 m0, s53
	s_nop 0
	global_load_lds_dwordx4 v[240:241], off
	s_barrier
	s_waitcnt lgkmcnt(0)
	s_setprio 0
	s_waitcnt lgkmcnt(0)
	v_mfma_f32_16x16x32_bf16 v[92:95], v[224:227], v[192:195], v[92:95]
	v_mfma_f32_16x16x32_bf16 v[88:91], v[232:235], v[192:195], v[88:91]
	v_mfma_f32_16x16x32_bf16 v[84:87], v[224:227], v[200:203], v[84:87]
	v_mfma_f32_16x16x32_bf16 v[80:83], v[232:235], v[200:203], v[80:83]
	v_mfma_f32_16x16x32_bf16 v[76:79], v[224:227], v[208:211], v[76:79]
	v_mfma_f32_16x16x32_bf16 v[72:75], v[232:235], v[208:211], v[72:75]
	v_mfma_f32_16x16x32_bf16 v[68:71], v[224:227], v[216:219], v[68:71]
	v_mfma_f32_16x16x32_bf16 v[64:67], v[232:235], v[216:219], v[64:67]
	v_mfma_f32_16x16x32_bf16 v[92:95], v[228:231], v[196:199], v[92:95]
	v_mfma_f32_16x16x32_bf16 v[88:91], v[236:239], v[196:199], v[88:91]
	v_mfma_f32_16x16x32_bf16 v[84:87], v[228:231], v[204:207], v[84:87]
	v_mfma_f32_16x16x32_bf16 v[80:83], v[236:239], v[204:207], v[80:83]
	v_mfma_f32_16x16x32_bf16 v[76:79], v[228:231], v[212:215], v[76:79]
	v_mfma_f32_16x16x32_bf16 v[72:75], v[236:239], v[212:215], v[72:75]
	v_mfma_f32_16x16x32_bf16 v[68:71], v[228:231], v[220:223], v[68:71]
	v_mfma_f32_16x16x32_bf16 v[64:67], v[236:239], v[220:223], v[64:67]
	s_setprio 1
	v_mov_b32_e32 v240, v141
	v_mov_b32_e32 v128, v139
	s_barrier
	ds_read_b128 v[192:195], v130 offset:49152
	ds_read_b128 v[196:199], v131 offset:49152
	ds_read_b128 v[200:203], v132 offset:49152
	ds_read_b128 v[204:207], v133 offset:49152
	ds_read_b128 v[208:211], v134 offset:49152
	ds_read_b128 v[212:215], v135 offset:49152
	ds_read_b128 v[216:219], v137 offset:49152
	ds_read_b128 v[220:223], v138 offset:49152
	v_readfirstlane_b32 s53, v145
	v_lshl_add_u64 v[242:243], s[42:43], 0, v[128:129]
	v_mov_b32_e32 v241, v129
	v_lshl_add_u64 v[242:243], v[242:243], 0, s[20:21]
	s_mov_b32 m0, s53
	v_lshl_add_u64 v[240:241], s[42:43], 0, v[240:241]
	v_readfirstlane_b32 s42, v146
	global_load_lds_dwordx4 v[242:243], off
	v_lshl_add_u64 v[240:241], v[240:241], 0, s[20:21]
	s_mov_b32 m0, s42
	s_nop 0
	global_load_lds_dwordx4 v[240:241], off
	s_barrier
	s_waitcnt lgkmcnt(0)
	s_setprio 0
	s_waitcnt lgkmcnt(0)
	v_mfma_f32_16x16x32_bf16 v[60:63], v[176:179], v[192:195], v[60:63]
	v_mfma_f32_16x16x32_bf16 v[56:59], v[184:187], v[192:195], v[56:59]
	v_mfma_f32_16x16x32_bf16 v[52:55], v[176:179], v[200:203], v[52:55]
	v_mfma_f32_16x16x32_bf16 v[48:51], v[184:187], v[200:203], v[48:51]
	v_mfma_f32_16x16x32_bf16 v[44:47], v[176:179], v[208:211], v[44:47]
	v_mfma_f32_16x16x32_bf16 v[40:43], v[184:187], v[208:211], v[40:43]
	v_mfma_f32_16x16x32_bf16 v[36:39], v[176:179], v[216:219], v[36:39]
	v_mfma_f32_16x16x32_bf16 v[32:35], v[184:187], v[216:219], v[32:35]
	v_mfma_f32_16x16x32_bf16 v[60:63], v[180:183], v[196:199], v[60:63]
	v_mfma_f32_16x16x32_bf16 v[56:59], v[188:191], v[196:199], v[56:59]
	v_mfma_f32_16x16x32_bf16 v[52:55], v[180:183], v[204:207], v[52:55]
	v_mfma_f32_16x16x32_bf16 v[48:51], v[188:191], v[204:207], v[48:51]
	v_mfma_f32_16x16x32_bf16 v[44:47], v[180:183], v[212:215], v[44:47]
	v_mfma_f32_16x16x32_bf16 v[40:43], v[188:191], v[212:215], v[40:43]
	v_mfma_f32_16x16x32_bf16 v[36:39], v[180:183], v[220:223], v[36:39]
	v_mfma_f32_16x16x32_bf16 v[32:35], v[188:191], v[220:223], v[32:35]
	s_setprio 1
	s_barrier
	v_mov_b32_e32 v176, v141
	v_mov_b32_e32 v128, v139
	v_readfirstlane_b32 s42, v147
	v_lshl_add_u64 v[178:179], s[44:45], 0, v[128:129]
	v_mov_b32_e32 v177, v129
	v_lshl_add_u64 v[178:179], v[178:179], 0, s[22:23]
	s_mov_b32 m0, s42
	v_lshl_add_u64 v[176:177], s[44:45], 0, v[176:177]
	v_readfirstlane_b32 s42, v148
	global_load_lds_dwordx4 v[178:179], off
	v_lshl_add_u64 v[176:177], v[176:177], 0, s[22:23]
	s_mov_b32 m0, s42
	s_nop 0
	global_load_lds_dwordx4 v[176:177], off
	s_waitcnt vmcnt(6)
	s_barrier
	s_setprio 0
	v_mfma_f32_16x16x32_bf16 v[28:31], v[224:227], v[192:195], v[28:31]
	v_mfma_f32_16x16x32_bf16 v[24:27], v[232:235], v[192:195], v[24:27]
	v_mfma_f32_16x16x32_bf16 v[20:23], v[224:227], v[200:203], v[20:23]
	v_mfma_f32_16x16x32_bf16 v[16:19], v[232:235], v[200:203], v[16:19]
	v_mfma_f32_16x16x32_bf16 v[12:15], v[224:227], v[208:211], v[12:15]
	v_mfma_f32_16x16x32_bf16 v[8:11], v[232:235], v[208:211], v[8:11]
	v_mfma_f32_16x16x32_bf16 v[4:7], v[224:227], v[216:219], v[4:7]
	v_mfma_f32_16x16x32_bf16 v[0:3], v[232:235], v[216:219], v[0:3]
	v_mfma_f32_16x16x32_bf16 v[28:31], v[228:231], v[196:199], v[28:31]
	v_mfma_f32_16x16x32_bf16 v[24:27], v[236:239], v[196:199], v[24:27]
	v_mfma_f32_16x16x32_bf16 v[20:23], v[228:231], v[204:207], v[20:23]
	v_mfma_f32_16x16x32_bf16 v[16:19], v[236:239], v[204:207], v[16:19]
	v_mfma_f32_16x16x32_bf16 v[12:15], v[228:231], v[212:215], v[12:15]
	v_mfma_f32_16x16x32_bf16 v[8:11], v[236:239], v[212:215], v[8:11]
	v_mfma_f32_16x16x32_bf16 v[4:7], v[228:231], v[220:223], v[4:7]
	v_mfma_f32_16x16x32_bf16 v[0:3], v[236:239], v[220:223], v[0:3]
	s_setprio 1
	s_add_i32 s39, s39, 2
	s_add_u32 s40, s40, 0x100
	s_addc_u32 s41, s41, 0
	s_cmp_lt_u32 s39, 12
	s_barrier
; #define LDA(dst, b, h) for (int m = 0; m < 4; ++m) for (int k = 0; k < 2; ++k) \
;     dst[m][k] = *reinterpret_cast<const bf16x8*>((char*)SA(b, h) + lds_byte(wr * 64 + m * 16 + fr, k * 32 + fq * 8))
; #define LDB(dst, b, h) for (int n = 0; n < 2; ++n) for (int k = 0; k < 2; ++k) \
;     dst[n][k] = *reinterpret_cast<const bf16x8*>((char*)SB(b, h) + lds_byte(wc * 32 + n * 16 + fr, k * 32 + fq * 8))
; #define MMA(ai, bj, At_, Bt_) do { __builtin_amdgcn_s_setprio(1); \
;     for (int m = 0; m < 4; ++m) for (int n = 0; n < 2; ++n) for (int k = 0; k < 2; ++k) \
;       acc[ai][bj][m][n] = MFMA16(Bt_[n][k], At_[m][k], acc[ai][bj][m][n]); \
;     __builtin_amdgcn_s_setprio(0); } while (0)
; #define WAIT_V(n) asm volatile("s_waitcnt vmcnt(" #n ")" ::: "memory")
; #define WAIT_L(n) asm volatile("s_waitcnt lgkmcnt(" #n ")" ::: "memory")
; #define BAR __builtin_amdgcn_s_barrier()
; template <int PART  , bool SYNC_FIRST = true>
; __device__ __forceinline__ void kloop_t(const u16* __restrict__ A, int lda, const u16* __restrict__ Bt, int ldb, int K, Acc& acc, const int wv) {
;     ...
;   { LDB(B0, 0, 0); LDA(At, 0, 0); STAGE(SA(1, 1), A, lda, HALF, nt - 1);
;     BAR; WAIT_L(0); MMA(0, 0, At, B0); BAR;
;     LDB(B1, 0, 1); BAR; WAIT_L(0); MMA(0, 1, At, B1); BAR;
;     LDA(At, 0, 1); WAIT_V(4); BAR; WAIT_L(0); MMA(1, 0, At, B0); MMA(1, 1, At, B1); BAR; }
	s_cbranch_scc1 .LBB0_193
	s_add_u32 s4, s4, 0x40780
	v_readfirstlane_b32 s36, v161
	s_addc_u32 s5, s5, 0
	s_mov_b32 m0, s36
	v_readfirstlane_b32 s36, v162
	ds_read_b128 v[142:145], v157
	ds_read_b128 v[146:149], v158
	ds_read_b128 v[150:153], v159
	ds_read_b128 v[154:157], v160
	ds_read_b128 v[176:179], v130
	ds_read_b128 v[180:183], v131
	ds_read_b128 v[184:187], v132
	ds_read_b128 v[188:191], v133
	ds_read_b128 v[192:195], v134
	ds_read_b128 v[196:199], v135
	ds_read_b128 v[200:203], v137
	ds_read_b128 v[204:207], v138
	s_nop 0
	global_load_lds_dwordx4 v139, s[4:5]
	s_mov_b32 m0, s36
	s_nop 0
	global_load_lds_dwordx4 v141, s[4:5]
	s_barrier
	s_waitcnt lgkmcnt(0)
	s_setprio 0
	s_waitcnt lgkmcnt(0)
	v_mfma_f32_16x16x32_bf16 v[124:127], v[142:145], v[176:179], v[124:127]
	v_mfma_f32_16x16x32_bf16 v[120:123], v[150:153], v[176:179], v[120:123]
	v_mfma_f32_16x16x32_bf16 v[116:119], v[142:145], v[184:187], v[116:119]
	v_mfma_f32_16x16x32_bf16 v[112:115], v[150:153], v[184:187], v[112:115]
	v_mfma_f32_16x16x32_bf16 v[100:103], v[142:145], v[200:203], v[100:103]
	v_mfma_f32_16x16x32_bf16 v[96:99], v[150:153], v[200:203], v[96:99]
	v_mfma_f32_16x16x32_bf16 v[124:127], v[146:149], v[180:183], v[124:127]
	v_mfma_f32_16x16x32_bf16 v[120:123], v[154:157], v[180:183], v[120:123]
	v_mfma_f32_16x16x32_bf16 v[116:119], v[146:149], v[188:191], v[116:119]
	v_mfma_f32_16x16x32_bf16 v[112:115], v[154:157], v[188:191], v[112:115]
	v_mfma_f32_16x16x32_bf16 v[108:111], v[142:145], v[192:195], v[108:111]
	v_mfma_f32_16x16x32_bf16 v[104:107], v[150:153], v[192:195], v[104:107]
	v_mfma_f32_16x16x32_bf16 v[100:103], v[146:149], v[204:207], v[100:103]
	v_mfma_f32_16x16x32_bf16 v[96:99], v[154:157], v[204:207], v[96:99]
	v_mfma_f32_16x16x32_bf16 v[158:161], v[146:149], v[196:199], v[108:111]
	v_mfma_f32_16x16x32_bf16 v[208:211], v[154:157], v[196:199], v[104:107]
	s_setprio 1
	s_barrier
	s_nop 1
	ds_read_b128 v[104:107], v163
	ds_read_b128 v[108:111], v164
	ds_read_b128 v[162:165], v165
	ds_read_b128 v[212:215], v166
	s_barrier
	s_waitcnt lgkmcnt(0)
	s_setprio 0
	s_waitcnt lgkmcnt(0)
	v_mfma_f32_16x16x32_bf16 v[84:87], v[104:107], v[184:187], v[84:87]
	v_mfma_f32_16x16x32_bf16 v[80:83], v[162:165], v[184:187], v[80:83]
	v_mfma_f32_16x16x32_bf16 v[68:71], v[104:107], v[200:203], v[68:71]
	v_mfma_f32_16x16x32_bf16 v[64:67], v[162:165], v[200:203], v[64:67]
	v_mfma_f32_16x16x32_bf16 v[92:95], v[104:107], v[176:179], v[92:95]
	v_mfma_f32_16x16x32_bf16 v[88:91], v[162:165], v[176:179], v[88:91]
	v_mfma_f32_16x16x32_bf16 v[84:87], v[108:111], v[188:191], v[84:87]
	v_mfma_f32_16x16x32_bf16 v[80:83], v[212:215], v[188:191], v[80:83]
	v_mfma_f32_16x16x32_bf16 v[76:79], v[104:107], v[192:195], v[76:79]
	v_mfma_f32_16x16x32_bf16 v[72:75], v[162:165], v[192:195], v[72:75]
	v_mfma_f32_16x16x32_bf16 v[68:71], v[108:111], v[204:207], v[68:71]
	v_mfma_f32_16x16x32_bf16 v[64:67], v[212:215], v[204:207], v[64:67]
	v_mfma_f32_16x16x32_bf16 v[216:219], v[108:111], v[180:183], v[92:95]
	v_mfma_f32_16x16x32_bf16 v[176:179], v[212:215], v[180:183], v[88:91]
	v_mfma_f32_16x16x32_bf16 v[180:183], v[108:111], v[196:199], v[76:79]
	v_mfma_f32_16x16x32_bf16 v[184:187], v[212:215], v[196:199], v[72:75]
	s_setprio 1
	s_barrier
	s_nop 0
	ds_read_b128 v[72:75], v130 offset:16384
	ds_read_b128 v[76:79], v131 offset:16384
	ds_read_b128 v[88:91], v132 offset:16384
	ds_read_b128 v[92:95], v133 offset:16384
	ds_read_b128 v[188:191], v134 offset:16384
	ds_read_b128 v[192:195], v135 offset:16384
	ds_read_b128 v[196:199], v137 offset:16384
	ds_read_b128 v[200:203], v138 offset:16384
	s_waitcnt vmcnt(4)
	s_barrier
	s_waitcnt lgkmcnt(0)
	s_setprio 0
	s_waitcnt lgkmcnt(0)
	v_mfma_f32_16x16x32_bf16 v[60:63], v[142:145], v[72:75], v[60:63]
	v_mfma_f32_16x16x32_bf16 v[56:59], v[150:153], v[72:75], v[56:59]
	v_mfma_f32_16x16x32_bf16 v[52:55], v[142:145], v[88:91], v[52:55]
	v_mfma_f32_16x16x32_bf16 v[48:51], v[150:153], v[88:91], v[48:51]
	v_mfma_f32_16x16x32_bf16 v[36:39], v[142:145], v[196:199], v[36:39]
	v_mfma_f32_16x16x32_bf16 v[32:35], v[150:153], v[196:199], v[32:35]
	v_mfma_f32_16x16x32_bf16 v[60:63], v[146:149], v[76:79], v[60:63]
	v_mfma_f32_16x16x32_bf16 v[56:59], v[154:157], v[76:79], v[56:59]
	v_mfma_f32_16x16x32_bf16 v[52:55], v[146:149], v[92:95], v[52:55]
	v_mfma_f32_16x16x32_bf16 v[48:51], v[154:157], v[92:95], v[48:51]
	v_mfma_f32_16x16x32_bf16 v[44:47], v[142:145], v[188:191], v[44:47]
	v_mfma_f32_16x16x32_bf16 v[40:43], v[150:153], v[188:191], v[40:43]
	v_mfma_f32_16x16x32_bf16 v[36:39], v[146:149], v[200:203], v[36:39]
	v_mfma_f32_16x16x32_bf16 v[32:35], v[154:157], v[200:203], v[32:35]
	v_mfma_f32_16x16x32_bf16 v[204:207], v[146:149], v[192:195], v[44:47]
	v_mfma_f32_16x16x32_bf16 v[220:223], v[154:157], v[192:195], v[40:43]
	s_setprio 1
	s_setprio 0
	v_mfma_f32_16x16x32_bf16 v[20:23], v[104:107], v[88:91], v[20:23]
	v_mfma_f32_16x16x32_bf16 v[16:19], v[162:165], v[88:91], v[16:19]
	v_mfma_f32_16x16x32_bf16 v[4:7], v[104:107], v[196:199], v[4:7]
	v_mfma_f32_16x16x32_bf16 v[0:3], v[162:165], v[196:199], v[0:3]
	v_mfma_f32_16x16x32_bf16 v[28:31], v[104:107], v[72:75], v[28:31]
	v_mfma_f32_16x16x32_bf16 v[24:27], v[162:165], v[72:75], v[24:27]
	v_mfma_f32_16x16x32_bf16 v[20:23], v[108:111], v[92:95], v[20:23]
	v_mfma_f32_16x16x32_bf16 v[16:19], v[212:215], v[92:95], v[16:19]
	v_mfma_f32_16x16x32_bf16 v[12:15], v[104:107], v[188:191], v[12:15]
	v_mfma_f32_16x16x32_bf16 v[8:11], v[162:165], v[188:191], v[8:11]
	v_mfma_f32_16x16x32_bf16 v[4:7], v[108:111], v[200:203], v[4:7]
	v_mfma_f32_16x16x32_bf16 v[0:3], v[212:215], v[200:203], v[0:3]
	v_mfma_f32_16x16x32_bf16 v[140:143], v[108:111], v[76:79], v[28:31]
	v_mfma_f32_16x16x32_bf16 v[144:147], v[212:215], v[76:79], v[24:27]
	v_mfma_f32_16x16x32_bf16 v[148:151], v[108:111], v[192:195], v[12:15]
	v_mfma_f32_16x16x32_bf16 v[152:155], v[212:215], v[192:195], v[8:11]
	s_setprio 1
	s_barrier
; #define LDA(dst, b, h) for (int m = 0; m < 4; ++m) for (int k = 0; k < 2; ++k) \
;     dst[m][k] = *reinterpret_cast<const bf16x8*>((char*)SA(b, h) + lds_byte(wr * 64 + m * 16 + fr, k * 32 + fq * 8))
; #define LDB(dst, b, h) for (int n = 0; n < 2; ++n) for (int k = 0; k < 2; ++k) \
;     dst[n][k] = *reinterpret_cast<const bf16x8*>((char*)SB(b, h) + lds_byte(wc * 32 + n * 16 + fr, k * 32 + fq * 8))
; #define MMA(ai, bj, At_, Bt_) do { __builtin_amdgcn_s_setprio(1); \
;     for (int m = 0; m < 4; ++m) for (int n = 0; n < 2; ++n) for (int k = 0; k < 2; ++k) \
;       acc[ai][bj][m][n] = MFMA16(Bt_[n][k], At_[m][k], acc[ai][bj][m][n]); \
;     __builtin_amdgcn_s_setprio(0); } while (0)
; #define WAIT_V(n) asm volatile("s_waitcnt vmcnt(" #n ")" ::: "memory")
; #define WAIT_L(n) asm volatile("s_waitcnt lgkmcnt(" #n ")" ::: "memory")
; #define BAR __builtin_amdgcn_s_barrier()
; template <int PART  , bool SYNC_FIRST = true>
; __device__ __forceinline__ void kloop_t(const u16* __restrict__ A, int lda, const u16* __restrict__ Bt, int ldb, int K, Acc& acc, const int wv) {
;     ...
;   { LDB(B0, 1, 0); LDA(At, 1, 0); WAIT_V(2); BAR; WAIT_L(0); MMA(0, 0, At, B0); BAR;
;     LDB(B1, 1, 1); WAIT_V(0); BAR; WAIT_L(0); MMA(0, 1, At, B1); BAR;
;     LDA(At, 1, 1); BAR; WAIT_L(0); MMA(1, 0, At, B0); MMA(1, 1, At, B1); BAR; }
;   if (wr == 0) BAR;
	s_nop 0
	ds_read_b128 v[8:11], v167
	ds_read_b128 v[12:15], v168
	ds_read_b128 v[162:165], v169
	ds_read_b128 v[166:169], v170
	ds_read_b128 v[24:27], v130 offset:32768
	ds_read_b128 v[28:31], v131 offset:32768
	ds_read_b128 v[40:43], v132 offset:32768
	ds_read_b128 v[44:47], v133 offset:32768
	ds_read_b128 v[188:191], v134 offset:32768
	ds_read_b128 v[192:195], v135 offset:32768
	ds_read_b128 v[196:199], v137 offset:32768
	ds_read_b128 v[200:203], v138 offset:32768
	s_waitcnt vmcnt(2)
	s_barrier
	s_waitcnt lgkmcnt(0)
	s_setprio 0
	s_waitcnt lgkmcnt(0)
	v_mfma_f32_16x16x32_bf16 v[72:75], v[8:11], v[24:27], v[124:127]
	v_mfma_f32_16x16x32_bf16 v[124:127], v[12:15], v[28:31], v[72:75]
	v_mfma_f32_16x16x32_bf16 v[72:75], v[162:165], v[24:27], v[120:123]
	v_mfma_f32_16x16x32_bf16 v[120:123], v[166:169], v[28:31], v[72:75]
	v_mfma_f32_16x16x32_bf16 v[72:75], v[8:11], v[40:43], v[116:119]
	v_mfma_f32_16x16x32_bf16 v[108:111], v[12:15], v[44:47], v[72:75]
	v_mfma_f32_16x16x32_bf16 v[72:75], v[162:165], v[40:43], v[112:115]
	v_mfma_f32_16x16x32_bf16 v[104:107], v[166:169], v[44:47], v[72:75]
	v_mfma_f32_16x16x32_bf16 v[72:75], v[8:11], v[188:191], v[158:161]
	v_mfma_f32_16x16x32_bf16 v[92:95], v[12:15], v[192:195], v[72:75]
	v_mfma_f32_16x16x32_bf16 v[72:75], v[162:165], v[188:191], v[208:211]
	v_mfma_f32_16x16x32_bf16 v[88:91], v[166:169], v[192:195], v[72:75]
	v_mfma_f32_16x16x32_bf16 v[72:75], v[8:11], v[196:199], v[100:103]
	v_mfma_f32_16x16x32_bf16 v[76:79], v[12:15], v[200:203], v[72:75]
	v_mfma_f32_16x16x32_bf16 v[72:75], v[162:165], v[196:199], v[96:99]
	v_mfma_f32_16x16x32_bf16 v[72:75], v[166:169], v[200:203], v[72:75]
	s_setprio 1
	s_barrier
	ds_read_b128 v[156:159], v171
	ds_read_b128 v[208:211], v172
	ds_read_b128 v[170:173], v173
	ds_read_b128 v[212:215], v174
	s_waitcnt vmcnt(0)
	s_barrier
	s_waitcnt lgkmcnt(0)
	s_setprio 0
	s_waitcnt lgkmcnt(0)
	v_mfma_f32_16x16x32_bf16 v[96:99], v[156:159], v[24:27], v[216:219]
	v_mfma_f32_16x16x32_bf16 v[24:27], v[170:173], v[24:27], v[176:179]
	v_mfma_f32_16x16x32_bf16 v[112:115], v[212:215], v[28:31], v[24:27]
	v_mfma_f32_16x16x32_bf16 v[24:27], v[156:159], v[40:43], v[84:87]
	v_mfma_f32_16x16x32_bf16 v[100:103], v[208:211], v[44:47], v[24:27]
	v_mfma_f32_16x16x32_bf16 v[24:27], v[170:173], v[40:43], v[80:83]
	v_mfma_f32_16x16x32_bf16 v[116:119], v[208:211], v[28:31], v[96:99]
	v_mfma_f32_16x16x32_bf16 v[96:99], v[212:215], v[44:47], v[24:27]
	v_mfma_f32_16x16x32_bf16 v[24:27], v[156:159], v[188:191], v[180:183]
	v_mfma_f32_16x16x32_bf16 v[84:87], v[208:211], v[192:195], v[24:27]
	v_mfma_f32_16x16x32_bf16 v[24:27], v[170:173], v[188:191], v[184:187]
	v_mfma_f32_16x16x32_bf16 v[80:83], v[212:215], v[192:195], v[24:27]
	v_mfma_f32_16x16x32_bf16 v[24:27], v[156:159], v[196:199], v[68:71]
	v_mfma_f32_16x16x32_bf16 v[68:71], v[208:211], v[200:203], v[24:27]
	v_mfma_f32_16x16x32_bf16 v[24:27], v[170:173], v[196:199], v[64:67]
	v_mfma_f32_16x16x32_bf16 v[64:67], v[212:215], v[200:203], v[24:27]
	s_setprio 1
	s_barrier
	ds_read_b128 v[174:177], v130 offset:49152
	ds_read_b128 v[178:181], v131 offset:49152
	ds_read_b128 v[182:185], v132 offset:49152
	ds_read_b128 v[130:133], v133 offset:49152
	ds_read_b128 v[186:189], v134 offset:49152
	ds_read_b128 v[190:193], v135 offset:49152
	ds_read_b128 v[194:197], v137 offset:49152
	ds_read_b128 v[198:201], v138 offset:49152
	s_barrier
	s_waitcnt lgkmcnt(0)
	s_setprio 0
	s_waitcnt lgkmcnt(0)
	v_mfma_f32_16x16x32_bf16 v[24:27], v[8:11], v[174:177], v[60:63]
	v_mfma_f32_16x16x32_bf16 v[60:63], v[12:15], v[178:181], v[24:27]
	v_mfma_f32_16x16x32_bf16 v[24:27], v[162:165], v[174:177], v[56:59]
	v_mfma_f32_16x16x32_bf16 v[56:59], v[166:169], v[178:181], v[24:27]
	v_mfma_f32_16x16x32_bf16 v[24:27], v[8:11], v[182:185], v[52:55]
	v_mfma_f32_16x16x32_bf16 v[44:47], v[12:15], v[130:133], v[24:27]
	v_mfma_f32_16x16x32_bf16 v[24:27], v[162:165], v[182:185], v[48:51]
	v_mfma_f32_16x16x32_bf16 v[40:43], v[166:169], v[130:133], v[24:27]
	v_mfma_f32_16x16x32_bf16 v[24:27], v[8:11], v[186:189], v[204:207]
	v_mfma_f32_16x16x32_bf16 v[8:11], v[8:11], v[194:197], v[36:39]
	v_mfma_f32_16x16x32_bf16 v[28:31], v[12:15], v[190:193], v[24:27]
	v_mfma_f32_16x16x32_bf16 v[24:27], v[162:165], v[186:189], v[220:223]
	v_mfma_f32_16x16x32_bf16 v[12:15], v[12:15], v[198:201], v[8:11]
	v_mfma_f32_16x16x32_bf16 v[8:11], v[162:165], v[194:197], v[32:35]
	v_mfma_f32_16x16x32_bf16 v[24:27], v[166:169], v[190:193], v[24:27]
	v_mfma_f32_16x16x32_bf16 v[8:11], v[166:169], v[198:201], v[8:11]
	s_setprio 1
	s_setprio 0
	v_mfma_f32_16x16x32_bf16 v[32:35], v[156:159], v[174:177], v[140:143]
	v_mfma_f32_16x16x32_bf16 v[52:55], v[208:211], v[178:181], v[32:35]
	v_mfma_f32_16x16x32_bf16 v[32:35], v[170:173], v[174:177], v[144:147]
	v_mfma_f32_16x16x32_bf16 v[16:19], v[170:173], v[182:185], v[16:19]
	v_mfma_f32_16x16x32_bf16 v[48:51], v[212:215], v[178:181], v[32:35]
	v_mfma_f32_16x16x32_bf16 v[20:23], v[156:159], v[182:185], v[20:23]
	v_mfma_f32_16x16x32_bf16 v[32:35], v[212:215], v[130:133], v[16:19]
	v_mfma_f32_16x16x32_bf16 v[16:19], v[156:159], v[186:189], v[148:151]
	v_mfma_f32_16x16x32_bf16 v[36:39], v[208:211], v[130:133], v[20:23]
	v_mfma_f32_16x16x32_bf16 v[20:23], v[208:211], v[190:193], v[16:19]
	v_mfma_f32_16x16x32_bf16 v[16:19], v[170:173], v[186:189], v[152:155]
	v_mfma_f32_16x16x32_bf16 v[4:7], v[156:159], v[194:197], v[4:7]
	v_mfma_f32_16x16x32_bf16 v[0:3], v[170:173], v[194:197], v[0:3]
	v_mfma_f32_16x16x32_bf16 v[16:19], v[212:215], v[190:193], v[16:19]
	v_mfma_f32_16x16x32_bf16 v[4:7], v[208:211], v[198:201], v[4:7]
	v_mfma_f32_16x16x32_bf16 v[0:3], v[212:215], v[198:201], v[0:3]
	s_setprio 1
	s_andn2_b64 vcc, exec, s[0:1]
	s_barrier
	s_cbranch_vccnz .LBB0_196
	s_barrier

; #define LDA(dst, b, h) for (int m = 0; m < 4; ++m) for (int k = 0; k < 2; ++k) \
;     dst[m][k] = *reinterpret_cast<const bf16x8*>((char*)SA(b, h) + lds_byte(wr * 64 + m * 16 + fr, k * 32 + fq * 8))
; #define LDB(dst, b, h) for (int n = 0; n < 2; ++n) for (int k = 0; k < 2; ++k) \
;     dst[n][k] = *reinterpret_cast<const bf16x8*>((char*)SB(b, h) + lds_byte(wc * 32 + n * 16 + fr, k * 32 + fq * 8))
; #define MMA(ai, bj, At_, Bt_) do { __builtin_amdgcn_s_setprio(1); \
;     for (int m = 0; m < 4; ++m) for (int n = 0; n < 2; ++n) for (int k = 0; k < 2; ++k) \
;       acc[ai][bj][m][n] = MFMA16(Bt_[n][k], At_[m][k], acc[ai][bj][m][n]); \
;     __builtin_amdgcn_s_setprio(0); } while (0)
; #define WAIT_L(n) asm volatile("s_waitcnt lgkmcnt(" #n ")" ::: "memory")
; #define BAR __builtin_amdgcn_s_barrier()
; #define SCHED __builtin_amdgcn_sched_barrier(0)
; template <int PART  , bool SYNC_FIRST = true>
; __device__ __forceinline__ void kloop_t(const u16* __restrict__ A, int lda, const u16* __restrict__ Bt, int ldb, int K, Acc& acc, const int wv) {
;     ...
;     LDB(B0, 0, 0); SCHED; LDA(At, 0, 0); STAGE(SA(1, 1), A, lda, HALF, t + 1);
;     WAIT_L(8); BAR; WAIT_L(0); MMA(0, 0, At, B0); BAR; SCHED;
;     LDB(B1, 0, 1); STAGE(SB(0, 0), Bt, ldb, 0, t + 2);
;     BAR; WAIT_L(0); MMA(0, 1, At, B1); BAR;
;     LDA(At, 0, 1); STAGE(SA(0, 0), A, lda, 0, t + 2);
.LBB0_318:
	v_add_u32_e32 v164, v156, v160
	v_add_u32_e32 v166, v156, v162
	v_add_u32_e32 v165, v156, v161
	ds_read_b128 v[174:177], v164
	ds_read_b128 v[178:181], v165
	v_add_u32_e32 v167, v156, v163
	ds_read_b128 v[182:185], v166
	ds_read_b128 v[186:189], v167
	s_add_u32 s44, s6, s4
	v_mov_b32_e32 v170, v131
	v_mov_b32_e32 v128, v130
	s_addc_u32 s45, s7, s5
	ds_read_b128 v[190:193], v132
	ds_read_b128 v[194:197], v133
	ds_read_b128 v[198:201], v134
	ds_read_b128 v[202:205], v135
	ds_read_b128 v[206:209], v136
	ds_read_b128 v[210:213], v137
	ds_read_b128 v[214:217], v138
	ds_read_b128 v[218:221], v139
	v_mov_b32_e32 v171, v129
	v_lshl_add_u64 v[168:169], s[44:45], 0, v[128:129]
	v_lshl_add_u64 v[172:173], v[168:169], 0, s[24:25]
	v_add_u32_e32 v168, 0xc000, v142
	v_add_u32_e32 v169, 0xe000, v142
	v_readfirstlane_b32 s52, v168
	s_mov_b32 m0, s52
	v_lshl_add_u64 v[170:171], s[44:45], 0, v[170:171]
	v_readfirstlane_b32 s52, v169
	global_load_lds_dwordx4 v[172:173], off
	v_lshl_add_u64 v[170:171], v[170:171], 0, s[24:25]
	s_mov_b32 m0, s52
	s_nop 0
	global_load_lds_dwordx4 v[170:171], off
	s_waitcnt lgkmcnt(8)
	s_barrier
	s_waitcnt lgkmcnt(0)
	s_setprio 0
	s_waitcnt lgkmcnt(0)
	v_mfma_f32_16x16x32_bf16 v[124:127], v[174:177], v[190:193], v[124:127]
	v_mfma_f32_16x16x32_bf16 v[120:123], v[182:185], v[190:193], v[120:123]
	v_mfma_f32_16x16x32_bf16 v[116:119], v[174:177], v[198:201], v[116:119]
	v_mfma_f32_16x16x32_bf16 v[112:115], v[182:185], v[198:201], v[112:115]
	v_mfma_f32_16x16x32_bf16 v[108:111], v[174:177], v[206:209], v[108:111]
	v_mfma_f32_16x16x32_bf16 v[104:107], v[182:185], v[206:209], v[104:107]
	v_mfma_f32_16x16x32_bf16 v[100:103], v[174:177], v[214:217], v[100:103]
	v_mfma_f32_16x16x32_bf16 v[96:99], v[182:185], v[214:217], v[96:99]
	v_mfma_f32_16x16x32_bf16 v[124:127], v[178:181], v[194:197], v[124:127]
	v_mfma_f32_16x16x32_bf16 v[120:123], v[186:189], v[194:197], v[120:123]
	v_mfma_f32_16x16x32_bf16 v[116:119], v[178:181], v[202:205], v[116:119]
	v_mfma_f32_16x16x32_bf16 v[112:115], v[186:189], v[202:205], v[112:115]
	v_mfma_f32_16x16x32_bf16 v[108:111], v[178:181], v[210:213], v[108:111]
	v_mfma_f32_16x16x32_bf16 v[104:107], v[186:189], v[210:213], v[104:107]
	v_mfma_f32_16x16x32_bf16 v[100:103], v[178:181], v[218:221], v[100:103]
	v_mfma_f32_16x16x32_bf16 v[96:99], v[186:189], v[218:221], v[96:99]
	s_setprio 1
	s_barrier
	s_add_u32 s52, s6, s43
	v_add_u32_e32 v170, v157, v160
	v_add_u32_e32 v172, v157, v162
	v_mov_b32_e32 v238, v131
	v_mov_b32_e32 v128, v130
	s_addc_u32 s53, s7, 0
	v_add_u32_e32 v171, v157, v161
	ds_read_b128 v[222:225], v170
	ds_read_b128 v[226:229], v171
	v_add_u32_e32 v173, v157, v163
	ds_read_b128 v[230:233], v172
	ds_read_b128 v[234:237], v173
	v_readfirstlane_b32 s91, v140
	v_lshl_add_u64 v[240:241], s[52:53], 0, v[128:129]
	v_mov_b32_e32 v239, v129
	v_lshl_add_u64 v[240:241], v[240:241], 0, s[26:27]
	s_mov_b32 m0, s91
	v_lshl_add_u64 v[238:239], s[52:53], 0, v[238:239]
	v_readfirstlane_b32 s91, v141
	global_load_lds_dwordx4 v[240:241], off
	v_lshl_add_u64 v[238:239], v[238:239], 0, s[26:27]
	s_mov_b32 m0, s91
	s_nop 0
	global_load_lds_dwordx4 v[238:239], off
	s_barrier
	s_waitcnt lgkmcnt(0)
	s_setprio 0
	s_waitcnt lgkmcnt(0)
	v_mfma_f32_16x16x32_bf16 v[92:95], v[222:225], v[190:193], v[92:95]
	v_mfma_f32_16x16x32_bf16 v[88:91], v[230:233], v[190:193], v[88:91]
	v_mfma_f32_16x16x32_bf16 v[84:87], v[222:225], v[198:201], v[84:87]
	v_mfma_f32_16x16x32_bf16 v[80:83], v[230:233], v[198:201], v[80:83]
	v_mfma_f32_16x16x32_bf16 v[76:79], v[222:225], v[206:209], v[76:79]
	v_mfma_f32_16x16x32_bf16 v[72:75], v[230:233], v[206:209], v[72:75]
	v_mfma_f32_16x16x32_bf16 v[68:71], v[222:225], v[214:217], v[68:71]
	v_mfma_f32_16x16x32_bf16 v[64:67], v[230:233], v[214:217], v[64:67]
	v_mfma_f32_16x16x32_bf16 v[92:95], v[226:229], v[194:197], v[92:95]
	v_mfma_f32_16x16x32_bf16 v[88:91], v[234:237], v[194:197], v[88:91]
	v_mfma_f32_16x16x32_bf16 v[84:87], v[226:229], v[202:205], v[84:87]
	v_mfma_f32_16x16x32_bf16 v[80:83], v[234:237], v[202:205], v[80:83]
	v_mfma_f32_16x16x32_bf16 v[76:79], v[226:229], v[210:213], v[76:79]
	v_mfma_f32_16x16x32_bf16 v[72:75], v[234:237], v[210:213], v[72:75]
	v_mfma_f32_16x16x32_bf16 v[68:71], v[226:229], v[218:221], v[68:71]
	v_mfma_f32_16x16x32_bf16 v[64:67], v[234:237], v[218:221], v[64:67]
	s_setprio 1
	v_mov_b32_e32 v238, v131
	v_mov_b32_e32 v128, v130
	s_barrier
	ds_read_b128 v[190:193], v132 offset:16384
	ds_read_b128 v[194:197], v133 offset:16384
	ds_read_b128 v[198:201], v134 offset:16384
	ds_read_b128 v[202:205], v135 offset:16384
	ds_read_b128 v[206:209], v136 offset:16384
	ds_read_b128 v[210:213], v137 offset:16384
	ds_read_b128 v[214:217], v138 offset:16384
	ds_read_b128 v[218:221], v139 offset:16384
	v_readfirstlane_b32 s91, v142
	v_lshl_add_u64 v[240:241], s[44:45], 0, v[128:129]
	v_mov_b32_e32 v239, v129
	v_lshl_add_u64 v[240:241], v[240:241], 0, s[28:29]
	s_mov_b32 m0, s91
	v_lshl_add_u64 v[238:239], s[44:45], 0, v[238:239]
	v_readfirstlane_b32 s91, v143
	global_load_lds_dwordx4 v[240:241], off
	v_lshl_add_u64 v[238:239], v[238:239], 0, s[28:29]
	s_mov_b32 m0, s91
	s_nop 0
	global_load_lds_dwordx4 v[238:239], off
	s_barrier
; #define LDA(dst, b, h) for (int m = 0; m < 4; ++m) for (int k = 0; k < 2; ++k) \
;     dst[m][k] = *reinterpret_cast<const bf16x8*>((char*)SA(b, h) + lds_byte(wr * 64 + m * 16 + fr, k * 32 + fq * 8))
; #define LDB(dst, b, h) for (int n = 0; n < 2; ++n) for (int k = 0; k < 2; ++k) \
;     dst[n][k] = *reinterpret_cast<const bf16x8*>((char*)SB(b, h) + lds_byte(wc * 32 + n * 16 + fr, k * 32 + fq * 8))
; #define MMA(ai, bj, At_, Bt_) do { __builtin_amdgcn_s_setprio(1); \
;     for (int m = 0; m < 4; ++m) for (int n = 0; n < 2; ++n) for (int k = 0; k < 2; ++k) \
;       acc[ai][bj][m][n] = MFMA16(Bt_[n][k], At_[m][k], acc[ai][bj][m][n]); \
;     __builtin_amdgcn_s_setprio(0); } while (0)
; #define WAIT_V(n) asm volatile("s_waitcnt vmcnt(" #n ")" ::: "memory")
; #define WAIT_L(n) asm volatile("s_waitcnt lgkmcnt(" #n ")" ::: "memory")
; #define BAR __builtin_amdgcn_s_barrier()
; #define SCHED __builtin_amdgcn_sched_barrier(0)
; template <int PART  , bool SYNC_FIRST = true>
; __device__ __forceinline__ void kloop_t(const u16* __restrict__ A, int lda, const u16* __restrict__ Bt, int ldb, int K, Acc& acc, const int wv) {
;     ...
;     BAR; WAIT_L(0); MMA(1, 0, At, B0); BAR; SCHED;
;     STAGE(SB(0, 1), Bt, ldb, HALF, t + 2);
;     WAIT_V(6); BAR; MMA(1, 1, At, B1); BAR;
;     LDB(B0, 1, 0); SCHED; LDA(At, 1, 0); STAGE(SA(0, 1), A, lda, HALF, t + 2);
;     WAIT_L(8); BAR; WAIT_L(0); MMA(0, 0, At, B0); BAR; SCHED;
;     LDB(B1, 1, 1); STAGE(SB(1, 0), Bt, ldb, 0, t + 3);
	s_waitcnt lgkmcnt(0)
	s_setprio 0
	s_waitcnt lgkmcnt(0)
	v_mfma_f32_16x16x32_bf16 v[60:63], v[174:177], v[190:193], v[60:63]
	v_mfma_f32_16x16x32_bf16 v[56:59], v[182:185], v[190:193], v[56:59]
	v_mfma_f32_16x16x32_bf16 v[52:55], v[174:177], v[198:201], v[52:55]
	v_mfma_f32_16x16x32_bf16 v[48:51], v[182:185], v[198:201], v[48:51]
	v_mfma_f32_16x16x32_bf16 v[44:47], v[174:177], v[206:209], v[44:47]
	v_mfma_f32_16x16x32_bf16 v[40:43], v[182:185], v[206:209], v[40:43]
	v_mfma_f32_16x16x32_bf16 v[36:39], v[174:177], v[214:217], v[36:39]
	v_mfma_f32_16x16x32_bf16 v[32:35], v[182:185], v[214:217], v[32:35]
	v_mfma_f32_16x16x32_bf16 v[60:63], v[178:181], v[194:197], v[60:63]
	v_mfma_f32_16x16x32_bf16 v[56:59], v[186:189], v[194:197], v[56:59]
	v_mfma_f32_16x16x32_bf16 v[52:55], v[178:181], v[202:205], v[52:55]
	v_mfma_f32_16x16x32_bf16 v[48:51], v[186:189], v[202:205], v[48:51]
	v_mfma_f32_16x16x32_bf16 v[44:47], v[178:181], v[210:213], v[44:47]
	v_mfma_f32_16x16x32_bf16 v[40:43], v[186:189], v[210:213], v[40:43]
	v_mfma_f32_16x16x32_bf16 v[36:39], v[178:181], v[218:221], v[36:39]
	v_mfma_f32_16x16x32_bf16 v[32:35], v[186:189], v[218:221], v[32:35]
	s_setprio 1
	s_barrier
	v_mov_b32_e32 v174, v131
	v_mov_b32_e32 v128, v130
	v_readfirstlane_b32 s91, v144
	v_lshl_add_u64 v[176:177], s[52:53], 0, v[128:129]
	v_mov_b32_e32 v175, v129
	v_lshl_add_u64 v[176:177], v[176:177], 0, s[30:31]
	s_mov_b32 m0, s91
	v_lshl_add_u64 v[174:175], s[52:53], 0, v[174:175]
	v_readfirstlane_b32 s91, v145
	global_load_lds_dwordx4 v[176:177], off
	v_lshl_add_u64 v[174:175], v[174:175], 0, s[30:31]
	s_mov_b32 m0, s91
	s_nop 0
	global_load_lds_dwordx4 v[174:175], off
	s_waitcnt vmcnt(6)
	s_barrier
	s_setprio 0
	v_mfma_f32_16x16x32_bf16 v[28:31], v[222:225], v[190:193], v[28:31]
	v_mfma_f32_16x16x32_bf16 v[24:27], v[230:233], v[190:193], v[24:27]
	v_mfma_f32_16x16x32_bf16 v[20:23], v[222:225], v[198:201], v[20:23]
	v_mfma_f32_16x16x32_bf16 v[16:19], v[230:233], v[198:201], v[16:19]
	v_mfma_f32_16x16x32_bf16 v[12:15], v[222:225], v[206:209], v[12:15]
	v_mfma_f32_16x16x32_bf16 v[8:11], v[230:233], v[206:209], v[8:11]
	v_mfma_f32_16x16x32_bf16 v[4:7], v[222:225], v[214:217], v[4:7]
	v_mfma_f32_16x16x32_bf16 v[0:3], v[230:233], v[214:217], v[0:3]
	v_mfma_f32_16x16x32_bf16 v[28:31], v[226:229], v[194:197], v[28:31]
	v_mfma_f32_16x16x32_bf16 v[24:27], v[234:237], v[194:197], v[24:27]
	v_mfma_f32_16x16x32_bf16 v[20:23], v[226:229], v[202:205], v[20:23]
	v_mfma_f32_16x16x32_bf16 v[16:19], v[234:237], v[202:205], v[16:19]
	v_mfma_f32_16x16x32_bf16 v[12:15], v[226:229], v[210:213], v[12:15]
	v_mfma_f32_16x16x32_bf16 v[8:11], v[234:237], v[210:213], v[8:11]
	v_mfma_f32_16x16x32_bf16 v[4:7], v[226:229], v[218:221], v[4:7]
	v_mfma_f32_16x16x32_bf16 v[0:3], v[234:237], v[218:221], v[0:3]
	s_setprio 1
	v_add_u32_e32 v174, v158, v160
	v_add_u32_e32 v176, v158, v162
	s_barrier
	v_add_u32_e32 v175, v158, v161
	ds_read_b128 v[182:185], v174
	ds_read_b128 v[186:189], v175
	v_add_u32_e32 v177, v158, v163
	ds_read_b128 v[190:193], v176
	ds_read_b128 v[194:197], v177
	v_mov_b32_e32 v178, v131
	v_mov_b32_e32 v128, v130
	ds_read_b128 v[198:201], v132 offset:32768
	ds_read_b128 v[202:205], v133 offset:32768
	ds_read_b128 v[206:209], v134 offset:32768
	ds_read_b128 v[210:213], v135 offset:32768
	ds_read_b128 v[214:217], v136 offset:32768
	ds_read_b128 v[218:221], v137 offset:32768
	ds_read_b128 v[222:225], v138 offset:32768
	ds_read_b128 v[226:229], v139 offset:32768
	v_readfirstlane_b32 s91, v148
	v_lshl_add_u64 v[180:181], s[44:45], 0, v[128:129]
	v_mov_b32_e32 v179, v129
	v_lshl_add_u64 v[180:181], v[180:181], 0, s[34:35]
	s_mov_b32 m0, s91
	v_lshl_add_u64 v[178:179], s[44:45], 0, v[178:179]
	v_readfirstlane_b32 s91, v149
	global_load_lds_dwordx4 v[180:181], off
	v_lshl_add_u64 v[178:179], v[178:179], 0, s[34:35]
	s_mov_b32 m0, s91
	s_nop 0
	global_load_lds_dwordx4 v[178:179], off
	s_waitcnt lgkmcnt(8)
	s_barrier
	s_waitcnt lgkmcnt(0)
	s_setprio 0
	s_waitcnt lgkmcnt(0)
	v_mfma_f32_16x16x32_bf16 v[124:127], v[182:185], v[198:201], v[124:127]
	v_mfma_f32_16x16x32_bf16 v[120:123], v[190:193], v[198:201], v[120:123]
	v_mfma_f32_16x16x32_bf16 v[116:119], v[182:185], v[206:209], v[116:119]
	v_mfma_f32_16x16x32_bf16 v[112:115], v[190:193], v[206:209], v[112:115]
	v_mfma_f32_16x16x32_bf16 v[108:111], v[182:185], v[214:217], v[108:111]
	v_mfma_f32_16x16x32_bf16 v[104:107], v[190:193], v[214:217], v[104:107]
	v_mfma_f32_16x16x32_bf16 v[100:103], v[182:185], v[222:225], v[100:103]
	v_mfma_f32_16x16x32_bf16 v[96:99], v[190:193], v[222:225], v[96:99]
	v_mfma_f32_16x16x32_bf16 v[124:127], v[186:189], v[202:205], v[124:127]
	v_mfma_f32_16x16x32_bf16 v[120:123], v[194:197], v[202:205], v[120:123]
	v_mfma_f32_16x16x32_bf16 v[116:119], v[186:189], v[210:213], v[116:119]
	v_mfma_f32_16x16x32_bf16 v[112:115], v[194:197], v[210:213], v[112:115]
	v_mfma_f32_16x16x32_bf16 v[108:111], v[186:189], v[218:221], v[108:111]
	v_mfma_f32_16x16x32_bf16 v[104:107], v[194:197], v[218:221], v[104:107]
	v_mfma_f32_16x16x32_bf16 v[100:103], v[186:189], v[226:229], v[100:103]
	v_mfma_f32_16x16x32_bf16 v[96:99], v[194:197], v[226:229], v[96:99]
	s_setprio 1
	s_barrier
	v_add_u32_e32 v178, v159, v160
	v_add_u32_e32 v180, v159, v162
	v_mov_b32_e32 v246, v131
	v_mov_b32_e32 v128, v130
	v_add_u32_e32 v179, v159, v161
	ds_read_b128 v[230:233], v178
	ds_read_b128 v[234:237], v179
	v_add_u32_e32 v181, v159, v163
	ds_read_b128 v[238:241], v180
	ds_read_b128 v[242:245], v181
	v_readfirstlane_b32 s91, v150
	v_lshl_add_u64 v[248:249], s[52:53], 0, v[128:129]
	v_mov_b32_e32 v247, v129
	v_lshl_add_u64 v[248:249], v[248:249], 0, s[36:37]
	s_mov_b32 m0, s91
	v_lshl_add_u64 v[246:247], s[52:53], 0, v[246:247]
	v_readfirstlane_b32 s91, v151
	global_load_lds_dwordx4 v[248:249], off
	v_lshl_add_u64 v[246:247], v[246:247], 0, s[36:37]
	s_mov_b32 m0, s91
	s_nop 0
	global_load_lds_dwordx4 v[246:247], off
	s_barrier
; #define LDA(dst, b, h) for (int m = 0; m < 4; ++m) for (int k = 0; k < 2; ++k) \
;     dst[m][k] = *reinterpret_cast<const bf16x8*>((char*)SA(b, h) + lds_byte(wr * 64 + m * 16 + fr, k * 32 + fq * 8))
; #define LDB(dst, b, h) for (int n = 0; n < 2; ++n) for (int k = 0; k < 2; ++k) \
;     dst[n][k] = *reinterpret_cast<const bf16x8*>((char*)SB(b, h) + lds_byte(wc * 32 + n * 16 + fr, k * 32 + fq * 8))
; #define MMA(ai, bj, At_, Bt_) do { __builtin_amdgcn_s_setprio(1); \
;     for (int m = 0; m < 4; ++m) for (int n = 0; n < 2; ++n) for (int k = 0; k < 2; ++k) \
;       acc[ai][bj][m][n] = MFMA16(Bt_[n][k], At_[m][k], acc[ai][bj][m][n]); \
;     __builtin_amdgcn_s_setprio(0); } while (0)
; #define WAIT_V(n) asm volatile("s_waitcnt vmcnt(" #n ")" ::: "memory")
; #define WAIT_L(n) asm volatile("s_waitcnt lgkmcnt(" #n ")" ::: "memory")
; #define BAR __builtin_amdgcn_s_barrier()
; #define SCHED __builtin_amdgcn_sched_barrier(0)
; template <int PART  , bool SYNC_FIRST = true>
; __device__ __forceinline__ void kloop_t(const u16* __restrict__ A, int lda, const u16* __restrict__ Bt, int ldb, int K, Acc& acc, const int wv) {
;     ...
;     LDB(B1, 1, 1); STAGE(SB(1, 0), Bt, ldb, 0, t + 3);
;     BAR; WAIT_L(0); MMA(0, 1, At, B1); BAR;
;     LDA(At, 1, 1); STAGE(SA(1, 0), A, lda, 0, t + 3);
;     BAR; WAIT_L(0); MMA(1, 0, At, B0); BAR; SCHED;
;     STAGE(SB(1, 1), Bt, ldb, HALF, t + 3);
;     WAIT_V(6); BAR; MMA(1, 1, At, B1); BAR;
;   }
;   { LDB(B0, 0, 0); LDA(At, 0, 0); STAGE(SA(1, 1), A, lda, HALF, nt - 1);
;     BAR; WAIT_L(0); MMA(0, 0, At, B0); BAR;
	s_waitcnt lgkmcnt(0)
	s_setprio 0
	s_waitcnt lgkmcnt(0)
	v_mfma_f32_16x16x32_bf16 v[92:95], v[230:233], v[198:201], v[92:95]
	v_mfma_f32_16x16x32_bf16 v[88:91], v[238:241], v[198:201], v[88:91]
	v_mfma_f32_16x16x32_bf16 v[84:87], v[230:233], v[206:209], v[84:87]
	v_mfma_f32_16x16x32_bf16 v[80:83], v[238:241], v[206:209], v[80:83]
	v_mfma_f32_16x16x32_bf16 v[76:79], v[230:233], v[214:217], v[76:79]
	v_mfma_f32_16x16x32_bf16 v[72:75], v[238:241], v[214:217], v[72:75]
	v_mfma_f32_16x16x32_bf16 v[68:71], v[230:233], v[222:225], v[68:71]
	v_mfma_f32_16x16x32_bf16 v[64:67], v[238:241], v[222:225], v[64:67]
	v_mfma_f32_16x16x32_bf16 v[92:95], v[234:237], v[202:205], v[92:95]
	v_mfma_f32_16x16x32_bf16 v[88:91], v[242:245], v[202:205], v[88:91]
	v_mfma_f32_16x16x32_bf16 v[84:87], v[234:237], v[210:213], v[84:87]
	v_mfma_f32_16x16x32_bf16 v[80:83], v[242:245], v[210:213], v[80:83]
	v_mfma_f32_16x16x32_bf16 v[76:79], v[234:237], v[218:221], v[76:79]
	v_mfma_f32_16x16x32_bf16 v[72:75], v[242:245], v[218:221], v[72:75]
	v_mfma_f32_16x16x32_bf16 v[68:71], v[234:237], v[226:229], v[68:71]
	v_mfma_f32_16x16x32_bf16 v[64:67], v[242:245], v[226:229], v[64:67]
	s_setprio 1
	v_mov_b32_e32 v246, v131
	v_mov_b32_e32 v128, v130
	s_barrier
	ds_read_b128 v[198:201], v132 offset:49152
	ds_read_b128 v[202:205], v133 offset:49152
	ds_read_b128 v[206:209], v134 offset:49152
	ds_read_b128 v[210:213], v135 offset:49152
	ds_read_b128 v[214:217], v136 offset:49152
	ds_read_b128 v[218:221], v137 offset:49152
	ds_read_b128 v[222:225], v138 offset:49152
	ds_read_b128 v[226:229], v139 offset:49152
	v_readfirstlane_b32 s91, v152
	v_lshl_add_u64 v[248:249], s[44:45], 0, v[128:129]
	v_mov_b32_e32 v247, v129
	v_lshl_add_u64 v[248:249], v[248:249], 0, s[38:39]
	s_mov_b32 m0, s91
	v_lshl_add_u64 v[246:247], s[44:45], 0, v[246:247]
	v_readfirstlane_b32 s44, v153
	global_load_lds_dwordx4 v[248:249], off
	v_lshl_add_u64 v[246:247], v[246:247], 0, s[38:39]
	s_mov_b32 m0, s44
	s_nop 0
	global_load_lds_dwordx4 v[246:247], off
	s_barrier
	s_waitcnt lgkmcnt(0)
	s_setprio 0
	s_waitcnt lgkmcnt(0)
	v_mfma_f32_16x16x32_bf16 v[60:63], v[182:185], v[198:201], v[60:63]
	v_mfma_f32_16x16x32_bf16 v[56:59], v[190:193], v[198:201], v[56:59]
	v_mfma_f32_16x16x32_bf16 v[52:55], v[182:185], v[206:209], v[52:55]
	v_mfma_f32_16x16x32_bf16 v[48:51], v[190:193], v[206:209], v[48:51]
	v_mfma_f32_16x16x32_bf16 v[44:47], v[182:185], v[214:217], v[44:47]
	v_mfma_f32_16x16x32_bf16 v[40:43], v[190:193], v[214:217], v[40:43]
	v_mfma_f32_16x16x32_bf16 v[36:39], v[182:185], v[222:225], v[36:39]
	v_mfma_f32_16x16x32_bf16 v[32:35], v[190:193], v[222:225], v[32:35]
	v_mfma_f32_16x16x32_bf16 v[60:63], v[186:189], v[202:205], v[60:63]
	v_mfma_f32_16x16x32_bf16 v[56:59], v[194:197], v[202:205], v[56:59]
	v_mfma_f32_16x16x32_bf16 v[52:55], v[186:189], v[210:213], v[52:55]
	v_mfma_f32_16x16x32_bf16 v[48:51], v[194:197], v[210:213], v[48:51]
	v_mfma_f32_16x16x32_bf16 v[44:47], v[186:189], v[218:221], v[44:47]
	v_mfma_f32_16x16x32_bf16 v[40:43], v[194:197], v[218:221], v[40:43]
	v_mfma_f32_16x16x32_bf16 v[36:39], v[186:189], v[226:229], v[36:39]
	v_mfma_f32_16x16x32_bf16 v[32:35], v[194:197], v[226:229], v[32:35]
	s_setprio 1
	s_barrier
	v_mov_b32_e32 v182, v131
	v_mov_b32_e32 v128, v130
	v_readfirstlane_b32 s44, v154
	v_lshl_add_u64 v[184:185], s[52:53], 0, v[128:129]
	v_mov_b32_e32 v183, v129
	v_lshl_add_u64 v[184:185], v[184:185], 0, s[40:41]
	s_mov_b32 m0, s44
	v_lshl_add_u64 v[182:183], s[52:53], 0, v[182:183]
	v_readfirstlane_b32 s44, v155
	global_load_lds_dwordx4 v[184:185], off
	v_lshl_add_u64 v[182:183], v[182:183], 0, s[40:41]
	s_mov_b32 m0, s44
	s_nop 0
	global_load_lds_dwordx4 v[182:183], off
	s_waitcnt vmcnt(6)
	s_barrier
	s_setprio 0
	v_mfma_f32_16x16x32_bf16 v[28:31], v[230:233], v[198:201], v[28:31]
	v_mfma_f32_16x16x32_bf16 v[24:27], v[238:241], v[198:201], v[24:27]
	v_mfma_f32_16x16x32_bf16 v[20:23], v[230:233], v[206:209], v[20:23]
	v_mfma_f32_16x16x32_bf16 v[16:19], v[238:241], v[206:209], v[16:19]
	v_mfma_f32_16x16x32_bf16 v[12:15], v[230:233], v[214:217], v[12:15]
	v_mfma_f32_16x16x32_bf16 v[8:11], v[238:241], v[214:217], v[8:11]
	v_mfma_f32_16x16x32_bf16 v[4:7], v[230:233], v[222:225], v[4:7]
	v_mfma_f32_16x16x32_bf16 v[0:3], v[238:241], v[222:225], v[0:3]
	v_mfma_f32_16x16x32_bf16 v[28:31], v[234:237], v[202:205], v[28:31]
	v_mfma_f32_16x16x32_bf16 v[24:27], v[242:245], v[202:205], v[24:27]
	v_mfma_f32_16x16x32_bf16 v[20:23], v[234:237], v[210:213], v[20:23]
	v_mfma_f32_16x16x32_bf16 v[16:19], v[242:245], v[210:213], v[16:19]
	v_mfma_f32_16x16x32_bf16 v[12:15], v[234:237], v[218:221], v[12:15]
	v_mfma_f32_16x16x32_bf16 v[8:11], v[242:245], v[218:221], v[8:11]
	v_mfma_f32_16x16x32_bf16 v[4:7], v[234:237], v[226:229], v[4:7]
	v_mfma_f32_16x16x32_bf16 v[0:3], v[242:245], v[226:229], v[0:3]
	s_setprio 1
	s_add_i32 s90, s90, 2
	s_add_u32 s6, s6, 0x100
	s_addc_u32 s7, s7, 0
	s_cmp_lt_u32 s90, 12
	s_barrier
	s_cbranch_scc1 .LBB0_318
	s_add_u32 s0, s0, 0x40780
	v_readfirstlane_b32 s4, v168
	s_addc_u32 s1, s1, 0
	s_mov_b32 m0, s4
	v_readfirstlane_b32 s4, v169
	ds_read_b128 v[140:143], v164
	ds_read_b128 v[148:151], v165
	ds_read_b128 v[152:155], v166
	ds_read_b128 v[156:159], v167
	ds_read_b128 v[160:163], v132
	ds_read_b128 v[164:167], v133
	ds_read_b128 v[182:185], v134
	ds_read_b128 v[186:189], v135
	ds_read_b128 v[190:193], v136
	ds_read_b128 v[194:197], v137
	ds_read_b128 v[198:201], v138
	ds_read_b128 v[202:205], v139
	s_nop 0
	global_load_lds_dwordx4 v130, s[0:1]
	s_mov_b32 m0, s4
	s_nop 0
	global_load_lds_dwordx4 v131, s[0:1]
	s_barrier
; #define LDA(dst, b, h) for (int m = 0; m < 4; ++m) for (int k = 0; k < 2; ++k) \
;     dst[m][k] = *reinterpret_cast<const bf16x8*>((char*)SA(b, h) + lds_byte(wr * 64 + m * 16 + fr, k * 32 + fq * 8))
; #define LDB(dst, b, h) for (int n = 0; n < 2; ++n) for (int k = 0; k < 2; ++k) \
;     dst[n][k] = *reinterpret_cast<const bf16x8*>((char*)SB(b, h) + lds_byte(wc * 32 + n * 16 + fr, k * 32 + fq * 8))
; #define MMA(ai, bj, At_, Bt_) do { __builtin_amdgcn_s_setprio(1); \
;     for (int m = 0; m < 4; ++m) for (int n = 0; n < 2; ++n) for (int k = 0; k < 2; ++k) \
;       acc[ai][bj][m][n] = MFMA16(Bt_[n][k], At_[m][k], acc[ai][bj][m][n]); \
;     __builtin_amdgcn_s_setprio(0); } while (0)
; #define WAIT_V(n) asm volatile("s_waitcnt vmcnt(" #n ")" ::: "memory")
; #define WAIT_L(n) asm volatile("s_waitcnt lgkmcnt(" #n ")" ::: "memory")
; #define BAR __builtin_amdgcn_s_barrier()
; template <int PART  , bool SYNC_FIRST = true>
; __device__ __forceinline__ void kloop_t(const u16* __restrict__ A, int lda, const u16* __restrict__ Bt, int ldb, int K, Acc& acc, const int wv) {
;     ...
;     BAR; WAIT_L(0); MMA(0, 0, At, B0); BAR;
;     LDB(B1, 0, 1); BAR; WAIT_L(0); MMA(0, 1, At, B1); BAR;
;     LDA(At, 0, 1); WAIT_V(4); BAR; WAIT_L(0); MMA(1, 0, At, B0); MMA(1, 1, At, B1); BAR; }
	s_waitcnt lgkmcnt(0)
	s_setprio 0
	s_waitcnt lgkmcnt(0)
	v_mfma_f32_16x16x32_bf16 v[124:127], v[140:143], v[160:163], v[124:127]
	v_mfma_f32_16x16x32_bf16 v[120:123], v[152:155], v[160:163], v[120:123]
	v_mfma_f32_16x16x32_bf16 v[116:119], v[140:143], v[182:185], v[116:119]
	v_mfma_f32_16x16x32_bf16 v[112:115], v[152:155], v[182:185], v[112:115]
	v_mfma_f32_16x16x32_bf16 v[100:103], v[140:143], v[198:201], v[100:103]
	v_mfma_f32_16x16x32_bf16 v[96:99], v[152:155], v[198:201], v[96:99]
	v_mfma_f32_16x16x32_bf16 v[124:127], v[148:151], v[164:167], v[124:127]
	v_mfma_f32_16x16x32_bf16 v[120:123], v[156:159], v[164:167], v[120:123]
	v_mfma_f32_16x16x32_bf16 v[116:119], v[148:151], v[186:189], v[116:119]
	v_mfma_f32_16x16x32_bf16 v[112:115], v[156:159], v[186:189], v[112:115]
	v_mfma_f32_16x16x32_bf16 v[108:111], v[140:143], v[190:193], v[108:111]
	v_mfma_f32_16x16x32_bf16 v[104:107], v[152:155], v[190:193], v[104:107]
	v_mfma_f32_16x16x32_bf16 v[100:103], v[148:151], v[202:205], v[100:103]
	v_mfma_f32_16x16x32_bf16 v[96:99], v[156:159], v[202:205], v[96:99]
	v_mfma_f32_16x16x32_bf16 v[206:209], v[148:151], v[194:197], v[108:111]
	v_mfma_f32_16x16x32_bf16 v[210:213], v[156:159], v[194:197], v[104:107]
	s_setprio 1
	s_barrier
	s_nop 1
	ds_read_b128 v[104:107], v170
	ds_read_b128 v[108:111], v171
	ds_read_b128 v[168:171], v172
	ds_read_b128 v[214:217], v173
	s_barrier
	s_waitcnt lgkmcnt(0)
	s_setprio 0
	s_waitcnt lgkmcnt(0)
	v_mfma_f32_16x16x32_bf16 v[84:87], v[104:107], v[182:185], v[84:87]
	v_mfma_f32_16x16x32_bf16 v[80:83], v[168:171], v[182:185], v[80:83]
	v_mfma_f32_16x16x32_bf16 v[68:71], v[104:107], v[198:201], v[68:71]
	v_mfma_f32_16x16x32_bf16 v[64:67], v[168:171], v[198:201], v[64:67]
	v_mfma_f32_16x16x32_bf16 v[92:95], v[104:107], v[160:163], v[92:95]
	v_mfma_f32_16x16x32_bf16 v[88:91], v[168:171], v[160:163], v[88:91]
	v_mfma_f32_16x16x32_bf16 v[84:87], v[108:111], v[186:189], v[84:87]
	v_mfma_f32_16x16x32_bf16 v[80:83], v[214:217], v[186:189], v[80:83]
	v_mfma_f32_16x16x32_bf16 v[76:79], v[104:107], v[190:193], v[76:79]
	v_mfma_f32_16x16x32_bf16 v[72:75], v[168:171], v[190:193], v[72:75]
	v_mfma_f32_16x16x32_bf16 v[68:71], v[108:111], v[202:205], v[68:71]
	v_mfma_f32_16x16x32_bf16 v[64:67], v[214:217], v[202:205], v[64:67]
	v_mfma_f32_16x16x32_bf16 v[218:221], v[108:111], v[164:167], v[92:95]
	v_mfma_f32_16x16x32_bf16 v[160:163], v[214:217], v[164:167], v[88:91]
	v_mfma_f32_16x16x32_bf16 v[164:167], v[108:111], v[194:197], v[76:79]
	v_mfma_f32_16x16x32_bf16 v[182:185], v[214:217], v[194:197], v[72:75]
	s_setprio 1
	s_barrier
	s_nop 0
	ds_read_b128 v[72:75], v132 offset:16384
	ds_read_b128 v[76:79], v133 offset:16384
	ds_read_b128 v[88:91], v134 offset:16384
	ds_read_b128 v[92:95], v135 offset:16384
	ds_read_b128 v[186:189], v136 offset:16384
	ds_read_b128 v[190:193], v137 offset:16384
	ds_read_b128 v[194:197], v138 offset:16384
	ds_read_b128 v[198:201], v139 offset:16384
	s_waitcnt vmcnt(4)
	s_barrier
	s_waitcnt lgkmcnt(0)
	s_setprio 0
	s_waitcnt lgkmcnt(0)
	v_mfma_f32_16x16x32_bf16 v[60:63], v[140:143], v[72:75], v[60:63]
	v_mfma_f32_16x16x32_bf16 v[56:59], v[152:155], v[72:75], v[56:59]
	v_mfma_f32_16x16x32_bf16 v[52:55], v[140:143], v[88:91], v[52:55]
	v_mfma_f32_16x16x32_bf16 v[48:51], v[152:155], v[88:91], v[48:51]
	v_mfma_f32_16x16x32_bf16 v[36:39], v[140:143], v[194:197], v[36:39]
	v_mfma_f32_16x16x32_bf16 v[32:35], v[152:155], v[194:197], v[32:35]
	v_mfma_f32_16x16x32_bf16 v[60:63], v[148:151], v[76:79], v[60:63]
	v_mfma_f32_16x16x32_bf16 v[56:59], v[156:159], v[76:79], v[56:59]
	v_mfma_f32_16x16x32_bf16 v[52:55], v[148:151], v[92:95], v[52:55]
	v_mfma_f32_16x16x32_bf16 v[48:51], v[156:159], v[92:95], v[48:51]
	v_mfma_f32_16x16x32_bf16 v[44:47], v[140:143], v[186:189], v[44:47]
	v_mfma_f32_16x16x32_bf16 v[40:43], v[152:155], v[186:189], v[40:43]
	v_mfma_f32_16x16x32_bf16 v[36:39], v[148:151], v[198:201], v[36:39]
	v_mfma_f32_16x16x32_bf16 v[32:35], v[156:159], v[198:201], v[32:35]
	v_mfma_f32_16x16x32_bf16 v[202:205], v[148:151], v[190:193], v[44:47]
	v_mfma_f32_16x16x32_bf16 v[222:225], v[156:159], v[190:193], v[40:43]
	s_setprio 1
	s_setprio 0
	v_mfma_f32_16x16x32_bf16 v[20:23], v[104:107], v[88:91], v[20:23]
	v_mfma_f32_16x16x32_bf16 v[16:19], v[168:171], v[88:91], v[16:19]
	v_mfma_f32_16x16x32_bf16 v[4:7], v[104:107], v[194:197], v[4:7]
	v_mfma_f32_16x16x32_bf16 v[0:3], v[168:171], v[194:197], v[0:3]
	v_mfma_f32_16x16x32_bf16 v[28:31], v[104:107], v[72:75], v[28:31]
	v_mfma_f32_16x16x32_bf16 v[24:27], v[168:171], v[72:75], v[24:27]
	v_mfma_f32_16x16x32_bf16 v[20:23], v[108:111], v[92:95], v[20:23]
	v_mfma_f32_16x16x32_bf16 v[16:19], v[214:217], v[92:95], v[16:19]
	v_mfma_f32_16x16x32_bf16 v[12:15], v[104:107], v[186:189], v[12:15]
	v_mfma_f32_16x16x32_bf16 v[8:11], v[168:171], v[186:189], v[8:11]
	v_mfma_f32_16x16x32_bf16 v[4:7], v[108:111], v[198:201], v[4:7]
	v_mfma_f32_16x16x32_bf16 v[0:3], v[214:217], v[198:201], v[0:3]
	v_mfma_f32_16x16x32_bf16 v[140:143], v[108:111], v[76:79], v[28:31]
	v_mfma_f32_16x16x32_bf16 v[148:151], v[214:217], v[76:79], v[24:27]
	v_mfma_f32_16x16x32_bf16 v[152:155], v[108:111], v[190:193], v[12:15]
	v_mfma_f32_16x16x32_bf16 v[156:159], v[214:217], v[190:193], v[8:11]
	s_setprio 1
	s_barrier
; #define LDA(dst, b, h) for (int m = 0; m < 4; ++m) for (int k = 0; k < 2; ++k) \
;     dst[m][k] = *reinterpret_cast<const bf16x8*>((char*)SA(b, h) + lds_byte(wr * 64 + m * 16 + fr, k * 32 + fq * 8))
; #define LDB(dst, b, h) for (int n = 0; n < 2; ++n) for (int k = 0; k < 2; ++k) \
;     dst[n][k] = *reinterpret_cast<const bf16x8*>((char*)SB(b, h) + lds_byte(wc * 32 + n * 16 + fr, k * 32 + fq * 8))
; #define MMA(ai, bj, At_, Bt_) do { __builtin_amdgcn_s_setprio(1); \
;     for (int m = 0; m < 4; ++m) for (int n = 0; n < 2; ++n) for (int k = 0; k < 2; ++k) \
;       acc[ai][bj][m][n] = MFMA16(Bt_[n][k], At_[m][k], acc[ai][bj][m][n]); \
;     __builtin_amdgcn_s_setprio(0); } while (0)
; #define WAIT_V(n) asm volatile("s_waitcnt vmcnt(" #n ")" ::: "memory")
; #define WAIT_L(n) asm volatile("s_waitcnt lgkmcnt(" #n ")" ::: "memory")
; #define BAR __builtin_amdgcn_s_barrier()
; template <int PART  , bool SYNC_FIRST = true>
; __device__ __forceinline__ void kloop_t(const u16* __restrict__ A, int lda, const u16* __restrict__ Bt, int ldb, int K, Acc& acc, const int wv) {
;     ...
;   { LDB(B0, 1, 0); LDA(At, 1, 0); WAIT_V(2); BAR; WAIT_L(0); MMA(0, 0, At, B0); BAR;
;     LDB(B1, 1, 1); WAIT_V(0); BAR; WAIT_L(0); MMA(0, 1, At, B1); BAR;
;     LDA(At, 1, 1); BAR; WAIT_L(0); MMA(1, 0, At, B0); MMA(1, 1, At, B1); BAR; }
;   if (wr == 0) BAR;
	s_nop 0
	ds_read_b128 v[8:11], v174
	ds_read_b128 v[12:15], v175
	ds_read_b128 v[168:171], v176
	ds_read_b128 v[172:175], v177
	ds_read_b128 v[24:27], v132 offset:32768
	ds_read_b128 v[28:31], v133 offset:32768
	ds_read_b128 v[40:43], v134 offset:32768
	ds_read_b128 v[44:47], v135 offset:32768
	ds_read_b128 v[186:189], v136 offset:32768
	ds_read_b128 v[190:193], v137 offset:32768
	ds_read_b128 v[194:197], v138 offset:32768
	ds_read_b128 v[198:201], v139 offset:32768
	s_waitcnt vmcnt(2)
	s_barrier
	s_waitcnt lgkmcnt(0)
	s_setprio 0
	s_waitcnt lgkmcnt(0)
	v_mfma_f32_16x16x32_bf16 v[72:75], v[8:11], v[24:27], v[124:127]
	v_mfma_f32_16x16x32_bf16 v[124:127], v[12:15], v[28:31], v[72:75]
	v_mfma_f32_16x16x32_bf16 v[72:75], v[168:171], v[24:27], v[120:123]
	v_mfma_f32_16x16x32_bf16 v[120:123], v[172:175], v[28:31], v[72:75]
	v_mfma_f32_16x16x32_bf16 v[72:75], v[8:11], v[40:43], v[116:119]
	v_mfma_f32_16x16x32_bf16 v[108:111], v[12:15], v[44:47], v[72:75]
	v_mfma_f32_16x16x32_bf16 v[72:75], v[168:171], v[40:43], v[112:115]
	v_mfma_f32_16x16x32_bf16 v[104:107], v[172:175], v[44:47], v[72:75]
	v_mfma_f32_16x16x32_bf16 v[72:75], v[8:11], v[186:189], v[206:209]
	v_mfma_f32_16x16x32_bf16 v[92:95], v[12:15], v[190:193], v[72:75]
	v_mfma_f32_16x16x32_bf16 v[72:75], v[168:171], v[186:189], v[210:213]
	v_mfma_f32_16x16x32_bf16 v[88:91], v[172:175], v[190:193], v[72:75]
	v_mfma_f32_16x16x32_bf16 v[72:75], v[8:11], v[194:197], v[100:103]
	v_mfma_f32_16x16x32_bf16 v[76:79], v[12:15], v[198:201], v[72:75]
	v_mfma_f32_16x16x32_bf16 v[72:75], v[168:171], v[194:197], v[96:99]
	v_mfma_f32_16x16x32_bf16 v[72:75], v[172:175], v[198:201], v[72:75]
	s_setprio 1
	s_barrier
	ds_read_b128 v[206:209], v178
	ds_read_b128 v[176:179], v179
	ds_read_b128 v[210:213], v180
	ds_read_b128 v[214:217], v181
	s_waitcnt vmcnt(0)
	s_barrier
	s_waitcnt lgkmcnt(0)
	s_setprio 0
	s_waitcnt lgkmcnt(0)
	v_mfma_f32_16x16x32_bf16 v[96:99], v[206:209], v[24:27], v[218:221]
	v_mfma_f32_16x16x32_bf16 v[24:27], v[210:213], v[24:27], v[160:163]
	v_mfma_f32_16x16x32_bf16 v[112:115], v[214:217], v[28:31], v[24:27]
	v_mfma_f32_16x16x32_bf16 v[24:27], v[206:209], v[40:43], v[84:87]
	v_mfma_f32_16x16x32_bf16 v[100:103], v[176:179], v[44:47], v[24:27]
	v_mfma_f32_16x16x32_bf16 v[24:27], v[210:213], v[40:43], v[80:83]
	v_mfma_f32_16x16x32_bf16 v[116:119], v[176:179], v[28:31], v[96:99]
	v_mfma_f32_16x16x32_bf16 v[96:99], v[214:217], v[44:47], v[24:27]
	v_mfma_f32_16x16x32_bf16 v[24:27], v[206:209], v[186:189], v[164:167]
	v_mfma_f32_16x16x32_bf16 v[84:87], v[176:179], v[190:193], v[24:27]
	v_mfma_f32_16x16x32_bf16 v[24:27], v[210:213], v[186:189], v[182:185]
	v_mfma_f32_16x16x32_bf16 v[80:83], v[214:217], v[190:193], v[24:27]
	v_mfma_f32_16x16x32_bf16 v[24:27], v[206:209], v[194:197], v[68:71]
	v_mfma_f32_16x16x32_bf16 v[68:71], v[176:179], v[198:201], v[24:27]
	v_mfma_f32_16x16x32_bf16 v[24:27], v[210:213], v[194:197], v[64:67]
	v_mfma_f32_16x16x32_bf16 v[64:67], v[214:217], v[198:201], v[24:27]
	s_setprio 1
	s_barrier
	ds_read_b128 v[160:163], v132 offset:49152
	ds_read_b128 v[130:133], v133 offset:49152
	ds_read_b128 v[164:167], v134 offset:49152
	ds_read_b128 v[180:183], v135 offset:49152
	ds_read_b128 v[184:187], v136 offset:49152
	ds_read_b128 v[134:137], v137 offset:49152
	ds_read_b128 v[188:191], v138 offset:49152
	ds_read_b128 v[192:195], v139 offset:49152
	s_barrier
	s_waitcnt lgkmcnt(0)
	s_setprio 0
	s_waitcnt lgkmcnt(0)
	v_mfma_f32_16x16x32_bf16 v[24:27], v[8:11], v[160:163], v[60:63]
	v_mfma_f32_16x16x32_bf16 v[60:63], v[12:15], v[130:133], v[24:27]
	v_mfma_f32_16x16x32_bf16 v[24:27], v[168:171], v[160:163], v[56:59]
	v_mfma_f32_16x16x32_bf16 v[56:59], v[172:175], v[130:133], v[24:27]
	v_mfma_f32_16x16x32_bf16 v[24:27], v[8:11], v[164:167], v[52:55]
	v_mfma_f32_16x16x32_bf16 v[44:47], v[12:15], v[180:183], v[24:27]
	v_mfma_f32_16x16x32_bf16 v[24:27], v[168:171], v[164:167], v[48:51]
	v_mfma_f32_16x16x32_bf16 v[40:43], v[172:175], v[180:183], v[24:27]
	v_mfma_f32_16x16x32_bf16 v[24:27], v[8:11], v[184:187], v[202:205]
	v_mfma_f32_16x16x32_bf16 v[8:11], v[8:11], v[188:191], v[36:39]
	v_mfma_f32_16x16x32_bf16 v[28:31], v[12:15], v[134:137], v[24:27]
	v_mfma_f32_16x16x32_bf16 v[24:27], v[168:171], v[184:187], v[222:225]
	v_mfma_f32_16x16x32_bf16 v[12:15], v[12:15], v[192:195], v[8:11]
	v_mfma_f32_16x16x32_bf16 v[8:11], v[168:171], v[188:191], v[32:35]
	v_mfma_f32_16x16x32_bf16 v[24:27], v[172:175], v[134:137], v[24:27]
	v_mfma_f32_16x16x32_bf16 v[8:11], v[172:175], v[192:195], v[8:11]
	s_setprio 1
	s_setprio 0
	v_mfma_f32_16x16x32_bf16 v[32:35], v[206:209], v[160:163], v[140:143]
	v_mfma_f32_16x16x32_bf16 v[52:55], v[176:179], v[130:133], v[32:35]
	v_mfma_f32_16x16x32_bf16 v[32:35], v[210:213], v[160:163], v[148:151]
	v_mfma_f32_16x16x32_bf16 v[16:19], v[210:213], v[164:167], v[16:19]
	v_mfma_f32_16x16x32_bf16 v[48:51], v[214:217], v[130:133], v[32:35]
	v_mfma_f32_16x16x32_bf16 v[20:23], v[206:209], v[164:167], v[20:23]
	v_mfma_f32_16x16x32_bf16 v[32:35], v[214:217], v[180:183], v[16:19]
	v_mfma_f32_16x16x32_bf16 v[16:19], v[206:209], v[184:187], v[152:155]
	v_mfma_f32_16x16x32_bf16 v[36:39], v[176:179], v[180:183], v[20:23]
	v_mfma_f32_16x16x32_bf16 v[20:23], v[176:179], v[134:137], v[16:19]
	v_mfma_f32_16x16x32_bf16 v[16:19], v[210:213], v[184:187], v[156:159]
	v_mfma_f32_16x16x32_bf16 v[4:7], v[206:209], v[188:191], v[4:7]
	v_mfma_f32_16x16x32_bf16 v[0:3], v[210:213], v[188:191], v[0:3]
	v_mfma_f32_16x16x32_bf16 v[16:19], v[214:217], v[134:137], v[16:19]
	v_mfma_f32_16x16x32_bf16 v[4:7], v[176:179], v[192:195], v[4:7]
	v_mfma_f32_16x16x32_bf16 v[0:3], v[214:217], v[192:195], v[0:3]
	s_setprio 1
	s_andn2_b64 vcc, exec, s[12:13]
	s_barrier
	s_cbranch_vccnz .LBB0_321
	s_barrier

; #define LDA(dst, b, h) for (int m = 0; m < 4; ++m) for (int k = 0; k < 2; ++k) \
;     dst[m][k] = *reinterpret_cast<const bf16x8*>((char*)SA(b, h) + lds_byte(wr * 64 + m * 16 + fr, k * 32 + fq * 8))
; #define LDB(dst, b, h) for (int n = 0; n < 2; ++n) for (int k = 0; k < 2; ++k) \
;     dst[n][k] = *reinterpret_cast<const bf16x8*>((char*)SB(b, h) + lds_byte(wc * 32 + n * 16 + fr, k * 32 + fq * 8))
; #define MMA(ai, bj, At_, Bt_) do { __builtin_amdgcn_s_setprio(1); \
;     for (int m = 0; m < 4; ++m) for (int n = 0; n < 2; ++n) for (int k = 0; k < 2; ++k) \
;       acc[ai][bj][m][n] = MFMA16(Bt_[n][k], At_[m][k], acc[ai][bj][m][n]); \
;     __builtin_amdgcn_s_setprio(0); } while (0)
; #define WAIT_L(n) asm volatile("s_waitcnt lgkmcnt(" #n ")" ::: "memory")
; #define BAR __builtin_amdgcn_s_barrier()
; #define SCHED __builtin_amdgcn_sched_barrier(0)
; template <int PART  , bool SYNC_FIRST = true>
; __device__ __forceinline__ void kloop_t(const u16* __restrict__ A, int lda, const u16* __restrict__ Bt, int ldb, int K, Acc& acc, const int wv) {
;     ...
;     LDB(B0, 0, 0); SCHED; LDA(At, 0, 0); STAGE(SA(1, 1), A, lda, HALF, t + 1);
;     WAIT_L(8); BAR; WAIT_L(0); MMA(0, 0, At, B0); BAR; SCHED;
;     LDB(B1, 0, 1); STAGE(SB(0, 0), Bt, ldb, 0, t + 2);
;     BAR; WAIT_L(0); MMA(0, 1, At, B1); BAR;
;     LDA(At, 0, 1); STAGE(SA(0, 0), A, lda, 0, t + 2);
.LBB0_704:
	v_add_u32_e32 v156, v148, v152
	v_add_u32_e32 v158, v148, v154
	v_add_u32_e32 v157, v148, v153
	ds_read_b128 v[166:169], v156
	ds_read_b128 v[170:173], v157
	v_add_u32_e32 v159, v148, v155
	ds_read_b128 v[174:177], v158
	ds_read_b128 v[178:181], v159
	s_add_u32 s58, s18, s56
	v_mov_b32_e32 v0, v130
	v_mov_b32_e32 v162, v132
	s_addc_u32 s59, vcc_lo, s57
	ds_read_b128 v[182:185], v134
	ds_read_b128 v[188:191], v135
	ds_read_b128 v[192:195], v136
	ds_read_b128 v[196:199], v137
	ds_read_b128 v[200:203], v138
	ds_read_b128 v[204:207], v139
	ds_read_b128 v[208:211], v140
	ds_read_b128 v[212:215], v141
	v_mov_b32_e32 v163, v1
	v_lshl_add_u64 v[160:161], s[58:59], 0, v[0:1]
	v_lshl_add_u64 v[164:165], v[160:161], 0, s[20:21]
	v_add_u32_e32 v160, 0xc000, v143
	v_add_u32_e32 v161, 0xe000, v143
	v_readfirstlane_b32 s60, v160
	s_mov_b32 m0, s60
	v_lshl_add_u64 v[162:163], s[58:59], 0, v[162:163]
	v_readfirstlane_b32 s60, v161
	global_load_lds_dwordx4 v[164:165], off
	v_lshl_add_u64 v[162:163], v[162:163], 0, s[20:21]
	s_mov_b32 m0, s60
	s_nop 0
	global_load_lds_dwordx4 v[162:163], off
	s_waitcnt lgkmcnt(8)
	s_barrier
	s_waitcnt lgkmcnt(0)
	s_setprio 0
	s_waitcnt lgkmcnt(0)
	v_mfma_f32_16x16x32_bf16 v[30:33], v[166:169], v[182:185], v[30:33]
	v_mfma_f32_16x16x32_bf16 v[38:41], v[174:177], v[182:185], v[38:41]
	v_mfma_f32_16x16x32_bf16 v[70:73], v[166:169], v[192:195], v[70:73]
	v_mfma_f32_16x16x32_bf16 v[78:81], v[174:177], v[192:195], v[78:81]
	v_mfma_f32_16x16x32_bf16 v[106:109], v[166:169], v[200:203], v[106:109]
	v_mfma_f32_16x16x32_bf16 v[114:117], v[174:177], v[200:203], v[114:117]
	v_mfma_f32_16x16x32_bf16 v[122:125], v[166:169], v[208:211], v[122:125]
	v_mfma_f32_16x16x32_bf16 v[110:113], v[174:177], v[208:211], v[110:113]
	v_mfma_f32_16x16x32_bf16 v[30:33], v[170:173], v[188:191], v[30:33]
	v_mfma_f32_16x16x32_bf16 v[38:41], v[178:181], v[188:191], v[38:41]
	v_mfma_f32_16x16x32_bf16 v[70:73], v[170:173], v[196:199], v[70:73]
	v_mfma_f32_16x16x32_bf16 v[78:81], v[178:181], v[196:199], v[78:81]
	v_mfma_f32_16x16x32_bf16 v[106:109], v[170:173], v[204:207], v[106:109]
	v_mfma_f32_16x16x32_bf16 v[114:117], v[178:181], v[204:207], v[114:117]
	v_mfma_f32_16x16x32_bf16 v[122:125], v[170:173], v[212:215], v[122:125]
	v_mfma_f32_16x16x32_bf16 v[110:113], v[178:181], v[212:215], v[110:113]
	s_setprio 1
	s_barrier
	v_add_u32_e32 v162, v149, v152
	v_add_u32_e32 v164, v149, v154
	v_mov_b32_e32 v0, v130
	v_mov_b32_e32 v232, v132
	s_add_u32 s60, s4, s56
	v_add_u32_e32 v163, v149, v153
	ds_read_b128 v[216:219], v162
	ds_read_b128 v[220:223], v163
	v_add_u32_e32 v165, v149, v155
	ds_read_b128 v[224:227], v164
	ds_read_b128 v[228:231], v165
	s_addc_u32 s61, s5, s57
	v_lshl_add_u64 v[234:235], s[60:61], 0, v[0:1]
	v_add_u32_e32 v0, s94, v131
	v_mov_b32_e32 v233, v1
	v_readfirstlane_b32 s62, v0
	v_add_u32_e32 v0, 0x2000, v0
	v_lshl_add_u64 v[234:235], v[234:235], 0, s[22:23]
	s_mov_b32 m0, s62
	v_lshl_add_u64 v[232:233], s[60:61], 0, v[232:233]
	v_readfirstlane_b32 s62, v0
	global_load_lds_dwordx4 v[234:235], off
	v_lshl_add_u64 v[232:233], v[232:233], 0, s[22:23]
	s_mov_b32 m0, s62
	s_nop 0
	global_load_lds_dwordx4 v[232:233], off
	s_barrier
	s_waitcnt lgkmcnt(0)
	s_setprio 0
	s_waitcnt lgkmcnt(0)
	v_mfma_f32_16x16x32_bf16 v[42:45], v[216:219], v[182:185], v[42:45]
	v_mfma_f32_16x16x32_bf16 v[46:49], v[224:227], v[182:185], v[46:49]
	v_mfma_f32_16x16x32_bf16 v[82:85], v[216:219], v[192:195], v[82:85]
	v_mfma_f32_16x16x32_bf16 v[90:93], v[224:227], v[192:195], v[90:93]
	v_mfma_f32_16x16x32_bf16 v[118:121], v[216:219], v[200:203], v[118:121]
	v_mfma_f32_16x16x32_bf16 v[126:129], v[224:227], v[200:203], v[126:129]
	v_mfma_f32_16x16x32_bf16 v[102:105], v[216:219], v[208:211], v[102:105]
	v_mfma_f32_16x16x32_bf16 v[98:101], v[224:227], v[208:211], v[98:101]
	v_mfma_f32_16x16x32_bf16 v[42:45], v[220:223], v[188:191], v[42:45]
	v_mfma_f32_16x16x32_bf16 v[46:49], v[228:231], v[188:191], v[46:49]
	v_mfma_f32_16x16x32_bf16 v[82:85], v[220:223], v[196:199], v[82:85]
	v_mfma_f32_16x16x32_bf16 v[90:93], v[228:231], v[196:199], v[90:93]
	v_mfma_f32_16x16x32_bf16 v[118:121], v[220:223], v[204:207], v[118:121]
	v_mfma_f32_16x16x32_bf16 v[126:129], v[228:231], v[204:207], v[126:129]
	v_mfma_f32_16x16x32_bf16 v[102:105], v[220:223], v[212:215], v[102:105]
	v_mfma_f32_16x16x32_bf16 v[98:101], v[228:231], v[212:215], v[98:101]
	s_setprio 1
	v_mov_b32_e32 v0, v130
	v_mov_b32_e32 v232, v132
	s_add_u32 s62, s0, s56
	s_barrier
	ds_read_b128 v[182:185], v134 offset:16384
	ds_read_b128 v[188:191], v135 offset:16384
	ds_read_b128 v[192:195], v136 offset:16384
	ds_read_b128 v[196:199], v137 offset:16384
	ds_read_b128 v[200:203], v138 offset:16384
	ds_read_b128 v[204:207], v139 offset:16384
	ds_read_b128 v[208:211], v140 offset:16384
	ds_read_b128 v[212:215], v141 offset:16384
	s_addc_u32 s63, s1, s57
	v_lshl_add_u64 v[234:235], s[62:63], 0, v[0:1]
	v_readfirstlane_b32 s64, v143
	v_mov_b32_e32 v233, v1
	v_add_u32_e32 v0, 0x2000, v143
	v_lshl_add_u64 v[234:235], v[234:235], 0, s[22:23]
	s_mov_b32 m0, s64
	v_lshl_add_u64 v[232:233], s[62:63], 0, v[232:233]
	v_readfirstlane_b32 s64, v0
	global_load_lds_dwordx4 v[234:235], off
	v_lshl_add_u64 v[232:233], v[232:233], 0, s[22:23]
	s_mov_b32 m0, s64
	s_nop 0
	global_load_lds_dwordx4 v[232:233], off
	s_barrier
; #define LDA(dst, b, h) for (int m = 0; m < 4; ++m) for (int k = 0; k < 2; ++k) \
;     dst[m][k] = *reinterpret_cast<const bf16x8*>((char*)SA(b, h) + lds_byte(wr * 64 + m * 16 + fr, k * 32 + fq * 8))
; #define LDB(dst, b, h) for (int n = 0; n < 2; ++n) for (int k = 0; k < 2; ++k) \
;     dst[n][k] = *reinterpret_cast<const bf16x8*>((char*)SB(b, h) + lds_byte(wc * 32 + n * 16 + fr, k * 32 + fq * 8))
; #define MMA(ai, bj, At_, Bt_) do { __builtin_amdgcn_s_setprio(1); \
;     for (int m = 0; m < 4; ++m) for (int n = 0; n < 2; ++n) for (int k = 0; k < 2; ++k) \
;       acc[ai][bj][m][n] = MFMA16(Bt_[n][k], At_[m][k], acc[ai][bj][m][n]); \
;     __builtin_amdgcn_s_setprio(0); } while (0)
; #define WAIT_V(n) asm volatile("s_waitcnt vmcnt(" #n ")" ::: "memory")
; #define WAIT_L(n) asm volatile("s_waitcnt lgkmcnt(" #n ")" ::: "memory")
; #define BAR __builtin_amdgcn_s_barrier()
; #define SCHED __builtin_amdgcn_sched_barrier(0)
; template <int PART  , bool SYNC_FIRST = true>
; __device__ __forceinline__ void kloop_t(const u16* __restrict__ A, int lda, const u16* __restrict__ Bt, int ldb, int K, Acc& acc, const int wv) {
;     ...
;     BAR; WAIT_L(0); MMA(1, 0, At, B0); BAR; SCHED;
;     STAGE(SB(0, 1), Bt, ldb, HALF, t + 2);
;     WAIT_V(6); BAR; MMA(1, 1, At, B1); BAR;
;     LDB(B0, 1, 0); SCHED; LDA(At, 1, 0); STAGE(SA(0, 1), A, lda, HALF, t + 2);
;     WAIT_L(8); BAR; WAIT_L(0); MMA(0, 0, At, B0); BAR; SCHED;
	s_waitcnt lgkmcnt(0)
	s_setprio 0
	s_waitcnt lgkmcnt(0)
	v_mfma_f32_16x16x32_bf16 v[94:97], v[166:169], v[182:185], v[94:97]
	v_mfma_f32_16x16x32_bf16 v[86:89], v[174:177], v[182:185], v[86:89]
	v_mfma_f32_16x16x32_bf16 v[62:65], v[166:169], v[192:195], v[62:65]
	v_mfma_f32_16x16x32_bf16 v[58:61], v[174:177], v[192:195], v[58:61]
	v_mfma_f32_16x16x32_bf16 v[34:37], v[166:169], v[200:203], v[34:37]
	v_mfma_f32_16x16x32_bf16 v[26:29], v[174:177], v[200:203], v[26:29]
	v_mfma_f32_16x16x32_bf16 v[14:17], v[166:169], v[208:211], v[14:17]
	v_mfma_f32_16x16x32_bf16 v[10:13], v[174:177], v[208:211], v[10:13]
	v_mfma_f32_16x16x32_bf16 v[94:97], v[170:173], v[188:191], v[94:97]
	v_mfma_f32_16x16x32_bf16 v[86:89], v[178:181], v[188:191], v[86:89]
	v_mfma_f32_16x16x32_bf16 v[62:65], v[170:173], v[196:199], v[62:65]
	v_mfma_f32_16x16x32_bf16 v[58:61], v[178:181], v[196:199], v[58:61]
	v_mfma_f32_16x16x32_bf16 v[34:37], v[170:173], v[204:207], v[34:37]
	v_mfma_f32_16x16x32_bf16 v[26:29], v[178:181], v[204:207], v[26:29]
	v_mfma_f32_16x16x32_bf16 v[14:17], v[170:173], v[212:215], v[14:17]
	v_mfma_f32_16x16x32_bf16 v[10:13], v[178:181], v[212:215], v[10:13]
	s_setprio 1
	s_barrier
	v_mov_b32_e32 v0, v130
	v_mov_b32_e32 v166, v132
	s_add_u32 s64, s8, s56
	s_addc_u32 s65, s9, s57
	v_lshl_add_u64 v[168:169], s[64:65], 0, v[0:1]
	v_add_u32_e32 v0, s95, v131
	v_mov_b32_e32 v167, v1
	v_readfirstlane_b32 s12, v0
	v_add_u32_e32 v0, 0x2000, v0
	v_lshl_add_u64 v[168:169], v[168:169], 0, s[22:23]
	s_mov_b32 m0, s12
	v_lshl_add_u64 v[166:167], s[64:65], 0, v[166:167]
	v_readfirstlane_b32 s12, v0
	global_load_lds_dwordx4 v[168:169], off
	v_lshl_add_u64 v[166:167], v[166:167], 0, s[22:23]
	s_mov_b32 m0, s12
	s_nop 0
	global_load_lds_dwordx4 v[166:167], off
	s_waitcnt vmcnt(6)
	s_barrier
	s_setprio 0
	v_mfma_f32_16x16x32_bf16 v[74:77], v[216:219], v[182:185], v[74:77]
	v_mfma_f32_16x16x32_bf16 v[66:69], v[224:227], v[182:185], v[66:69]
	v_mfma_f32_16x16x32_bf16 v[54:57], v[216:219], v[192:195], v[54:57]
	v_mfma_f32_16x16x32_bf16 v[50:53], v[224:227], v[192:195], v[50:53]
	v_mfma_f32_16x16x32_bf16 v[22:25], v[216:219], v[200:203], v[22:25]
	v_mfma_f32_16x16x32_bf16 v[18:21], v[224:227], v[200:203], v[18:21]
	v_mfma_f32_16x16x32_bf16 v[6:9], v[216:219], v[208:211], v[6:9]
	v_mfma_f32_16x16x32_bf16 v[2:5], v[224:227], v[208:211], v[2:5]
	v_mfma_f32_16x16x32_bf16 v[74:77], v[220:223], v[188:191], v[74:77]
	v_mfma_f32_16x16x32_bf16 v[66:69], v[228:231], v[188:191], v[66:69]
	v_mfma_f32_16x16x32_bf16 v[54:57], v[220:223], v[196:199], v[54:57]
	v_mfma_f32_16x16x32_bf16 v[50:53], v[228:231], v[196:199], v[50:53]
	v_mfma_f32_16x16x32_bf16 v[22:25], v[220:223], v[204:207], v[22:25]
	v_mfma_f32_16x16x32_bf16 v[18:21], v[228:231], v[204:207], v[18:21]
	v_mfma_f32_16x16x32_bf16 v[6:9], v[220:223], v[212:215], v[6:9]
	v_mfma_f32_16x16x32_bf16 v[2:5], v[228:231], v[212:215], v[2:5]
	s_setprio 1
	v_add_u32_e32 v166, v150, v152
	v_add_u32_e32 v168, v150, v154
	s_barrier
	v_add_u32_e32 v167, v150, v153
	ds_read_b128 v[174:177], v166
	ds_read_b128 v[178:181], v167
	v_add_u32_e32 v169, v150, v155
	ds_read_b128 v[182:185], v168
	ds_read_b128 v[188:191], v169
	v_mov_b32_e32 v0, v130
	v_mov_b32_e32 v170, v132
	ds_read_b128 v[192:195], v134 offset:32768
	ds_read_b128 v[196:199], v135 offset:32768
	ds_read_b128 v[200:203], v136 offset:32768
	ds_read_b128 v[204:207], v137 offset:32768
	ds_read_b128 v[208:211], v138 offset:32768
	ds_read_b128 v[212:215], v139 offset:32768
	ds_read_b128 v[216:219], v140 offset:32768
	ds_read_b128 v[220:223], v141 offset:32768
	v_mov_b32_e32 v171, v1
	v_lshl_add_u64 v[172:173], s[58:59], 0, v[0:1]
	v_add_u32_e32 v0, 0x4000, v143
	v_lshl_add_u64 v[172:173], v[172:173], 0, s[22:23]
	v_readfirstlane_b32 s12, v0
	v_add_u32_e32 v0, 0x6000, v143
	s_mov_b32 m0, s12
	v_lshl_add_u64 v[170:171], s[58:59], 0, v[170:171]
	v_readfirstlane_b32 s12, v0
	global_load_lds_dwordx4 v[172:173], off
	v_lshl_add_u64 v[170:171], v[170:171], 0, s[22:23]
	s_mov_b32 m0, s12
	s_nop 0
	global_load_lds_dwordx4 v[170:171], off
	s_waitcnt lgkmcnt(8)
	s_barrier
	s_waitcnt lgkmcnt(0)
	s_setprio 0
	s_waitcnt lgkmcnt(0)
	v_mfma_f32_16x16x32_bf16 v[30:33], v[174:177], v[192:195], v[30:33]
	v_mfma_f32_16x16x32_bf16 v[38:41], v[182:185], v[192:195], v[38:41]
	v_mfma_f32_16x16x32_bf16 v[70:73], v[174:177], v[200:203], v[70:73]
	v_mfma_f32_16x16x32_bf16 v[78:81], v[182:185], v[200:203], v[78:81]
	v_mfma_f32_16x16x32_bf16 v[106:109], v[174:177], v[208:211], v[106:109]
	v_mfma_f32_16x16x32_bf16 v[114:117], v[182:185], v[208:211], v[114:117]
	v_mfma_f32_16x16x32_bf16 v[122:125], v[174:177], v[216:219], v[122:125]
	v_mfma_f32_16x16x32_bf16 v[110:113], v[182:185], v[216:219], v[110:113]
	v_mfma_f32_16x16x32_bf16 v[30:33], v[178:181], v[196:199], v[30:33]
	v_mfma_f32_16x16x32_bf16 v[38:41], v[188:191], v[196:199], v[38:41]
	v_mfma_f32_16x16x32_bf16 v[70:73], v[178:181], v[204:207], v[70:73]
	v_mfma_f32_16x16x32_bf16 v[78:81], v[188:191], v[204:207], v[78:81]
	v_mfma_f32_16x16x32_bf16 v[106:109], v[178:181], v[212:215], v[106:109]
	v_mfma_f32_16x16x32_bf16 v[114:117], v[188:191], v[212:215], v[114:117]
	v_mfma_f32_16x16x32_bf16 v[122:125], v[178:181], v[220:223], v[122:125]
	v_mfma_f32_16x16x32_bf16 v[110:113], v[188:191], v[220:223], v[110:113]
	s_setprio 1
	s_barrier
; #define LDA(dst, b, h) for (int m = 0; m < 4; ++m) for (int k = 0; k < 2; ++k) \
;     dst[m][k] = *reinterpret_cast<const bf16x8*>((char*)SA(b, h) + lds_byte(wr * 64 + m * 16 + fr, k * 32 + fq * 8))
; #define LDB(dst, b, h) for (int n = 0; n < 2; ++n) for (int k = 0; k < 2; ++k) \
;     dst[n][k] = *reinterpret_cast<const bf16x8*>((char*)SB(b, h) + lds_byte(wc * 32 + n * 16 + fr, k * 32 + fq * 8))
; #define MMA(ai, bj, At_, Bt_) do { __builtin_amdgcn_s_setprio(1); \
;     for (int m = 0; m < 4; ++m) for (int n = 0; n < 2; ++n) for (int k = 0; k < 2; ++k) \
;       acc[ai][bj][m][n] = MFMA16(Bt_[n][k], At_[m][k], acc[ai][bj][m][n]); \
;     __builtin_amdgcn_s_setprio(0); } while (0)
; #define WAIT_V(n) asm volatile("s_waitcnt vmcnt(" #n ")" ::: "memory")
; #define WAIT_L(n) asm volatile("s_waitcnt lgkmcnt(" #n ")" ::: "memory")
; #define BAR __builtin_amdgcn_s_barrier()
; #define SCHED __builtin_amdgcn_sched_barrier(0)
; template <int PART  , bool SYNC_FIRST = true>
; __device__ __forceinline__ void kloop_t(const u16* __restrict__ A, int lda, const u16* __restrict__ Bt, int ldb, int K, Acc& acc, const int wv) {
;     ...
;     LDB(B1, 1, 1); STAGE(SB(1, 0), Bt, ldb, 0, t + 3);
;     BAR; WAIT_L(0); MMA(0, 1, At, B1); BAR;
;     LDA(At, 1, 1); STAGE(SA(1, 0), A, lda, 0, t + 3);
;     BAR; WAIT_L(0); MMA(1, 0, At, B0); BAR; SCHED;
;     STAGE(SB(1, 1), Bt, ldb, HALF, t + 3);
;     WAIT_V(6); BAR; MMA(1, 1, At, B1); BAR;
;   }
	v_add_u32_e32 v170, v151, v152
	v_add_u32_e32 v172, v151, v154
	v_mov_b32_e32 v0, v130
	v_mov_b32_e32 v240, v132
	v_add_u32_e32 v171, v151, v153
	ds_read_b128 v[224:227], v170
	ds_read_b128 v[228:231], v171
	v_add_u32_e32 v173, v151, v155
	ds_read_b128 v[232:235], v172
	ds_read_b128 v[236:239], v173
	v_readfirstlane_b32 s12, v133
	v_lshl_add_u64 v[242:243], s[60:61], 0, v[0:1]
	v_mov_b32_e32 v241, v1
	v_lshl_add_u64 v[242:243], v[242:243], 0, s[24:25]
	s_mov_b32 m0, s12
	v_lshl_add_u64 v[240:241], s[60:61], 0, v[240:241]
	v_readfirstlane_b32 s12, v142
	global_load_lds_dwordx4 v[242:243], off
	v_lshl_add_u64 v[240:241], v[240:241], 0, s[24:25]
	s_mov_b32 m0, s12
	s_nop 0
	global_load_lds_dwordx4 v[240:241], off
	s_barrier
	s_waitcnt lgkmcnt(0)
	s_setprio 0
	s_waitcnt lgkmcnt(0)
	v_mfma_f32_16x16x32_bf16 v[42:45], v[224:227], v[192:195], v[42:45]
	v_mfma_f32_16x16x32_bf16 v[46:49], v[232:235], v[192:195], v[46:49]
	v_mfma_f32_16x16x32_bf16 v[82:85], v[224:227], v[200:203], v[82:85]
	v_mfma_f32_16x16x32_bf16 v[90:93], v[232:235], v[200:203], v[90:93]
	v_mfma_f32_16x16x32_bf16 v[118:121], v[224:227], v[208:211], v[118:121]
	v_mfma_f32_16x16x32_bf16 v[126:129], v[232:235], v[208:211], v[126:129]
	v_mfma_f32_16x16x32_bf16 v[102:105], v[224:227], v[216:219], v[102:105]
	v_mfma_f32_16x16x32_bf16 v[98:101], v[232:235], v[216:219], v[98:101]
	v_mfma_f32_16x16x32_bf16 v[42:45], v[228:231], v[196:199], v[42:45]
	v_mfma_f32_16x16x32_bf16 v[46:49], v[236:239], v[196:199], v[46:49]
	v_mfma_f32_16x16x32_bf16 v[82:85], v[228:231], v[204:207], v[82:85]
	v_mfma_f32_16x16x32_bf16 v[90:93], v[236:239], v[204:207], v[90:93]
	v_mfma_f32_16x16x32_bf16 v[118:121], v[228:231], v[212:215], v[118:121]
	v_mfma_f32_16x16x32_bf16 v[126:129], v[236:239], v[212:215], v[126:129]
	v_mfma_f32_16x16x32_bf16 v[102:105], v[228:231], v[220:223], v[102:105]
	v_mfma_f32_16x16x32_bf16 v[98:101], v[236:239], v[220:223], v[98:101]
	s_setprio 1
	v_mov_b32_e32 v0, v130
	v_mov_b32_e32 v240, v132
	s_barrier
	ds_read_b128 v[192:195], v134 offset:49152
	ds_read_b128 v[196:199], v135 offset:49152
	ds_read_b128 v[200:203], v136 offset:49152
	ds_read_b128 v[204:207], v137 offset:49152
	ds_read_b128 v[208:211], v138 offset:49152
	ds_read_b128 v[212:215], v139 offset:49152
	ds_read_b128 v[216:219], v140 offset:49152
	ds_read_b128 v[220:223], v141 offset:49152
	v_readfirstlane_b32 s12, v144
	v_lshl_add_u64 v[242:243], s[62:63], 0, v[0:1]
	v_mov_b32_e32 v241, v1
	v_lshl_add_u64 v[242:243], v[242:243], 0, s[24:25]
	s_mov_b32 m0, s12
	v_lshl_add_u64 v[240:241], s[62:63], 0, v[240:241]
	v_readfirstlane_b32 s12, v145
	global_load_lds_dwordx4 v[242:243], off
	v_lshl_add_u64 v[240:241], v[240:241], 0, s[24:25]
	s_mov_b32 m0, s12
	s_nop 0
	global_load_lds_dwordx4 v[240:241], off
	s_barrier
	s_waitcnt lgkmcnt(0)
	s_setprio 0
	s_waitcnt lgkmcnt(0)
	v_mfma_f32_16x16x32_bf16 v[94:97], v[174:177], v[192:195], v[94:97]
	v_mfma_f32_16x16x32_bf16 v[86:89], v[182:185], v[192:195], v[86:89]
	v_mfma_f32_16x16x32_bf16 v[62:65], v[174:177], v[200:203], v[62:65]
	v_mfma_f32_16x16x32_bf16 v[58:61], v[182:185], v[200:203], v[58:61]
	v_mfma_f32_16x16x32_bf16 v[34:37], v[174:177], v[208:211], v[34:37]
	v_mfma_f32_16x16x32_bf16 v[26:29], v[182:185], v[208:211], v[26:29]
	v_mfma_f32_16x16x32_bf16 v[14:17], v[174:177], v[216:219], v[14:17]
	v_mfma_f32_16x16x32_bf16 v[10:13], v[182:185], v[216:219], v[10:13]
	v_mfma_f32_16x16x32_bf16 v[94:97], v[178:181], v[196:199], v[94:97]
	v_mfma_f32_16x16x32_bf16 v[86:89], v[188:191], v[196:199], v[86:89]
	v_mfma_f32_16x16x32_bf16 v[62:65], v[178:181], v[204:207], v[62:65]
	v_mfma_f32_16x16x32_bf16 v[58:61], v[188:191], v[204:207], v[58:61]
	v_mfma_f32_16x16x32_bf16 v[34:37], v[178:181], v[212:215], v[34:37]
	v_mfma_f32_16x16x32_bf16 v[26:29], v[188:191], v[212:215], v[26:29]
	v_mfma_f32_16x16x32_bf16 v[14:17], v[178:181], v[220:223], v[14:17]
	v_mfma_f32_16x16x32_bf16 v[10:13], v[188:191], v[220:223], v[10:13]
	s_setprio 1
	s_barrier
	v_mov_b32_e32 v0, v130
	v_mov_b32_e32 v174, v132
	v_readfirstlane_b32 s12, v146
	v_lshl_add_u64 v[176:177], s[64:65], 0, v[0:1]
	v_mov_b32_e32 v175, v1
	v_lshl_add_u64 v[176:177], v[176:177], 0, s[24:25]
	s_mov_b32 m0, s12
	v_lshl_add_u64 v[174:175], s[64:65], 0, v[174:175]
	v_readfirstlane_b32 s12, v147
	global_load_lds_dwordx4 v[176:177], off
	v_lshl_add_u64 v[174:175], v[174:175], 0, s[24:25]
	s_mov_b32 m0, s12
	s_nop 0
	global_load_lds_dwordx4 v[174:175], off
	s_waitcnt vmcnt(6)
	s_barrier
	s_setprio 0
	v_mfma_f32_16x16x32_bf16 v[74:77], v[224:227], v[192:195], v[74:77]
	v_mfma_f32_16x16x32_bf16 v[66:69], v[232:235], v[192:195], v[66:69]
	v_mfma_f32_16x16x32_bf16 v[54:57], v[224:227], v[200:203], v[54:57]
	v_mfma_f32_16x16x32_bf16 v[50:53], v[232:235], v[200:203], v[50:53]
	v_mfma_f32_16x16x32_bf16 v[22:25], v[224:227], v[208:211], v[22:25]
	v_mfma_f32_16x16x32_bf16 v[18:21], v[232:235], v[208:211], v[18:21]
	v_mfma_f32_16x16x32_bf16 v[6:9], v[224:227], v[216:219], v[6:9]
	v_mfma_f32_16x16x32_bf16 v[2:5], v[232:235], v[216:219], v[2:5]
	v_mfma_f32_16x16x32_bf16 v[74:77], v[228:231], v[196:199], v[74:77]
	v_mfma_f32_16x16x32_bf16 v[66:69], v[236:239], v[196:199], v[66:69]
	v_mfma_f32_16x16x32_bf16 v[54:57], v[228:231], v[204:207], v[54:57]
	v_mfma_f32_16x16x32_bf16 v[50:53], v[236:239], v[204:207], v[50:53]
	v_mfma_f32_16x16x32_bf16 v[22:25], v[228:231], v[212:215], v[22:25]
	v_mfma_f32_16x16x32_bf16 v[18:21], v[236:239], v[212:215], v[18:21]
	v_mfma_f32_16x16x32_bf16 v[6:9], v[228:231], v[220:223], v[6:9]
	v_mfma_f32_16x16x32_bf16 v[2:5], v[236:239], v[220:223], v[2:5]
	s_setprio 1
	s_add_i32 vcc_hi, vcc_hi, 2
	s_add_u32 s56, s56, 0x100
	s_addc_u32 s57, s57, 0
	s_cmp_lt_u32 vcc_hi, 4
	s_barrier
; #define LDA(dst, b, h) for (int m = 0; m < 4; ++m) for (int k = 0; k < 2; ++k) \
;     dst[m][k] = *reinterpret_cast<const bf16x8*>((char*)SA(b, h) + lds_byte(wr * 64 + m * 16 + fr, k * 32 + fq * 8))
; #define LDB(dst, b, h) for (int n = 0; n < 2; ++n) for (int k = 0; k < 2; ++k) \
;     dst[n][k] = *reinterpret_cast<const bf16x8*>((char*)SB(b, h) + lds_byte(wc * 32 + n * 16 + fr, k * 32 + fq * 8))
; #define MMA(ai, bj, At_, Bt_) do { __builtin_amdgcn_s_setprio(1); \
;     for (int m = 0; m < 4; ++m) for (int n = 0; n < 2; ++n) for (int k = 0; k < 2; ++k) \
;       acc[ai][bj][m][n] = MFMA16(Bt_[n][k], At_[m][k], acc[ai][bj][m][n]); \
;     __builtin_amdgcn_s_setprio(0); } while (0)
; #define WAIT_V(n) asm volatile("s_waitcnt vmcnt(" #n ")" ::: "memory")
; #define WAIT_L(n) asm volatile("s_waitcnt lgkmcnt(" #n ")" ::: "memory")
; #define BAR __builtin_amdgcn_s_barrier()
; template <int PART  , bool SYNC_FIRST = true>
; __device__ __forceinline__ void kloop_t(const u16* __restrict__ A, int lda, const u16* __restrict__ Bt, int ldb, int K, Acc& acc, const int wv) {
;     ...
;   }
;   { LDB(B0, 0, 0); LDA(At, 0, 0); STAGE(SA(1, 1), A, lda, HALF, nt - 1);
;     BAR; WAIT_L(0); MMA(0, 0, At, B0); BAR;
;     LDB(B1, 0, 1); BAR; WAIT_L(0); MMA(0, 1, At, B1); BAR;
;     LDA(At, 0, 1); WAIT_V(4); BAR; WAIT_L(0); MMA(1, 0, At, B0); MMA(1, 1, At, B1); BAR; }
	s_cbranch_scc1 .LBB0_704
	s_add_u32 s0, s0, s6
	ds_read_b128 v[142:145], v156
	ds_read_b128 v[146:149], v157
	ds_read_b128 v[150:153], v158
	ds_read_b128 v[154:157], v159
	ds_read_b128 v[174:177], v134
	ds_read_b128 v[178:181], v135
	ds_read_b128 v[182:185], v136
	ds_read_b128 v[188:191], v137
	ds_read_b128 v[192:195], v138
	ds_read_b128 v[196:199], v139
	ds_read_b128 v[200:203], v140
	ds_read_b128 v[204:207], v141
	s_addc_u32 s1, s1, s7
	v_mov_b32_e32 v131, v1
	v_lshl_add_u64 v[130:131], s[0:1], 0, v[130:131]
	v_readfirstlane_b32 s4, v160
	v_lshl_add_u64 v[130:131], v[130:131], 0, s[26:27]
	s_mov_b32 m0, s4
	v_mov_b32_e32 v133, v1
	global_load_lds_dwordx4 v[130:131], off
	v_lshl_add_u64 v[130:131], s[0:1], 0, v[132:133]
	v_readfirstlane_b32 s0, v161
	v_lshl_add_u64 v[130:131], v[130:131], 0, s[26:27]
	s_mov_b32 m0, s0
	s_nop 0
	global_load_lds_dwordx4 v[130:131], off
	s_barrier
	s_waitcnt lgkmcnt(0)
	s_setprio 0
	s_waitcnt lgkmcnt(0)
	v_mfma_f32_16x16x32_bf16 v[30:33], v[142:145], v[174:177], v[30:33]
	v_mfma_f32_16x16x32_bf16 v[38:41], v[150:153], v[174:177], v[38:41]
	v_mfma_f32_16x16x32_bf16 v[70:73], v[142:145], v[182:185], v[70:73]
	v_mfma_f32_16x16x32_bf16 v[78:81], v[150:153], v[182:185], v[78:81]
	v_mfma_f32_16x16x32_bf16 v[106:109], v[142:145], v[192:195], v[106:109]
	v_mfma_f32_16x16x32_bf16 v[114:117], v[150:153], v[192:195], v[114:117]
	v_mfma_f32_16x16x32_bf16 v[122:125], v[142:145], v[200:203], v[122:125]
	v_mfma_f32_16x16x32_bf16 v[110:113], v[150:153], v[200:203], v[110:113]
	v_mfma_f32_16x16x32_bf16 v[30:33], v[146:149], v[178:181], v[30:33]
	v_mfma_f32_16x16x32_bf16 v[38:41], v[154:157], v[178:181], v[38:41]
	v_mfma_f32_16x16x32_bf16 v[70:73], v[146:149], v[188:191], v[70:73]
	v_mfma_f32_16x16x32_bf16 v[78:81], v[154:157], v[188:191], v[78:81]
	v_mfma_f32_16x16x32_bf16 v[106:109], v[146:149], v[196:199], v[106:109]
	v_mfma_f32_16x16x32_bf16 v[114:117], v[154:157], v[196:199], v[114:117]
	v_mfma_f32_16x16x32_bf16 v[122:125], v[146:149], v[204:207], v[122:125]
	v_mfma_f32_16x16x32_bf16 v[110:113], v[154:157], v[204:207], v[110:113]
	s_setprio 1
	s_barrier
	ds_read_b128 v[130:133], v162
	ds_read_b128 v[158:161], v163
	ds_read_b128 v[208:211], v164
	ds_read_b128 v[162:165], v165
	s_barrier
	s_waitcnt lgkmcnt(0)
	s_setprio 0
	s_waitcnt lgkmcnt(0)
	v_mfma_f32_16x16x32_bf16 v[42:45], v[130:133], v[174:177], v[42:45]
	v_mfma_f32_16x16x32_bf16 v[46:49], v[208:211], v[174:177], v[46:49]
	v_mfma_f32_16x16x32_bf16 v[82:85], v[130:133], v[182:185], v[82:85]
	v_mfma_f32_16x16x32_bf16 v[90:93], v[208:211], v[182:185], v[90:93]
	v_mfma_f32_16x16x32_bf16 v[118:121], v[130:133], v[192:195], v[118:121]
	v_mfma_f32_16x16x32_bf16 v[126:129], v[208:211], v[192:195], v[126:129]
	v_mfma_f32_16x16x32_bf16 v[102:105], v[130:133], v[200:203], v[102:105]
	v_mfma_f32_16x16x32_bf16 v[98:101], v[208:211], v[200:203], v[98:101]
	v_mfma_f32_16x16x32_bf16 v[42:45], v[158:161], v[178:181], v[42:45]
	v_mfma_f32_16x16x32_bf16 v[46:49], v[162:165], v[178:181], v[46:49]
	v_mfma_f32_16x16x32_bf16 v[82:85], v[158:161], v[188:191], v[82:85]
	v_mfma_f32_16x16x32_bf16 v[90:93], v[162:165], v[188:191], v[90:93]
	v_mfma_f32_16x16x32_bf16 v[118:121], v[158:161], v[196:199], v[118:121]
	v_mfma_f32_16x16x32_bf16 v[126:129], v[162:165], v[196:199], v[126:129]
	v_mfma_f32_16x16x32_bf16 v[102:105], v[158:161], v[204:207], v[102:105]
	v_mfma_f32_16x16x32_bf16 v[98:101], v[162:165], v[204:207], v[98:101]
	s_setprio 1
	s_barrier
	ds_read_b128 v[174:177], v134 offset:16384
	ds_read_b128 v[178:181], v135 offset:16384
	ds_read_b128 v[182:185], v136 offset:16384
	ds_read_b128 v[188:191], v137 offset:16384
	ds_read_b128 v[192:195], v138 offset:16384
	ds_read_b128 v[196:199], v139 offset:16384
	ds_read_b128 v[200:203], v140 offset:16384
	ds_read_b128 v[204:207], v141 offset:16384
	s_waitcnt vmcnt(4)
	s_barrier
	s_waitcnt lgkmcnt(0)
	s_setprio 0
	s_waitcnt lgkmcnt(0)
	v_mfma_f32_16x16x32_bf16 v[94:97], v[142:145], v[174:177], v[94:97]
	v_mfma_f32_16x16x32_bf16 v[86:89], v[150:153], v[174:177], v[86:89]
	v_mfma_f32_16x16x32_bf16 v[62:65], v[142:145], v[182:185], v[62:65]
	v_mfma_f32_16x16x32_bf16 v[58:61], v[150:153], v[182:185], v[58:61]
	v_mfma_f32_16x16x32_bf16 v[34:37], v[142:145], v[192:195], v[34:37]
	v_mfma_f32_16x16x32_bf16 v[26:29], v[150:153], v[192:195], v[26:29]
	v_mfma_f32_16x16x32_bf16 v[14:17], v[142:145], v[200:203], v[14:17]
	v_mfma_f32_16x16x32_bf16 v[10:13], v[150:153], v[200:203], v[10:13]
	v_mfma_f32_16x16x32_bf16 v[94:97], v[146:149], v[178:181], v[94:97]
	v_mfma_f32_16x16x32_bf16 v[86:89], v[154:157], v[178:181], v[86:89]
	v_mfma_f32_16x16x32_bf16 v[62:65], v[146:149], v[188:191], v[62:65]
	v_mfma_f32_16x16x32_bf16 v[58:61], v[154:157], v[188:191], v[58:61]
	v_mfma_f32_16x16x32_bf16 v[34:37], v[146:149], v[196:199], v[34:37]
	v_mfma_f32_16x16x32_bf16 v[26:29], v[154:157], v[196:199], v[26:29]
	v_mfma_f32_16x16x32_bf16 v[14:17], v[146:149], v[204:207], v[14:17]
	v_mfma_f32_16x16x32_bf16 v[10:13], v[154:157], v[204:207], v[10:13]
	s_setprio 1
	s_setprio 0
	v_mfma_f32_16x16x32_bf16 v[74:77], v[130:133], v[174:177], v[74:77]
	v_mfma_f32_16x16x32_bf16 v[66:69], v[208:211], v[174:177], v[66:69]
	v_mfma_f32_16x16x32_bf16 v[54:57], v[130:133], v[182:185], v[54:57]
	v_mfma_f32_16x16x32_bf16 v[50:53], v[208:211], v[182:185], v[50:53]
	v_mfma_f32_16x16x32_bf16 v[22:25], v[130:133], v[192:195], v[22:25]
	v_mfma_f32_16x16x32_bf16 v[18:21], v[208:211], v[192:195], v[18:21]
	v_mfma_f32_16x16x32_bf16 v[6:9], v[130:133], v[200:203], v[6:9]
	v_mfma_f32_16x16x32_bf16 v[2:5], v[208:211], v[200:203], v[2:5]
	v_mfma_f32_16x16x32_bf16 v[74:77], v[158:161], v[178:181], v[74:77]
	v_mfma_f32_16x16x32_bf16 v[66:69], v[162:165], v[178:181], v[66:69]
	v_mfma_f32_16x16x32_bf16 v[54:57], v[158:161], v[188:191], v[54:57]
	v_mfma_f32_16x16x32_bf16 v[50:53], v[162:165], v[188:191], v[50:53]
	v_mfma_f32_16x16x32_bf16 v[22:25], v[158:161], v[196:199], v[22:25]
	v_mfma_f32_16x16x32_bf16 v[18:21], v[162:165], v[196:199], v[18:21]
	v_mfma_f32_16x16x32_bf16 v[6:9], v[158:161], v[204:207], v[6:9]
	v_mfma_f32_16x16x32_bf16 v[2:5], v[162:165], v[204:207], v[2:5]
	s_setprio 1
	s_barrier
; #define LDA(dst, b, h) for (int m = 0; m < 4; ++m) for (int k = 0; k < 2; ++k) \
;     dst[m][k] = *reinterpret_cast<const bf16x8*>((char*)SA(b, h) + lds_byte(wr * 64 + m * 16 + fr, k * 32 + fq * 8))
; #define LDB(dst, b, h) for (int n = 0; n < 2; ++n) for (int k = 0; k < 2; ++k) \
;     dst[n][k] = *reinterpret_cast<const bf16x8*>((char*)SB(b, h) + lds_byte(wc * 32 + n * 16 + fr, k * 32 + fq * 8))
; #define MMA(ai, bj, At_, Bt_) do { __builtin_amdgcn_s_setprio(1); \
;     for (int m = 0; m < 4; ++m) for (int n = 0; n < 2; ++n) for (int k = 0; k < 2; ++k) \
;       acc[ai][bj][m][n] = MFMA16(Bt_[n][k], At_[m][k], acc[ai][bj][m][n]); \
;     __builtin_amdgcn_s_setprio(0); } while (0)
; #define WAIT_V(n) asm volatile("s_waitcnt vmcnt(" #n ")" ::: "memory")
; #define WAIT_L(n) asm volatile("s_waitcnt lgkmcnt(" #n ")" ::: "memory")
; #define BAR __builtin_amdgcn_s_barrier()
; template <int PART  , bool SYNC_FIRST = true>
; __device__ __forceinline__ void kloop_t(const u16* __restrict__ A, int lda, const u16* __restrict__ Bt, int ldb, int K, Acc& acc, const int wv) {
;     ...
;   { LDB(B0, 1, 0); LDA(At, 1, 0); WAIT_V(2); BAR; WAIT_L(0); MMA(0, 0, At, B0); BAR;
;     LDB(B1, 1, 1); WAIT_V(0); BAR; WAIT_L(0); MMA(0, 1, At, B1); BAR;
;     LDA(At, 1, 1); BAR; WAIT_L(0); MMA(1, 0, At, B0); MMA(1, 1, At, B1); BAR; }
;   if (wr == 0) BAR;
	ds_read_b128 v[130:133], v166
	ds_read_b128 v[142:145], v167
	ds_read_b128 v[146:149], v168
	ds_read_b128 v[150:153], v169
	ds_read_b128 v[154:157], v134 offset:32768
	ds_read_b128 v[158:161], v135 offset:32768
	ds_read_b128 v[162:165], v136 offset:32768
	ds_read_b128 v[166:169], v137 offset:32768
	ds_read_b128 v[174:177], v138 offset:32768
	ds_read_b128 v[178:181], v139 offset:32768
	ds_read_b128 v[182:185], v140 offset:32768
	ds_read_b128 v[188:191], v141 offset:32768
	s_waitcnt vmcnt(2)
	s_barrier
	s_waitcnt lgkmcnt(0)
	s_setprio 0
	s_waitcnt lgkmcnt(0)
	v_mfma_f32_16x16x32_bf16 v[30:33], v[130:133], v[154:157], v[30:33]
	v_mfma_f32_16x16x32_bf16 v[38:41], v[146:149], v[154:157], v[38:41]
	v_mfma_f32_16x16x32_bf16 v[70:73], v[130:133], v[162:165], v[70:73]
	v_mfma_f32_16x16x32_bf16 v[78:81], v[146:149], v[162:165], v[78:81]
	v_mfma_f32_16x16x32_bf16 v[106:109], v[130:133], v[174:177], v[106:109]
	v_mfma_f32_16x16x32_bf16 v[114:117], v[146:149], v[174:177], v[114:117]
	v_mfma_f32_16x16x32_bf16 v[122:125], v[130:133], v[182:185], v[122:125]
	v_mfma_f32_16x16x32_bf16 v[110:113], v[146:149], v[182:185], v[110:113]
	v_mfma_f32_16x16x32_bf16 v[30:33], v[142:145], v[158:161], v[30:33]
	v_mfma_f32_16x16x32_bf16 v[38:41], v[150:153], v[158:161], v[38:41]
	v_mfma_f32_16x16x32_bf16 v[70:73], v[142:145], v[166:169], v[70:73]
	v_mfma_f32_16x16x32_bf16 v[78:81], v[150:153], v[166:169], v[78:81]
	v_mfma_f32_16x16x32_bf16 v[106:109], v[142:145], v[178:181], v[106:109]
	v_mfma_f32_16x16x32_bf16 v[114:117], v[150:153], v[178:181], v[114:117]
	v_mfma_f32_16x16x32_bf16 v[122:125], v[142:145], v[188:191], v[122:125]
	v_mfma_f32_16x16x32_bf16 v[110:113], v[150:153], v[188:191], v[110:113]
	s_setprio 1
	s_barrier
	ds_read_b128 v[192:195], v170
	ds_read_b128 v[196:199], v171
	ds_read_b128 v[200:203], v172
	ds_read_b128 v[170:173], v173
	s_waitcnt vmcnt(0)
	s_barrier
	s_waitcnt lgkmcnt(0)
	s_setprio 0
	s_waitcnt lgkmcnt(0)
	v_mfma_f32_16x16x32_bf16 v[42:45], v[192:195], v[154:157], v[42:45]
	v_mfma_f32_16x16x32_bf16 v[46:49], v[200:203], v[154:157], v[46:49]
	v_mfma_f32_16x16x32_bf16 v[82:85], v[192:195], v[162:165], v[82:85]
	v_mfma_f32_16x16x32_bf16 v[90:93], v[200:203], v[162:165], v[90:93]
	v_mfma_f32_16x16x32_bf16 v[118:121], v[192:195], v[174:177], v[118:121]
	v_mfma_f32_16x16x32_bf16 v[126:129], v[200:203], v[174:177], v[126:129]
	v_mfma_f32_16x16x32_bf16 v[102:105], v[192:195], v[182:185], v[102:105]
	v_mfma_f32_16x16x32_bf16 v[98:101], v[200:203], v[182:185], v[98:101]
	v_mfma_f32_16x16x32_bf16 v[42:45], v[196:199], v[158:161], v[42:45]
	v_mfma_f32_16x16x32_bf16 v[46:49], v[170:173], v[158:161], v[46:49]
	v_mfma_f32_16x16x32_bf16 v[82:85], v[196:199], v[166:169], v[82:85]
	v_mfma_f32_16x16x32_bf16 v[90:93], v[170:173], v[166:169], v[90:93]
	v_mfma_f32_16x16x32_bf16 v[118:121], v[196:199], v[178:181], v[118:121]
	v_mfma_f32_16x16x32_bf16 v[126:129], v[170:173], v[178:181], v[126:129]
	v_mfma_f32_16x16x32_bf16 v[102:105], v[196:199], v[188:191], v[102:105]
	v_mfma_f32_16x16x32_bf16 v[98:101], v[170:173], v[188:191], v[98:101]
	s_setprio 1
	s_barrier
	ds_read_b128 v[154:157], v134 offset:49152
	ds_read_b128 v[158:161], v135 offset:49152
	ds_read_b128 v[162:165], v136 offset:49152
	ds_read_b128 v[134:137], v137 offset:49152
	ds_read_b128 v[166:169], v138 offset:49152
	ds_read_b128 v[174:177], v139 offset:49152
	ds_read_b128 v[178:181], v140 offset:49152
	ds_read_b128 v[138:141], v141 offset:49152
	s_barrier
	s_waitcnt lgkmcnt(0)
	s_setprio 0
	s_waitcnt lgkmcnt(0)
	v_mfma_f32_16x16x32_bf16 v[94:97], v[130:133], v[154:157], v[94:97]
	v_mfma_f32_16x16x32_bf16 v[86:89], v[146:149], v[154:157], v[86:89]
	v_mfma_f32_16x16x32_bf16 v[62:65], v[130:133], v[162:165], v[62:65]
	v_mfma_f32_16x16x32_bf16 v[58:61], v[146:149], v[162:165], v[58:61]
	v_mfma_f32_16x16x32_bf16 v[34:37], v[130:133], v[166:169], v[34:37]
	v_mfma_f32_16x16x32_bf16 v[26:29], v[146:149], v[166:169], v[26:29]
	v_mfma_f32_16x16x32_bf16 v[14:17], v[130:133], v[178:181], v[14:17]
	v_mfma_f32_16x16x32_bf16 v[10:13], v[146:149], v[178:181], v[10:13]
	v_mfma_f32_16x16x32_bf16 v[94:97], v[142:145], v[158:161], v[94:97]
	v_mfma_f32_16x16x32_bf16 v[86:89], v[150:153], v[158:161], v[86:89]
	v_mfma_f32_16x16x32_bf16 v[62:65], v[142:145], v[134:137], v[62:65]
	v_mfma_f32_16x16x32_bf16 v[58:61], v[150:153], v[134:137], v[58:61]
	v_mfma_f32_16x16x32_bf16 v[34:37], v[142:145], v[174:177], v[34:37]
	v_mfma_f32_16x16x32_bf16 v[26:29], v[150:153], v[174:177], v[26:29]
	v_mfma_f32_16x16x32_bf16 v[14:17], v[142:145], v[138:141], v[14:17]
	v_mfma_f32_16x16x32_bf16 v[10:13], v[150:153], v[138:141], v[10:13]
	s_setprio 1
	s_setprio 0
	v_mfma_f32_16x16x32_bf16 v[74:77], v[192:195], v[154:157], v[74:77]
	v_mfma_f32_16x16x32_bf16 v[66:69], v[200:203], v[154:157], v[66:69]
	v_mfma_f32_16x16x32_bf16 v[54:57], v[192:195], v[162:165], v[54:57]
	v_mfma_f32_16x16x32_bf16 v[50:53], v[200:203], v[162:165], v[50:53]
	v_mfma_f32_16x16x32_bf16 v[22:25], v[192:195], v[166:169], v[22:25]
	v_mfma_f32_16x16x32_bf16 v[18:21], v[200:203], v[166:169], v[18:21]
	v_mfma_f32_16x16x32_bf16 v[6:9], v[192:195], v[178:181], v[6:9]
	v_mfma_f32_16x16x32_bf16 v[2:5], v[200:203], v[178:181], v[2:5]
	v_mfma_f32_16x16x32_bf16 v[74:77], v[196:199], v[158:161], v[74:77]
	v_mfma_f32_16x16x32_bf16 v[66:69], v[170:173], v[158:161], v[66:69]
	v_mfma_f32_16x16x32_bf16 v[54:57], v[196:199], v[134:137], v[54:57]
	v_mfma_f32_16x16x32_bf16 v[50:53], v[170:173], v[134:137], v[50:53]
	v_mfma_f32_16x16x32_bf16 v[22:25], v[196:199], v[174:177], v[22:25]
	v_mfma_f32_16x16x32_bf16 v[18:21], v[170:173], v[174:177], v[18:21]
	v_mfma_f32_16x16x32_bf16 v[6:9], v[196:199], v[138:141], v[6:9]
	v_mfma_f32_16x16x32_bf16 v[2:5], v[170:173], v[138:141], v[2:5]
	s_setprio 1
	s_andn2_b64 vcc, exec, s[16:17]
	s_barrier
	s_cbranch_vccnz .LBB0_707
	s_barrier

; #define LDA(dst, b, h) for (int m = 0; m < 4; ++m) for (int k = 0; k < 2; ++k) \
;     dst[m][k] = *reinterpret_cast<const bf16x8*>((char*)SA(b, h) + lds_byte(wr * 64 + m * 16 + fr, k * 32 + fq * 8))
; #define LDB(dst, b, h) for (int n = 0; n < 2; ++n) for (int k = 0; k < 2; ++k) \
;     dst[n][k] = *reinterpret_cast<const bf16x8*>((char*)SB(b, h) + lds_byte(wc * 32 + n * 16 + fr, k * 32 + fq * 8))
; #define MMA(ai, bj, At_, Bt_) do { __builtin_amdgcn_s_setprio(1); \
;     for (int m = 0; m < 4; ++m) for (int n = 0; n < 2; ++n) for (int k = 0; k < 2; ++k) \
;       acc[ai][bj][m][n] = MFMA16(Bt_[n][k], At_[m][k], acc[ai][bj][m][n]); \
;     __builtin_amdgcn_s_setprio(0); } while (0)
; #define WAIT_L(n) asm volatile("s_waitcnt lgkmcnt(" #n ")" ::: "memory")
; #define BAR __builtin_amdgcn_s_barrier()
; #define SCHED __builtin_amdgcn_sched_barrier(0)
; template <int PART  , bool SYNC_FIRST = true>
; __device__ __forceinline__ void kloop_t(const u16* __restrict__ A, int lda, const u16* __restrict__ Bt, int ldb, int K, Acc& acc, const int wv) {
;     ...
;     LDB(B0, 0, 0); SCHED; LDA(At, 0, 0); STAGE(SA(1, 1), A, lda, HALF, t + 1);
;     WAIT_L(8); BAR; WAIT_L(0); MMA(0, 0, At, B0); BAR; SCHED;
;     LDB(B1, 0, 1); STAGE(SB(0, 0), Bt, ldb, 0, t + 2);
;     BAR; WAIT_L(0); MMA(0, 1, At, B1); BAR;
;     LDA(At, 0, 1); STAGE(SA(0, 0), A, lda, 0, t + 2);
.LBB0_980:
	v_add_u32_e32 v163, v155, v159
	v_add_u32_e32 v165, v155, v161
	v_add_u32_e32 v164, v155, v160
	ds_read_b128 v[174:177], v163
	ds_read_b128 v[178:181], v164
	v_add_u32_e32 v166, v155, v162
	ds_read_b128 v[182:185], v165
	ds_read_b128 v[186:189], v166
	s_add_u32 s36, s34, s72
	v_mov_b32_e32 v128, v130
	v_mov_b32_e32 v168, v131
	s_addc_u32 s37, s35, 0
	v_add_u32_e32 v167, 0xc000, v143
	ds_read_b128 v[190:193], v132
	ds_read_b128 v[194:197], v133
	ds_read_b128 v[198:201], v135
	ds_read_b128 v[202:205], v136
	ds_read_b128 v[206:209], v137
	ds_read_b128 v[210:213], v138
	ds_read_b128 v[214:217], v139
	ds_read_b128 v[218:221], v140
	v_readfirstlane_b32 s38, v167
	v_lshl_add_u64 v[170:171], s[36:37], 0, v[128:129]
	v_mov_b32_e32 v169, v129
	v_lshl_add_u64 v[170:171], v[170:171], 0, s[14:15]
	s_mov_b32 m0, s38
	v_lshl_add_u64 v[168:169], s[36:37], 0, v[168:169]
	global_load_lds_dwordx4 v[170:171], off
	v_lshl_add_u64 v[170:171], v[168:169], 0, s[14:15]
	v_add_u32_e32 v168, 0xe000, v143
	s_nop 0
	v_readfirstlane_b32 s38, v168
	s_mov_b32 m0, s38
	s_nop 0
	global_load_lds_dwordx4 v[170:171], off
	s_waitcnt lgkmcnt(8)
	s_barrier
	s_waitcnt lgkmcnt(0)
	s_setprio 0
	s_waitcnt lgkmcnt(0)
	v_mfma_f32_16x16x32_bf16 v[124:127], v[174:177], v[190:193], v[124:127]
	v_mfma_f32_16x16x32_bf16 v[120:123], v[182:185], v[190:193], v[120:123]
	v_mfma_f32_16x16x32_bf16 v[116:119], v[174:177], v[198:201], v[116:119]
	v_mfma_f32_16x16x32_bf16 v[112:115], v[182:185], v[198:201], v[112:115]
	v_mfma_f32_16x16x32_bf16 v[108:111], v[174:177], v[206:209], v[108:111]
	v_mfma_f32_16x16x32_bf16 v[104:107], v[182:185], v[206:209], v[104:107]
	v_mfma_f32_16x16x32_bf16 v[100:103], v[174:177], v[214:217], v[100:103]
	v_mfma_f32_16x16x32_bf16 v[96:99], v[182:185], v[214:217], v[96:99]
	v_mfma_f32_16x16x32_bf16 v[124:127], v[178:181], v[194:197], v[124:127]
	v_mfma_f32_16x16x32_bf16 v[120:123], v[186:189], v[194:197], v[120:123]
	v_mfma_f32_16x16x32_bf16 v[116:119], v[178:181], v[202:205], v[116:119]
	v_mfma_f32_16x16x32_bf16 v[112:115], v[186:189], v[202:205], v[112:115]
	v_mfma_f32_16x16x32_bf16 v[108:111], v[178:181], v[210:213], v[108:111]
	v_mfma_f32_16x16x32_bf16 v[104:107], v[186:189], v[210:213], v[104:107]
	v_mfma_f32_16x16x32_bf16 v[100:103], v[178:181], v[218:221], v[100:103]
	v_mfma_f32_16x16x32_bf16 v[96:99], v[186:189], v[218:221], v[96:99]
	s_setprio 1
	s_barrier
	s_add_u32 s38, s34, s73
	v_add_u32_e32 v169, v156, v159
	v_add_u32_e32 v171, v156, v161
	v_mov_b32_e32 v128, v130
	v_mov_b32_e32 v238, v131
	s_addc_u32 s39, s35, 0
	v_add_u32_e32 v170, v156, v160
	ds_read_b128 v[222:225], v169
	ds_read_b128 v[226:229], v170
	v_add_u32_e32 v172, v156, v162
	ds_read_b128 v[230:233], v171
	ds_read_b128 v[234:237], v172
	v_readfirstlane_b32 s75, v141
	v_lshl_add_u64 v[240:241], s[38:39], 0, v[128:129]
	v_mov_b32_e32 v239, v129
	v_lshl_add_u64 v[240:241], v[240:241], 0, s[16:17]
	s_mov_b32 m0, s75
	v_lshl_add_u64 v[238:239], s[38:39], 0, v[238:239]
	v_readfirstlane_b32 s75, v142
	global_load_lds_dwordx4 v[240:241], off
	v_lshl_add_u64 v[238:239], v[238:239], 0, s[16:17]
	s_mov_b32 m0, s75
	s_nop 0
	global_load_lds_dwordx4 v[238:239], off
	s_barrier
	s_waitcnt lgkmcnt(0)
	s_setprio 0
	s_waitcnt lgkmcnt(0)
	v_mfma_f32_16x16x32_bf16 v[92:95], v[222:225], v[190:193], v[92:95]
	v_mfma_f32_16x16x32_bf16 v[88:91], v[230:233], v[190:193], v[88:91]
	v_mfma_f32_16x16x32_bf16 v[84:87], v[222:225], v[198:201], v[84:87]
	v_mfma_f32_16x16x32_bf16 v[80:83], v[230:233], v[198:201], v[80:83]
	v_mfma_f32_16x16x32_bf16 v[76:79], v[222:225], v[206:209], v[76:79]
	v_mfma_f32_16x16x32_bf16 v[72:75], v[230:233], v[206:209], v[72:75]
	v_mfma_f32_16x16x32_bf16 v[68:71], v[222:225], v[214:217], v[68:71]
	v_mfma_f32_16x16x32_bf16 v[64:67], v[230:233], v[214:217], v[64:67]
	v_mfma_f32_16x16x32_bf16 v[92:95], v[226:229], v[194:197], v[92:95]
	v_mfma_f32_16x16x32_bf16 v[88:91], v[234:237], v[194:197], v[88:91]
	v_mfma_f32_16x16x32_bf16 v[84:87], v[226:229], v[202:205], v[84:87]
	v_mfma_f32_16x16x32_bf16 v[80:83], v[234:237], v[202:205], v[80:83]
	v_mfma_f32_16x16x32_bf16 v[76:79], v[226:229], v[210:213], v[76:79]
	v_mfma_f32_16x16x32_bf16 v[72:75], v[234:237], v[210:213], v[72:75]
	v_mfma_f32_16x16x32_bf16 v[68:71], v[226:229], v[218:221], v[68:71]
	v_mfma_f32_16x16x32_bf16 v[64:67], v[234:237], v[218:221], v[64:67]
	s_setprio 1
	v_mov_b32_e32 v128, v130
	v_mov_b32_e32 v238, v131
	s_barrier
	ds_read_b128 v[190:193], v132 offset:16384
	ds_read_b128 v[194:197], v133 offset:16384
	ds_read_b128 v[198:201], v135 offset:16384
	ds_read_b128 v[202:205], v136 offset:16384
	ds_read_b128 v[206:209], v137 offset:16384
	ds_read_b128 v[210:213], v138 offset:16384
	ds_read_b128 v[214:217], v139 offset:16384
	ds_read_b128 v[218:221], v140 offset:16384
	v_readfirstlane_b32 s75, v143
	v_lshl_add_u64 v[240:241], s[36:37], 0, v[128:129]
	v_mov_b32_e32 v239, v129
	v_lshl_add_u64 v[240:241], v[240:241], 0, s[18:19]
	s_mov_b32 m0, s75
	v_lshl_add_u64 v[238:239], s[36:37], 0, v[238:239]
	v_readfirstlane_b32 s75, v144
	global_load_lds_dwordx4 v[240:241], off
	v_lshl_add_u64 v[238:239], v[238:239], 0, s[18:19]
	s_mov_b32 m0, s75
	s_nop 0
	global_load_lds_dwordx4 v[238:239], off
	s_barrier
; #define LDA(dst, b, h) for (int m = 0; m < 4; ++m) for (int k = 0; k < 2; ++k) \
;     dst[m][k] = *reinterpret_cast<const bf16x8*>((char*)SA(b, h) + lds_byte(wr * 64 + m * 16 + fr, k * 32 + fq * 8))
; #define LDB(dst, b, h) for (int n = 0; n < 2; ++n) for (int k = 0; k < 2; ++k) \
;     dst[n][k] = *reinterpret_cast<const bf16x8*>((char*)SB(b, h) + lds_byte(wc * 32 + n * 16 + fr, k * 32 + fq * 8))
; #define MMA(ai, bj, At_, Bt_) do { __builtin_amdgcn_s_setprio(1); \
;     for (int m = 0; m < 4; ++m) for (int n = 0; n < 2; ++n) for (int k = 0; k < 2; ++k) \
;       acc[ai][bj][m][n] = MFMA16(Bt_[n][k], At_[m][k], acc[ai][bj][m][n]); \
;     __builtin_amdgcn_s_setprio(0); } while (0)
; #define WAIT_V(n) asm volatile("s_waitcnt vmcnt(" #n ")" ::: "memory")
; #define WAIT_L(n) asm volatile("s_waitcnt lgkmcnt(" #n ")" ::: "memory")
; #define BAR __builtin_amdgcn_s_barrier()
; #define SCHED __builtin_amdgcn_sched_barrier(0)
; template <int PART  , bool SYNC_FIRST = true>
; __device__ __forceinline__ void kloop_t(const u16* __restrict__ A, int lda, const u16* __restrict__ Bt, int ldb, int K, Acc& acc, const int wv) {
;     ...
;     BAR; WAIT_L(0); MMA(1, 0, At, B0); BAR; SCHED;
;     STAGE(SB(0, 1), Bt, ldb, HALF, t + 2);
;     WAIT_V(6); BAR; MMA(1, 1, At, B1); BAR;
;     LDB(B0, 1, 0); SCHED; LDA(At, 1, 0); STAGE(SA(0, 1), A, lda, HALF, t + 2);
;     WAIT_L(8); BAR; WAIT_L(0); MMA(0, 0, At, B0); BAR; SCHED;
;     LDB(B1, 1, 1); STAGE(SB(1, 0), Bt, ldb, 0, t + 3);
	s_waitcnt lgkmcnt(0)
	s_setprio 0
	s_waitcnt lgkmcnt(0)
	v_mfma_f32_16x16x32_bf16 v[60:63], v[174:177], v[190:193], v[60:63]
	v_mfma_f32_16x16x32_bf16 v[56:59], v[182:185], v[190:193], v[56:59]
	v_mfma_f32_16x16x32_bf16 v[52:55], v[174:177], v[198:201], v[52:55]
	v_mfma_f32_16x16x32_bf16 v[48:51], v[182:185], v[198:201], v[48:51]
	v_mfma_f32_16x16x32_bf16 v[44:47], v[174:177], v[206:209], v[44:47]
	v_mfma_f32_16x16x32_bf16 v[40:43], v[182:185], v[206:209], v[40:43]
	v_mfma_f32_16x16x32_bf16 v[36:39], v[174:177], v[214:217], v[36:39]
	v_mfma_f32_16x16x32_bf16 v[32:35], v[182:185], v[214:217], v[32:35]
	v_mfma_f32_16x16x32_bf16 v[60:63], v[178:181], v[194:197], v[60:63]
	v_mfma_f32_16x16x32_bf16 v[56:59], v[186:189], v[194:197], v[56:59]
	v_mfma_f32_16x16x32_bf16 v[52:55], v[178:181], v[202:205], v[52:55]
	v_mfma_f32_16x16x32_bf16 v[48:51], v[186:189], v[202:205], v[48:51]
	v_mfma_f32_16x16x32_bf16 v[44:47], v[178:181], v[210:213], v[44:47]
	v_mfma_f32_16x16x32_bf16 v[40:43], v[186:189], v[210:213], v[40:43]
	v_mfma_f32_16x16x32_bf16 v[36:39], v[178:181], v[218:221], v[36:39]
	v_mfma_f32_16x16x32_bf16 v[32:35], v[186:189], v[218:221], v[32:35]
	s_setprio 1
	s_barrier
	v_mov_b32_e32 v128, v130
	v_mov_b32_e32 v174, v131
	v_readfirstlane_b32 s75, v145
	v_lshl_add_u64 v[176:177], s[38:39], 0, v[128:129]
	v_mov_b32_e32 v175, v129
	v_lshl_add_u64 v[176:177], v[176:177], 0, s[20:21]
	s_mov_b32 m0, s75
	v_lshl_add_u64 v[174:175], s[38:39], 0, v[174:175]
	v_readfirstlane_b32 s75, v146
	global_load_lds_dwordx4 v[176:177], off
	v_lshl_add_u64 v[174:175], v[174:175], 0, s[20:21]
	s_mov_b32 m0, s75
	s_nop 0
	global_load_lds_dwordx4 v[174:175], off
	s_waitcnt vmcnt(6)
	s_barrier
	s_setprio 0
	v_mfma_f32_16x16x32_bf16 v[28:31], v[222:225], v[190:193], v[28:31]
	v_mfma_f32_16x16x32_bf16 v[24:27], v[230:233], v[190:193], v[24:27]
	v_mfma_f32_16x16x32_bf16 v[20:23], v[222:225], v[198:201], v[20:23]
	v_mfma_f32_16x16x32_bf16 v[16:19], v[230:233], v[198:201], v[16:19]
	v_mfma_f32_16x16x32_bf16 v[12:15], v[222:225], v[206:209], v[12:15]
	v_mfma_f32_16x16x32_bf16 v[8:11], v[230:233], v[206:209], v[8:11]
	v_mfma_f32_16x16x32_bf16 v[4:7], v[222:225], v[214:217], v[4:7]
	v_mfma_f32_16x16x32_bf16 v[0:3], v[230:233], v[214:217], v[0:3]
	v_mfma_f32_16x16x32_bf16 v[28:31], v[226:229], v[194:197], v[28:31]
	v_mfma_f32_16x16x32_bf16 v[24:27], v[234:237], v[194:197], v[24:27]
	v_mfma_f32_16x16x32_bf16 v[20:23], v[226:229], v[202:205], v[20:23]
	v_mfma_f32_16x16x32_bf16 v[16:19], v[234:237], v[202:205], v[16:19]
	v_mfma_f32_16x16x32_bf16 v[12:15], v[226:229], v[210:213], v[12:15]
	v_mfma_f32_16x16x32_bf16 v[8:11], v[234:237], v[210:213], v[8:11]
	v_mfma_f32_16x16x32_bf16 v[4:7], v[226:229], v[218:221], v[4:7]
	v_mfma_f32_16x16x32_bf16 v[0:3], v[234:237], v[218:221], v[0:3]
	s_setprio 1
	v_add_u32_e32 v173, v157, v159
	v_add_u32_e32 v175, v157, v161
	s_barrier
	v_add_u32_e32 v174, v157, v160
	ds_read_b128 v[182:185], v173
	ds_read_b128 v[186:189], v174
	v_add_u32_e32 v176, v157, v162
	ds_read_b128 v[190:193], v175
	ds_read_b128 v[194:197], v176
	v_mov_b32_e32 v128, v130
	v_mov_b32_e32 v178, v131
	ds_read_b128 v[198:201], v132 offset:32768
	ds_read_b128 v[202:205], v133 offset:32768
	ds_read_b128 v[206:209], v135 offset:32768
	ds_read_b128 v[210:213], v136 offset:32768
	ds_read_b128 v[214:217], v137 offset:32768
	ds_read_b128 v[218:221], v138 offset:32768
	ds_read_b128 v[222:225], v139 offset:32768
	ds_read_b128 v[226:229], v140 offset:32768
	v_readfirstlane_b32 s75, v147
	v_lshl_add_u64 v[180:181], s[36:37], 0, v[128:129]
	v_mov_b32_e32 v179, v129
	v_lshl_add_u64 v[180:181], v[180:181], 0, s[22:23]
	s_mov_b32 m0, s75
	v_lshl_add_u64 v[178:179], s[36:37], 0, v[178:179]
	v_readfirstlane_b32 s75, v148
	global_load_lds_dwordx4 v[180:181], off
	v_lshl_add_u64 v[178:179], v[178:179], 0, s[22:23]
	s_mov_b32 m0, s75
	s_nop 0
	global_load_lds_dwordx4 v[178:179], off
	s_waitcnt lgkmcnt(8)
	s_barrier
	s_waitcnt lgkmcnt(0)
	s_setprio 0
	s_waitcnt lgkmcnt(0)
	v_mfma_f32_16x16x32_bf16 v[124:127], v[182:185], v[198:201], v[124:127]
	v_mfma_f32_16x16x32_bf16 v[120:123], v[190:193], v[198:201], v[120:123]
	v_mfma_f32_16x16x32_bf16 v[116:119], v[182:185], v[206:209], v[116:119]
	v_mfma_f32_16x16x32_bf16 v[112:115], v[190:193], v[206:209], v[112:115]
	v_mfma_f32_16x16x32_bf16 v[108:111], v[182:185], v[214:217], v[108:111]
	v_mfma_f32_16x16x32_bf16 v[104:107], v[190:193], v[214:217], v[104:107]
	v_mfma_f32_16x16x32_bf16 v[100:103], v[182:185], v[222:225], v[100:103]
	v_mfma_f32_16x16x32_bf16 v[96:99], v[190:193], v[222:225], v[96:99]
	v_mfma_f32_16x16x32_bf16 v[124:127], v[186:189], v[202:205], v[124:127]
	v_mfma_f32_16x16x32_bf16 v[120:123], v[194:197], v[202:205], v[120:123]
	v_mfma_f32_16x16x32_bf16 v[116:119], v[186:189], v[210:213], v[116:119]
	v_mfma_f32_16x16x32_bf16 v[112:115], v[194:197], v[210:213], v[112:115]
	v_mfma_f32_16x16x32_bf16 v[108:111], v[186:189], v[218:221], v[108:111]
	v_mfma_f32_16x16x32_bf16 v[104:107], v[194:197], v[218:221], v[104:107]
	v_mfma_f32_16x16x32_bf16 v[100:103], v[186:189], v[226:229], v[100:103]
	v_mfma_f32_16x16x32_bf16 v[96:99], v[194:197], v[226:229], v[96:99]
	s_setprio 1
	s_barrier
	v_add_u32_e32 v177, v158, v159
	v_add_u32_e32 v179, v158, v161
	v_mov_b32_e32 v128, v130
	v_mov_b32_e32 v246, v131
	v_add_u32_e32 v178, v158, v160
	ds_read_b128 v[230:233], v177
	ds_read_b128 v[234:237], v178
	v_add_u32_e32 v180, v158, v162
	ds_read_b128 v[238:241], v179
	ds_read_b128 v[242:245], v180
	v_readfirstlane_b32 s75, v149
	v_lshl_add_u64 v[248:249], s[38:39], 0, v[128:129]
	v_mov_b32_e32 v247, v129
	v_lshl_add_u64 v[248:249], v[248:249], 0, s[24:25]
	s_mov_b32 m0, s75
	v_lshl_add_u64 v[246:247], s[38:39], 0, v[246:247]
	v_readfirstlane_b32 s75, v150
	global_load_lds_dwordx4 v[248:249], off
	v_lshl_add_u64 v[246:247], v[246:247], 0, s[24:25]
	s_mov_b32 m0, s75
	s_nop 0
	global_load_lds_dwordx4 v[246:247], off
	s_barrier
; #define LDA(dst, b, h) for (int m = 0; m < 4; ++m) for (int k = 0; k < 2; ++k) \
;     dst[m][k] = *reinterpret_cast<const bf16x8*>((char*)SA(b, h) + lds_byte(wr * 64 + m * 16 + fr, k * 32 + fq * 8))
; #define LDB(dst, b, h) for (int n = 0; n < 2; ++n) for (int k = 0; k < 2; ++k) \
;     dst[n][k] = *reinterpret_cast<const bf16x8*>((char*)SB(b, h) + lds_byte(wc * 32 + n * 16 + fr, k * 32 + fq * 8))
; #define MMA(ai, bj, At_, Bt_) do { __builtin_amdgcn_s_setprio(1); \
;     for (int m = 0; m < 4; ++m) for (int n = 0; n < 2; ++n) for (int k = 0; k < 2; ++k) \
;       acc[ai][bj][m][n] = MFMA16(Bt_[n][k], At_[m][k], acc[ai][bj][m][n]); \
;     __builtin_amdgcn_s_setprio(0); } while (0)
; #define WAIT_V(n) asm volatile("s_waitcnt vmcnt(" #n ")" ::: "memory")
; #define WAIT_L(n) asm volatile("s_waitcnt lgkmcnt(" #n ")" ::: "memory")
; #define BAR __builtin_amdgcn_s_barrier()
; #define SCHED __builtin_amdgcn_sched_barrier(0)
; template <int PART  , bool SYNC_FIRST = true>
; __device__ __forceinline__ void kloop_t(const u16* __restrict__ A, int lda, const u16* __restrict__ Bt, int ldb, int K, Acc& acc, const int wv) {
;     ...
;     BAR; WAIT_L(0); MMA(0, 1, At, B1); BAR;
;     LDA(At, 1, 1); STAGE(SA(1, 0), A, lda, 0, t + 3);
;     BAR; WAIT_L(0); MMA(1, 0, At, B0); BAR; SCHED;
;     STAGE(SB(1, 1), Bt, ldb, HALF, t + 3);
;     WAIT_V(6); BAR; MMA(1, 1, At, B1); BAR;
;   }
;   { LDB(B0, 0, 0); LDA(At, 0, 0); STAGE(SA(1, 1), A, lda, HALF, nt - 1);
;     BAR; WAIT_L(0); MMA(0, 0, At, B0); BAR;
	s_waitcnt lgkmcnt(0)
	s_setprio 0
	s_waitcnt lgkmcnt(0)
	v_mfma_f32_16x16x32_bf16 v[92:95], v[230:233], v[198:201], v[92:95]
	v_mfma_f32_16x16x32_bf16 v[88:91], v[238:241], v[198:201], v[88:91]
	v_mfma_f32_16x16x32_bf16 v[84:87], v[230:233], v[206:209], v[84:87]
	v_mfma_f32_16x16x32_bf16 v[80:83], v[238:241], v[206:209], v[80:83]
	v_mfma_f32_16x16x32_bf16 v[76:79], v[230:233], v[214:217], v[76:79]
	v_mfma_f32_16x16x32_bf16 v[72:75], v[238:241], v[214:217], v[72:75]
	v_mfma_f32_16x16x32_bf16 v[68:71], v[230:233], v[222:225], v[68:71]
	v_mfma_f32_16x16x32_bf16 v[64:67], v[238:241], v[222:225], v[64:67]
	v_mfma_f32_16x16x32_bf16 v[92:95], v[234:237], v[202:205], v[92:95]
	v_mfma_f32_16x16x32_bf16 v[88:91], v[242:245], v[202:205], v[88:91]
	v_mfma_f32_16x16x32_bf16 v[84:87], v[234:237], v[210:213], v[84:87]
	v_mfma_f32_16x16x32_bf16 v[80:83], v[242:245], v[210:213], v[80:83]
	v_mfma_f32_16x16x32_bf16 v[76:79], v[234:237], v[218:221], v[76:79]
	v_mfma_f32_16x16x32_bf16 v[72:75], v[242:245], v[218:221], v[72:75]
	v_mfma_f32_16x16x32_bf16 v[68:71], v[234:237], v[226:229], v[68:71]
	v_mfma_f32_16x16x32_bf16 v[64:67], v[242:245], v[226:229], v[64:67]
	s_setprio 1
	v_mov_b32_e32 v128, v130
	v_mov_b32_e32 v246, v131
	s_barrier
	ds_read_b128 v[198:201], v132 offset:49152
	ds_read_b128 v[202:205], v133 offset:49152
	ds_read_b128 v[206:209], v135 offset:49152
	ds_read_b128 v[210:213], v136 offset:49152
	ds_read_b128 v[214:217], v137 offset:49152
	ds_read_b128 v[218:221], v138 offset:49152
	ds_read_b128 v[222:225], v139 offset:49152
	ds_read_b128 v[226:229], v140 offset:49152
	v_readfirstlane_b32 s75, v151
	v_lshl_add_u64 v[248:249], s[36:37], 0, v[128:129]
	v_mov_b32_e32 v247, v129
	v_lshl_add_u64 v[248:249], v[248:249], 0, s[26:27]
	s_mov_b32 m0, s75
	v_lshl_add_u64 v[246:247], s[36:37], 0, v[246:247]
	v_readfirstlane_b32 s36, v152
	global_load_lds_dwordx4 v[248:249], off
	v_lshl_add_u64 v[246:247], v[246:247], 0, s[26:27]
	s_mov_b32 m0, s36
	s_nop 0
	global_load_lds_dwordx4 v[246:247], off
	s_barrier
	s_waitcnt lgkmcnt(0)
	s_setprio 0
	s_waitcnt lgkmcnt(0)
	v_mfma_f32_16x16x32_bf16 v[60:63], v[182:185], v[198:201], v[60:63]
	v_mfma_f32_16x16x32_bf16 v[56:59], v[190:193], v[198:201], v[56:59]
	v_mfma_f32_16x16x32_bf16 v[52:55], v[182:185], v[206:209], v[52:55]
	v_mfma_f32_16x16x32_bf16 v[48:51], v[190:193], v[206:209], v[48:51]
	v_mfma_f32_16x16x32_bf16 v[44:47], v[182:185], v[214:217], v[44:47]
	v_mfma_f32_16x16x32_bf16 v[40:43], v[190:193], v[214:217], v[40:43]
	v_mfma_f32_16x16x32_bf16 v[36:39], v[182:185], v[222:225], v[36:39]
	v_mfma_f32_16x16x32_bf16 v[32:35], v[190:193], v[222:225], v[32:35]
	v_mfma_f32_16x16x32_bf16 v[60:63], v[186:189], v[202:205], v[60:63]
	v_mfma_f32_16x16x32_bf16 v[56:59], v[194:197], v[202:205], v[56:59]
	v_mfma_f32_16x16x32_bf16 v[52:55], v[186:189], v[210:213], v[52:55]
	v_mfma_f32_16x16x32_bf16 v[48:51], v[194:197], v[210:213], v[48:51]
	v_mfma_f32_16x16x32_bf16 v[44:47], v[186:189], v[218:221], v[44:47]
	v_mfma_f32_16x16x32_bf16 v[40:43], v[194:197], v[218:221], v[40:43]
	v_mfma_f32_16x16x32_bf16 v[36:39], v[186:189], v[226:229], v[36:39]
	v_mfma_f32_16x16x32_bf16 v[32:35], v[194:197], v[226:229], v[32:35]
	s_setprio 1
	s_barrier
	v_mov_b32_e32 v128, v130
	v_mov_b32_e32 v182, v131
	v_readfirstlane_b32 s36, v153
	v_lshl_add_u64 v[184:185], s[38:39], 0, v[128:129]
	v_mov_b32_e32 v183, v129
	v_lshl_add_u64 v[184:185], v[184:185], 0, s[28:29]
	s_mov_b32 m0, s36
	v_lshl_add_u64 v[182:183], s[38:39], 0, v[182:183]
	v_readfirstlane_b32 s36, v154
	global_load_lds_dwordx4 v[184:185], off
	v_lshl_add_u64 v[182:183], v[182:183], 0, s[28:29]
	s_mov_b32 m0, s36
	s_nop 0
	global_load_lds_dwordx4 v[182:183], off
	s_waitcnt vmcnt(6)
	s_barrier
	s_setprio 0
	v_mfma_f32_16x16x32_bf16 v[28:31], v[230:233], v[198:201], v[28:31]
	v_mfma_f32_16x16x32_bf16 v[24:27], v[238:241], v[198:201], v[24:27]
	v_mfma_f32_16x16x32_bf16 v[20:23], v[230:233], v[206:209], v[20:23]
	v_mfma_f32_16x16x32_bf16 v[16:19], v[238:241], v[206:209], v[16:19]
	v_mfma_f32_16x16x32_bf16 v[12:15], v[230:233], v[214:217], v[12:15]
	v_mfma_f32_16x16x32_bf16 v[8:11], v[238:241], v[214:217], v[8:11]
	v_mfma_f32_16x16x32_bf16 v[4:7], v[230:233], v[222:225], v[4:7]
	v_mfma_f32_16x16x32_bf16 v[0:3], v[238:241], v[222:225], v[0:3]
	v_mfma_f32_16x16x32_bf16 v[28:31], v[234:237], v[202:205], v[28:31]
	v_mfma_f32_16x16x32_bf16 v[24:27], v[242:245], v[202:205], v[24:27]
	v_mfma_f32_16x16x32_bf16 v[20:23], v[234:237], v[210:213], v[20:23]
	v_mfma_f32_16x16x32_bf16 v[16:19], v[242:245], v[210:213], v[16:19]
	v_mfma_f32_16x16x32_bf16 v[12:15], v[234:237], v[218:221], v[12:15]
	v_mfma_f32_16x16x32_bf16 v[8:11], v[242:245], v[218:221], v[8:11]
	v_mfma_f32_16x16x32_bf16 v[4:7], v[234:237], v[226:229], v[4:7]
	v_mfma_f32_16x16x32_bf16 v[0:3], v[242:245], v[226:229], v[0:3]
	s_setprio 1
	s_add_i32 s74, s74, 2
	s_add_u32 s34, s34, 0x100
	s_addc_u32 s35, s35, 0
	s_cmp_lt_u32 s74, 12
	s_barrier
	s_cbranch_scc1 .LBB0_980
	s_add_u32 s30, s30, 0x40780
	v_readfirstlane_b32 s34, v167
	s_addc_u32 s31, s31, 0
	s_mov_b32 m0, s34
	v_readfirstlane_b32 s34, v168
	ds_read_b128 v[142:145], v163
	ds_read_b128 v[146:149], v164
	ds_read_b128 v[150:153], v165
	ds_read_b128 v[154:157], v166
	ds_read_b128 v[158:161], v132
	ds_read_b128 v[162:165], v133
	ds_read_b128 v[182:185], v135
	ds_read_b128 v[186:189], v136
	ds_read_b128 v[190:193], v137
	ds_read_b128 v[194:197], v138
	ds_read_b128 v[198:201], v139
	ds_read_b128 v[202:205], v140
	s_nop 0
	global_load_lds_dwordx4 v130, s[30:31]
	s_mov_b32 m0, s34
	s_nop 0
	global_load_lds_dwordx4 v131, s[30:31]
	s_barrier
; #define LDA(dst, b, h) for (int m = 0; m < 4; ++m) for (int k = 0; k < 2; ++k) \
;     dst[m][k] = *reinterpret_cast<const bf16x8*>((char*)SA(b, h) + lds_byte(wr * 64 + m * 16 + fr, k * 32 + fq * 8))
; #define LDB(dst, b, h) for (int n = 0; n < 2; ++n) for (int k = 0; k < 2; ++k) \
;     dst[n][k] = *reinterpret_cast<const bf16x8*>((char*)SB(b, h) + lds_byte(wc * 32 + n * 16 + fr, k * 32 + fq * 8))
; #define MMA(ai, bj, At_, Bt_) do { __builtin_amdgcn_s_setprio(1); \
;     for (int m = 0; m < 4; ++m) for (int n = 0; n < 2; ++n) for (int k = 0; k < 2; ++k) \
;       acc[ai][bj][m][n] = MFMA16(Bt_[n][k], At_[m][k], acc[ai][bj][m][n]); \
;     __builtin_amdgcn_s_setprio(0); } while (0)
; #define WAIT_V(n) asm volatile("s_waitcnt vmcnt(" #n ")" ::: "memory")
; #define WAIT_L(n) asm volatile("s_waitcnt lgkmcnt(" #n ")" ::: "memory")
; #define BAR __builtin_amdgcn_s_barrier()
; template <int PART  , bool SYNC_FIRST = true>
; __device__ __forceinline__ void kloop_t(const u16* __restrict__ A, int lda, const u16* __restrict__ Bt, int ldb, int K, Acc& acc, const int wv) {
;     ...
;     BAR; WAIT_L(0); MMA(0, 0, At, B0); BAR;
;     LDB(B1, 0, 1); BAR; WAIT_L(0); MMA(0, 1, At, B1); BAR;
;     LDA(At, 0, 1); WAIT_V(4); BAR; WAIT_L(0); MMA(1, 0, At, B0); MMA(1, 1, At, B1); BAR; }
	s_waitcnt lgkmcnt(0)
	s_setprio 0
	s_waitcnt lgkmcnt(0)
	v_mfma_f32_16x16x32_bf16 v[124:127], v[142:145], v[158:161], v[124:127]
	v_mfma_f32_16x16x32_bf16 v[116:119], v[142:145], v[182:185], v[116:119]
	v_mfma_f32_16x16x32_bf16 v[112:115], v[150:153], v[182:185], v[112:115]
	v_mfma_f32_16x16x32_bf16 v[100:103], v[142:145], v[198:201], v[100:103]
	v_mfma_f32_16x16x32_bf16 v[96:99], v[150:153], v[198:201], v[96:99]
	v_mfma_f32_16x16x32_bf16 v[124:127], v[146:149], v[162:165], v[124:127]
	v_mfma_f32_16x16x32_bf16 v[120:123], v[150:153], v[158:161], v[120:123]
	v_mfma_f32_16x16x32_bf16 v[116:119], v[146:149], v[186:189], v[116:119]
	v_mfma_f32_16x16x32_bf16 v[112:115], v[154:157], v[186:189], v[112:115]
	v_mfma_f32_16x16x32_bf16 v[108:111], v[142:145], v[190:193], v[108:111]
	v_mfma_f32_16x16x32_bf16 v[104:107], v[150:153], v[190:193], v[104:107]
	v_mfma_f32_16x16x32_bf16 v[100:103], v[146:149], v[202:205], v[100:103]
	v_mfma_f32_16x16x32_bf16 v[96:99], v[154:157], v[202:205], v[96:99]
	v_mfma_f32_16x16x32_bf16 v[206:209], v[154:157], v[162:165], v[120:123]
	v_mfma_f32_16x16x32_bf16 v[210:213], v[146:149], v[194:197], v[108:111]
	v_mfma_f32_16x16x32_bf16 v[214:217], v[154:157], v[194:197], v[104:107]
	s_setprio 1
	s_barrier
	s_nop 0
	ds_read_b128 v[104:107], v169
	ds_read_b128 v[108:111], v170
	ds_read_b128 v[120:123], v171
	ds_read_b128 v[166:169], v172
	s_barrier
	s_waitcnt lgkmcnt(0)
	s_setprio 0
	s_waitcnt lgkmcnt(0)
	v_mfma_f32_16x16x32_bf16 v[84:87], v[104:107], v[182:185], v[84:87]
	v_mfma_f32_16x16x32_bf16 v[80:83], v[120:123], v[182:185], v[80:83]
	v_mfma_f32_16x16x32_bf16 v[68:71], v[104:107], v[198:201], v[68:71]
	v_mfma_f32_16x16x32_bf16 v[64:67], v[120:123], v[198:201], v[64:67]
	v_mfma_f32_16x16x32_bf16 v[92:95], v[104:107], v[158:161], v[92:95]
	v_mfma_f32_16x16x32_bf16 v[88:91], v[120:123], v[158:161], v[88:91]
	v_mfma_f32_16x16x32_bf16 v[84:87], v[108:111], v[186:189], v[84:87]
	v_mfma_f32_16x16x32_bf16 v[80:83], v[166:169], v[186:189], v[80:83]
	v_mfma_f32_16x16x32_bf16 v[76:79], v[104:107], v[190:193], v[76:79]
	v_mfma_f32_16x16x32_bf16 v[72:75], v[120:123], v[190:193], v[72:75]
	v_mfma_f32_16x16x32_bf16 v[68:71], v[108:111], v[202:205], v[68:71]
	v_mfma_f32_16x16x32_bf16 v[64:67], v[166:169], v[202:205], v[64:67]
	v_mfma_f32_16x16x32_bf16 v[218:221], v[108:111], v[162:165], v[92:95]
	v_mfma_f32_16x16x32_bf16 v[158:161], v[166:169], v[162:165], v[88:91]
	v_mfma_f32_16x16x32_bf16 v[162:165], v[108:111], v[194:197], v[76:79]
	v_mfma_f32_16x16x32_bf16 v[182:185], v[166:169], v[194:197], v[72:75]
	s_setprio 1
	s_barrier
	s_nop 0
	ds_read_b128 v[72:75], v132 offset:16384
	ds_read_b128 v[76:79], v133 offset:16384
	ds_read_b128 v[88:91], v135 offset:16384
	ds_read_b128 v[92:95], v136 offset:16384
	ds_read_b128 v[186:189], v137 offset:16384
	ds_read_b128 v[190:193], v138 offset:16384
	ds_read_b128 v[194:197], v139 offset:16384
	ds_read_b128 v[198:201], v140 offset:16384
	s_waitcnt vmcnt(4)
	s_barrier
	s_waitcnt lgkmcnt(0)
	s_setprio 0
	s_waitcnt lgkmcnt(0)
	v_mfma_f32_16x16x32_bf16 v[60:63], v[142:145], v[72:75], v[60:63]
	v_mfma_f32_16x16x32_bf16 v[52:55], v[142:145], v[88:91], v[52:55]
	v_mfma_f32_16x16x32_bf16 v[48:51], v[150:153], v[88:91], v[48:51]
	v_mfma_f32_16x16x32_bf16 v[36:39], v[142:145], v[194:197], v[36:39]
	v_mfma_f32_16x16x32_bf16 v[32:35], v[150:153], v[194:197], v[32:35]
	v_mfma_f32_16x16x32_bf16 v[60:63], v[146:149], v[76:79], v[60:63]
	v_mfma_f32_16x16x32_bf16 v[56:59], v[150:153], v[72:75], v[56:59]
	v_mfma_f32_16x16x32_bf16 v[52:55], v[146:149], v[92:95], v[52:55]
	v_mfma_f32_16x16x32_bf16 v[48:51], v[154:157], v[92:95], v[48:51]
	v_mfma_f32_16x16x32_bf16 v[44:47], v[142:145], v[186:189], v[44:47]
	v_mfma_f32_16x16x32_bf16 v[40:43], v[150:153], v[186:189], v[40:43]
	v_mfma_f32_16x16x32_bf16 v[36:39], v[146:149], v[198:201], v[36:39]
	v_mfma_f32_16x16x32_bf16 v[32:35], v[154:157], v[198:201], v[32:35]
	v_mfma_f32_16x16x32_bf16 v[202:205], v[154:157], v[76:79], v[56:59]
	v_mfma_f32_16x16x32_bf16 v[222:225], v[146:149], v[190:193], v[44:47]
	v_mfma_f32_16x16x32_bf16 v[226:229], v[154:157], v[190:193], v[40:43]
	s_setprio 1
	s_setprio 0
	v_mfma_f32_16x16x32_bf16 v[20:23], v[104:107], v[88:91], v[20:23]
	v_mfma_f32_16x16x32_bf16 v[16:19], v[120:123], v[88:91], v[16:19]
	v_mfma_f32_16x16x32_bf16 v[4:7], v[104:107], v[194:197], v[4:7]
	v_mfma_f32_16x16x32_bf16 v[0:3], v[120:123], v[194:197], v[0:3]
	v_mfma_f32_16x16x32_bf16 v[28:31], v[104:107], v[72:75], v[28:31]
	v_mfma_f32_16x16x32_bf16 v[24:27], v[120:123], v[72:75], v[24:27]
	v_mfma_f32_16x16x32_bf16 v[20:23], v[108:111], v[92:95], v[20:23]
	v_mfma_f32_16x16x32_bf16 v[16:19], v[166:169], v[92:95], v[16:19]
	v_mfma_f32_16x16x32_bf16 v[12:15], v[104:107], v[186:189], v[12:15]
	v_mfma_f32_16x16x32_bf16 v[8:11], v[120:123], v[186:189], v[8:11]
	v_mfma_f32_16x16x32_bf16 v[4:7], v[108:111], v[198:201], v[4:7]
	v_mfma_f32_16x16x32_bf16 v[0:3], v[166:169], v[198:201], v[0:3]
	v_mfma_f32_16x16x32_bf16 v[142:145], v[108:111], v[76:79], v[28:31]
	v_mfma_f32_16x16x32_bf16 v[146:149], v[166:169], v[76:79], v[24:27]
	v_mfma_f32_16x16x32_bf16 v[150:153], v[108:111], v[190:193], v[12:15]
	v_mfma_f32_16x16x32_bf16 v[154:157], v[166:169], v[190:193], v[8:11]
	s_setprio 1
	s_barrier
; #define LDA(dst, b, h) for (int m = 0; m < 4; ++m) for (int k = 0; k < 2; ++k) \
;     dst[m][k] = *reinterpret_cast<const bf16x8*>((char*)SA(b, h) + lds_byte(wr * 64 + m * 16 + fr, k * 32 + fq * 8))
; #define LDB(dst, b, h) for (int n = 0; n < 2; ++n) for (int k = 0; k < 2; ++k) \
;     dst[n][k] = *reinterpret_cast<const bf16x8*>((char*)SB(b, h) + lds_byte(wc * 32 + n * 16 + fr, k * 32 + fq * 8))
; #define MMA(ai, bj, At_, Bt_) do { __builtin_amdgcn_s_setprio(1); \
;     for (int m = 0; m < 4; ++m) for (int n = 0; n < 2; ++n) for (int k = 0; k < 2; ++k) \
;       acc[ai][bj][m][n] = MFMA16(Bt_[n][k], At_[m][k], acc[ai][bj][m][n]); \
;     __builtin_amdgcn_s_setprio(0); } while (0)
; #define WAIT_V(n) asm volatile("s_waitcnt vmcnt(" #n ")" ::: "memory")
; #define WAIT_L(n) asm volatile("s_waitcnt lgkmcnt(" #n ")" ::: "memory")
; #define BAR __builtin_amdgcn_s_barrier()
; template <int PART  , bool SYNC_FIRST = true>
; __device__ __forceinline__ void kloop_t(const u16* __restrict__ A, int lda, const u16* __restrict__ Bt, int ldb, int K, Acc& acc, const int wv) {
;     ...
;   { LDB(B0, 1, 0); LDA(At, 1, 0); WAIT_V(2); BAR; WAIT_L(0); MMA(0, 0, At, B0); BAR;
;     LDB(B1, 1, 1); WAIT_V(0); BAR; WAIT_L(0); MMA(0, 1, At, B1); BAR;
;     LDA(At, 1, 1); BAR; WAIT_L(0); MMA(1, 0, At, B0); MMA(1, 1, At, B1); BAR; }
;   if (wr == 0) BAR;
	s_nop 0
	ds_read_b128 v[8:11], v173
	ds_read_b128 v[12:15], v174
	ds_read_b128 v[166:169], v175
	ds_read_b128 v[170:173], v176
	ds_read_b128 v[24:27], v132 offset:32768
	ds_read_b128 v[28:31], v133 offset:32768
	ds_read_b128 v[40:43], v135 offset:32768
	ds_read_b128 v[44:47], v136 offset:32768
	ds_read_b128 v[56:59], v137 offset:32768
	ds_read_b128 v[186:189], v138 offset:32768
	ds_read_b128 v[190:193], v139 offset:32768
	ds_read_b128 v[194:197], v140 offset:32768
	s_waitcnt vmcnt(2)
	s_barrier
	s_waitcnt lgkmcnt(0)
	s_setprio 0
	s_waitcnt lgkmcnt(0)
	v_mfma_f32_16x16x32_bf16 v[72:75], v[8:11], v[24:27], v[124:127]
	v_mfma_f32_16x16x32_bf16 v[120:123], v[12:15], v[28:31], v[72:75]
	v_mfma_f32_16x16x32_bf16 v[72:75], v[166:169], v[24:27], v[206:209]
	v_mfma_f32_16x16x32_bf16 v[124:127], v[170:173], v[28:31], v[72:75]
	v_mfma_f32_16x16x32_bf16 v[72:75], v[8:11], v[40:43], v[116:119]
	v_mfma_f32_16x16x32_bf16 v[104:107], v[12:15], v[44:47], v[72:75]
	v_mfma_f32_16x16x32_bf16 v[72:75], v[166:169], v[40:43], v[112:115]
	v_mfma_f32_16x16x32_bf16 v[108:111], v[170:173], v[44:47], v[72:75]
	v_mfma_f32_16x16x32_bf16 v[72:75], v[8:11], v[56:59], v[210:213]
	v_mfma_f32_16x16x32_bf16 v[88:91], v[12:15], v[186:189], v[72:75]
	v_mfma_f32_16x16x32_bf16 v[72:75], v[166:169], v[56:59], v[214:217]
	v_mfma_f32_16x16x32_bf16 v[92:95], v[170:173], v[186:189], v[72:75]
	v_mfma_f32_16x16x32_bf16 v[72:75], v[8:11], v[190:193], v[100:103]
	v_mfma_f32_16x16x32_bf16 v[76:79], v[166:169], v[190:193], v[96:99]
	v_mfma_f32_16x16x32_bf16 v[72:75], v[12:15], v[194:197], v[72:75]
	v_mfma_f32_16x16x32_bf16 v[76:79], v[170:173], v[194:197], v[76:79]
	s_setprio 1
	s_barrier
	ds_read_b128 v[174:177], v177
	ds_read_b128 v[198:201], v178
	ds_read_b128 v[206:209], v179
	ds_read_b128 v[178:181], v180
	s_waitcnt vmcnt(0)
	s_barrier
	s_waitcnt lgkmcnt(0)
	s_setprio 0
	s_waitcnt lgkmcnt(0)
	v_mfma_f32_16x16x32_bf16 v[96:99], v[174:177], v[24:27], v[218:221]
	v_mfma_f32_16x16x32_bf16 v[24:27], v[206:209], v[24:27], v[158:161]
	v_mfma_f32_16x16x32_bf16 v[112:115], v[178:181], v[28:31], v[24:27]
	v_mfma_f32_16x16x32_bf16 v[24:27], v[174:177], v[40:43], v[84:87]
	v_mfma_f32_16x16x32_bf16 v[100:103], v[198:201], v[44:47], v[24:27]
	v_mfma_f32_16x16x32_bf16 v[24:27], v[206:209], v[40:43], v[80:83]
	v_mfma_f32_16x16x32_bf16 v[116:119], v[198:201], v[28:31], v[96:99]
	v_mfma_f32_16x16x32_bf16 v[96:99], v[178:181], v[44:47], v[24:27]
	v_mfma_f32_16x16x32_bf16 v[24:27], v[174:177], v[56:59], v[162:165]
	v_mfma_f32_16x16x32_bf16 v[84:87], v[198:201], v[186:189], v[24:27]
	v_mfma_f32_16x16x32_bf16 v[24:27], v[206:209], v[56:59], v[182:185]
	v_mfma_f32_16x16x32_bf16 v[80:83], v[178:181], v[186:189], v[24:27]
	v_mfma_f32_16x16x32_bf16 v[24:27], v[174:177], v[190:193], v[68:71]
	v_mfma_f32_16x16x32_bf16 v[68:71], v[198:201], v[194:197], v[24:27]
	v_mfma_f32_16x16x32_bf16 v[24:27], v[206:209], v[190:193], v[64:67]
	v_mfma_f32_16x16x32_bf16 v[64:67], v[178:181], v[194:197], v[24:27]
	s_setprio 1
	s_barrier
	ds_read_b128 v[158:161], v132 offset:49152
	ds_read_b128 v[130:133], v133 offset:49152
	ds_read_b128 v[162:165], v135 offset:49152
	ds_read_b128 v[182:185], v136 offset:49152
	ds_read_b128 v[186:189], v137 offset:49152
	ds_read_b128 v[190:193], v138 offset:49152
	ds_read_b128 v[136:139], v139 offset:49152
	ds_read_b128 v[194:197], v140 offset:49152
	s_barrier
	s_waitcnt lgkmcnt(0)
	s_setprio 0
	s_waitcnt lgkmcnt(0)
	v_mfma_f32_16x16x32_bf16 v[24:27], v[8:11], v[158:161], v[60:63]
	v_mfma_f32_16x16x32_bf16 v[56:59], v[12:15], v[130:133], v[24:27]
	v_mfma_f32_16x16x32_bf16 v[24:27], v[166:169], v[158:161], v[202:205]
	v_mfma_f32_16x16x32_bf16 v[60:63], v[170:173], v[130:133], v[24:27]
	v_mfma_f32_16x16x32_bf16 v[24:27], v[8:11], v[162:165], v[52:55]
	v_mfma_f32_16x16x32_bf16 v[40:43], v[12:15], v[182:185], v[24:27]
	v_mfma_f32_16x16x32_bf16 v[24:27], v[166:169], v[162:165], v[48:51]
	v_mfma_f32_16x16x32_bf16 v[44:47], v[170:173], v[182:185], v[24:27]
	v_mfma_f32_16x16x32_bf16 v[24:27], v[8:11], v[186:189], v[222:225]
	v_mfma_f32_16x16x32_bf16 v[8:11], v[8:11], v[136:139], v[36:39]
	v_mfma_f32_16x16x32_bf16 v[24:27], v[12:15], v[190:193], v[24:27]
	v_mfma_f32_16x16x32_bf16 v[28:31], v[166:169], v[186:189], v[226:229]
	v_mfma_f32_16x16x32_bf16 v[8:11], v[12:15], v[194:197], v[8:11]
	v_mfma_f32_16x16x32_bf16 v[12:15], v[166:169], v[136:139], v[32:35]
	v_mfma_f32_16x16x32_bf16 v[28:31], v[170:173], v[190:193], v[28:31]
	v_mfma_f32_16x16x32_bf16 v[12:15], v[170:173], v[194:197], v[12:15]
	s_setprio 1
	s_setprio 0
	v_mfma_f32_16x16x32_bf16 v[32:35], v[174:177], v[158:161], v[142:145]
	v_mfma_f32_16x16x32_bf16 v[52:55], v[198:201], v[130:133], v[32:35]
	v_mfma_f32_16x16x32_bf16 v[32:35], v[206:209], v[158:161], v[146:149]
	v_mfma_f32_16x16x32_bf16 v[16:19], v[206:209], v[162:165], v[16:19]
	v_mfma_f32_16x16x32_bf16 v[48:51], v[178:181], v[130:133], v[32:35]
	v_mfma_f32_16x16x32_bf16 v[20:23], v[174:177], v[162:165], v[20:23]
	v_mfma_f32_16x16x32_bf16 v[32:35], v[178:181], v[182:185], v[16:19]
	v_mfma_f32_16x16x32_bf16 v[16:19], v[174:177], v[186:189], v[150:153]
	v_mfma_f32_16x16x32_bf16 v[36:39], v[198:201], v[182:185], v[20:23]
	v_mfma_f32_16x16x32_bf16 v[20:23], v[198:201], v[190:193], v[16:19]
	v_mfma_f32_16x16x32_bf16 v[16:19], v[206:209], v[186:189], v[154:157]
	v_mfma_f32_16x16x32_bf16 v[4:7], v[174:177], v[136:139], v[4:7]
	v_mfma_f32_16x16x32_bf16 v[0:3], v[206:209], v[136:139], v[0:3]
	v_mfma_f32_16x16x32_bf16 v[16:19], v[178:181], v[190:193], v[16:19]
	v_mfma_f32_16x16x32_bf16 v[4:7], v[198:201], v[194:197], v[4:7]
	v_mfma_f32_16x16x32_bf16 v[0:3], v[178:181], v[194:197], v[0:3]
	s_setprio 1
	s_andn2_b64 vcc, exec, s[0:1]
	s_barrier
	s_cbranch_vccnz .LBB0_983
	s_barrier

; #define LDA(dst, b, h) for (int m = 0; m < 4; ++m) for (int k = 0; k < 2; ++k) \
;     dst[m][k] = *reinterpret_cast<const bf16x8*>((char*)SA(b, h) + lds_byte(wr * 64 + m * 16 + fr, k * 32 + fq * 8))
; #define LDB(dst, b, h) for (int n = 0; n < 2; ++n) for (int k = 0; k < 2; ++k) \
;     dst[n][k] = *reinterpret_cast<const bf16x8*>((char*)SB(b, h) + lds_byte(wc * 32 + n * 16 + fr, k * 32 + fq * 8))
; #define MMA(ai, bj, At_, Bt_) do { __builtin_amdgcn_s_setprio(1); \
;     for (int m = 0; m < 4; ++m) for (int n = 0; n < 2; ++n) for (int k = 0; k < 2; ++k) \
;       acc[ai][bj][m][n] = MFMA16(Bt_[n][k], At_[m][k], acc[ai][bj][m][n]); \
;     __builtin_amdgcn_s_setprio(0); } while (0)
; #define WAIT_L(n) asm volatile("s_waitcnt lgkmcnt(" #n ")" ::: "memory")
; #define BAR __builtin_amdgcn_s_barrier()
; #define SCHED __builtin_amdgcn_sched_barrier(0)
; template <int PART  , bool SYNC_FIRST = true>
; __device__ __forceinline__ void kloop_t(const u16* __restrict__ A, int lda, const u16* __restrict__ Bt, int ldb, int K, Acc& acc, const int wv) {
;     ...
;     LDB(B0, 0, 0); SCHED; LDA(At, 0, 0); STAGE(SA(1, 1), A, lda, HALF, t + 1);
;     WAIT_L(8); BAR; WAIT_L(0); MMA(0, 0, At, B0); BAR; SCHED;
;     LDB(B1, 0, 1); STAGE(SB(0, 0), Bt, ldb, 0, t + 2);
;     BAR; WAIT_L(0); MMA(0, 1, At, B1); BAR;
;     LDA(At, 0, 1); STAGE(SA(0, 0), A, lda, 0, t + 2);
.LBB0_1069:
	v_add_u32_e32 v158, v150, v154
	v_add_u32_e32 v160, v150, v156
	v_add_u32_e32 v159, v150, v155
	ds_read_b128 v[168:171], v158
	ds_read_b128 v[172:175], v159
	v_add_u32_e32 v161, v150, v157
	ds_read_b128 v[176:179], v160
	ds_read_b128 v[180:183], v161
	s_add_u32 s40, s38, s79
	v_mov_b32_e32 v128, v140
	v_mov_b32_e32 v164, v142
	s_addc_u32 s41, s39, 0
	ds_read_b128 v[184:187], v130
	ds_read_b128 v[188:191], v131
	ds_read_b128 v[192:195], v134
	ds_read_b128 v[196:199], v135
	ds_read_b128 v[200:203], v136
	ds_read_b128 v[204:207], v137
	ds_read_b128 v[208:211], v138
	ds_read_b128 v[212:215], v139
	v_mov_b32_e32 v165, v129
	v_lshl_add_u64 v[162:163], s[40:41], 0, v[128:129]
	v_lshl_add_u64 v[166:167], v[162:163], 0, s[18:19]
	v_add_u32_e32 v162, 0xc000, v145
	v_add_u32_e32 v163, 0xe000, v145
	v_readfirstlane_b32 s42, v162
	s_mov_b32 m0, s42
	v_lshl_add_u64 v[164:165], s[40:41], 0, v[164:165]
	v_readfirstlane_b32 s42, v163
	global_load_lds_dwordx4 v[166:167], off
	v_lshl_add_u64 v[164:165], v[164:165], 0, s[18:19]
	s_mov_b32 m0, s42
	s_nop 0
	global_load_lds_dwordx4 v[164:165], off
	s_waitcnt lgkmcnt(8)
	s_barrier
	s_waitcnt lgkmcnt(0)
	s_setprio 0
	s_waitcnt lgkmcnt(0)
	v_mfma_f32_16x16x32_bf16 v[124:127], v[168:171], v[184:187], v[124:127]
	v_mfma_f32_16x16x32_bf16 v[120:123], v[176:179], v[184:187], v[120:123]
	v_mfma_f32_16x16x32_bf16 v[116:119], v[168:171], v[192:195], v[116:119]
	v_mfma_f32_16x16x32_bf16 v[112:115], v[176:179], v[192:195], v[112:115]
	v_mfma_f32_16x16x32_bf16 v[108:111], v[168:171], v[200:203], v[108:111]
	v_mfma_f32_16x16x32_bf16 v[104:107], v[176:179], v[200:203], v[104:107]
	v_mfma_f32_16x16x32_bf16 v[100:103], v[168:171], v[208:211], v[100:103]
	v_mfma_f32_16x16x32_bf16 v[96:99], v[176:179], v[208:211], v[96:99]
	v_mfma_f32_16x16x32_bf16 v[124:127], v[172:175], v[188:191], v[124:127]
	v_mfma_f32_16x16x32_bf16 v[120:123], v[180:183], v[188:191], v[120:123]
	v_mfma_f32_16x16x32_bf16 v[116:119], v[172:175], v[196:199], v[116:119]
	v_mfma_f32_16x16x32_bf16 v[112:115], v[180:183], v[196:199], v[112:115]
	v_mfma_f32_16x16x32_bf16 v[108:111], v[172:175], v[204:207], v[108:111]
	v_mfma_f32_16x16x32_bf16 v[104:107], v[180:183], v[204:207], v[104:107]
	v_mfma_f32_16x16x32_bf16 v[100:103], v[172:175], v[212:215], v[100:103]
	v_mfma_f32_16x16x32_bf16 v[96:99], v[180:183], v[212:215], v[96:99]
	s_setprio 1
	s_barrier
	v_add_u32_e32 v164, v151, v154
	v_add_u32_e32 v166, v151, v156
	v_mov_b32_e32 v128, v140
	v_mov_b32_e32 v232, v142
	s_add_u32 s42, s38, s80
	v_add_u32_e32 v165, v151, v155
	ds_read_b128 v[216:219], v164
	ds_read_b128 v[220:223], v165
	v_add_u32_e32 v167, v151, v157
	ds_read_b128 v[224:227], v166
	ds_read_b128 v[228:231], v167
	s_addc_u32 s43, s39, 0
	v_lshl_add_u64 v[234:235], s[42:43], 0, v[128:129]
	v_add_u32_e32 v128, s54, v141
	v_mov_b32_e32 v233, v129
	v_readfirstlane_b32 s82, v128
	v_add_u32_e32 v128, 0x2000, v128
	v_lshl_add_u64 v[234:235], v[234:235], 0, s[20:21]
	s_mov_b32 m0, s82
	v_lshl_add_u64 v[232:233], s[42:43], 0, v[232:233]
	v_readfirstlane_b32 s82, v128
	global_load_lds_dwordx4 v[234:235], off
	v_lshl_add_u64 v[232:233], v[232:233], 0, s[20:21]
	s_mov_b32 m0, s82
	s_nop 0
	global_load_lds_dwordx4 v[232:233], off
	s_barrier
	s_waitcnt lgkmcnt(0)
	s_setprio 0
	s_waitcnt lgkmcnt(0)
	v_mfma_f32_16x16x32_bf16 v[92:95], v[216:219], v[184:187], v[92:95]
	v_mfma_f32_16x16x32_bf16 v[88:91], v[224:227], v[184:187], v[88:91]
	v_mfma_f32_16x16x32_bf16 v[84:87], v[216:219], v[192:195], v[84:87]
	v_mfma_f32_16x16x32_bf16 v[80:83], v[224:227], v[192:195], v[80:83]
	v_mfma_f32_16x16x32_bf16 v[76:79], v[216:219], v[200:203], v[76:79]
	v_mfma_f32_16x16x32_bf16 v[72:75], v[224:227], v[200:203], v[72:75]
	v_mfma_f32_16x16x32_bf16 v[68:71], v[216:219], v[208:211], v[68:71]
	v_mfma_f32_16x16x32_bf16 v[64:67], v[224:227], v[208:211], v[64:67]
	v_mfma_f32_16x16x32_bf16 v[92:95], v[220:223], v[188:191], v[92:95]
	v_mfma_f32_16x16x32_bf16 v[88:91], v[228:231], v[188:191], v[88:91]
	v_mfma_f32_16x16x32_bf16 v[84:87], v[220:223], v[196:199], v[84:87]
	v_mfma_f32_16x16x32_bf16 v[80:83], v[228:231], v[196:199], v[80:83]
	v_mfma_f32_16x16x32_bf16 v[76:79], v[220:223], v[204:207], v[76:79]
	v_mfma_f32_16x16x32_bf16 v[72:75], v[228:231], v[204:207], v[72:75]
	v_mfma_f32_16x16x32_bf16 v[68:71], v[220:223], v[212:215], v[68:71]
	v_mfma_f32_16x16x32_bf16 v[64:67], v[228:231], v[212:215], v[64:67]
	s_setprio 1
	v_mov_b32_e32 v128, v140
	v_mov_b32_e32 v232, v142
	s_barrier
	ds_read_b128 v[184:187], v130 offset:16384
	ds_read_b128 v[188:191], v131 offset:16384
	ds_read_b128 v[192:195], v134 offset:16384
	ds_read_b128 v[196:199], v135 offset:16384
	ds_read_b128 v[200:203], v136 offset:16384
	ds_read_b128 v[204:207], v137 offset:16384
	ds_read_b128 v[208:211], v138 offset:16384
	ds_read_b128 v[212:215], v139 offset:16384
	v_readfirstlane_b32 s82, v145
	v_lshl_add_u64 v[234:235], s[40:41], 0, v[128:129]
	v_mov_b32_e32 v233, v129
	v_add_u32_e32 v128, 0x2000, v145
	v_lshl_add_u64 v[234:235], v[234:235], 0, s[22:23]
	s_mov_b32 m0, s82
	v_lshl_add_u64 v[232:233], s[40:41], 0, v[232:233]
	v_readfirstlane_b32 s82, v128
	global_load_lds_dwordx4 v[234:235], off
	v_lshl_add_u64 v[232:233], v[232:233], 0, s[22:23]
	s_mov_b32 m0, s82
	s_nop 0
	global_load_lds_dwordx4 v[232:233], off
	s_barrier
; #define LDA(dst, b, h) for (int m = 0; m < 4; ++m) for (int k = 0; k < 2; ++k) \
;     dst[m][k] = *reinterpret_cast<const bf16x8*>((char*)SA(b, h) + lds_byte(wr * 64 + m * 16 + fr, k * 32 + fq * 8))
; #define LDB(dst, b, h) for (int n = 0; n < 2; ++n) for (int k = 0; k < 2; ++k) \
;     dst[n][k] = *reinterpret_cast<const bf16x8*>((char*)SB(b, h) + lds_byte(wc * 32 + n * 16 + fr, k * 32 + fq * 8))
; #define MMA(ai, bj, At_, Bt_) do { __builtin_amdgcn_s_setprio(1); \
;     for (int m = 0; m < 4; ++m) for (int n = 0; n < 2; ++n) for (int k = 0; k < 2; ++k) \
;       acc[ai][bj][m][n] = MFMA16(Bt_[n][k], At_[m][k], acc[ai][bj][m][n]); \
;     __builtin_amdgcn_s_setprio(0); } while (0)
; #define WAIT_V(n) asm volatile("s_waitcnt vmcnt(" #n ")" ::: "memory")
; #define WAIT_L(n) asm volatile("s_waitcnt lgkmcnt(" #n ")" ::: "memory")
; #define BAR __builtin_amdgcn_s_barrier()
; #define SCHED __builtin_amdgcn_sched_barrier(0)
; template <int PART  , bool SYNC_FIRST = true>
; __device__ __forceinline__ void kloop_t(const u16* __restrict__ A, int lda, const u16* __restrict__ Bt, int ldb, int K, Acc& acc, const int wv) {
;     ...
;     BAR; WAIT_L(0); MMA(1, 0, At, B0); BAR; SCHED;
;     STAGE(SB(0, 1), Bt, ldb, HALF, t + 2);
;     WAIT_V(6); BAR; MMA(1, 1, At, B1); BAR;
;     LDB(B0, 1, 0); SCHED; LDA(At, 1, 0); STAGE(SA(0, 1), A, lda, HALF, t + 2);
;     WAIT_L(8); BAR; WAIT_L(0); MMA(0, 0, At, B0); BAR; SCHED;
	s_waitcnt lgkmcnt(0)
	s_setprio 0
	s_waitcnt lgkmcnt(0)
	v_mfma_f32_16x16x32_bf16 v[60:63], v[168:171], v[184:187], v[60:63]
	v_mfma_f32_16x16x32_bf16 v[56:59], v[176:179], v[184:187], v[56:59]
	v_mfma_f32_16x16x32_bf16 v[52:55], v[168:171], v[192:195], v[52:55]
	v_mfma_f32_16x16x32_bf16 v[48:51], v[176:179], v[192:195], v[48:51]
	v_mfma_f32_16x16x32_bf16 v[44:47], v[168:171], v[200:203], v[44:47]
	v_mfma_f32_16x16x32_bf16 v[40:43], v[176:179], v[200:203], v[40:43]
	v_mfma_f32_16x16x32_bf16 v[36:39], v[168:171], v[208:211], v[36:39]
	v_mfma_f32_16x16x32_bf16 v[32:35], v[176:179], v[208:211], v[32:35]
	v_mfma_f32_16x16x32_bf16 v[60:63], v[172:175], v[188:191], v[60:63]
	v_mfma_f32_16x16x32_bf16 v[56:59], v[180:183], v[188:191], v[56:59]
	v_mfma_f32_16x16x32_bf16 v[52:55], v[172:175], v[196:199], v[52:55]
	v_mfma_f32_16x16x32_bf16 v[48:51], v[180:183], v[196:199], v[48:51]
	v_mfma_f32_16x16x32_bf16 v[44:47], v[172:175], v[204:207], v[44:47]
	v_mfma_f32_16x16x32_bf16 v[40:43], v[180:183], v[204:207], v[40:43]
	v_mfma_f32_16x16x32_bf16 v[36:39], v[172:175], v[212:215], v[36:39]
	v_mfma_f32_16x16x32_bf16 v[32:35], v[180:183], v[212:215], v[32:35]
	s_setprio 1
	s_barrier
	v_mov_b32_e32 v128, v140
	v_mov_b32_e32 v168, v142
	v_mov_b32_e32 v169, v129
	v_lshl_add_u64 v[170:171], s[42:43], 0, v[128:129]
	v_add_u32_e32 v128, s55, v141
	v_lshl_add_u64 v[170:171], v[170:171], 0, s[24:25]
	v_readfirstlane_b32 s82, v128
	v_add_u32_e32 v128, 0x2000, v128
	s_mov_b32 m0, s82
	v_lshl_add_u64 v[168:169], s[42:43], 0, v[168:169]
	v_readfirstlane_b32 s82, v128
	global_load_lds_dwordx4 v[170:171], off
	v_lshl_add_u64 v[168:169], v[168:169], 0, s[24:25]
	s_mov_b32 m0, s82
	s_nop 0
	global_load_lds_dwordx4 v[168:169], off
	s_waitcnt vmcnt(6)
	s_barrier
	s_setprio 0
	v_mfma_f32_16x16x32_bf16 v[28:31], v[216:219], v[184:187], v[28:31]
	v_mfma_f32_16x16x32_bf16 v[24:27], v[224:227], v[184:187], v[24:27]
	v_mfma_f32_16x16x32_bf16 v[20:23], v[216:219], v[192:195], v[20:23]
	v_mfma_f32_16x16x32_bf16 v[16:19], v[224:227], v[192:195], v[16:19]
	v_mfma_f32_16x16x32_bf16 v[12:15], v[216:219], v[200:203], v[12:15]
	v_mfma_f32_16x16x32_bf16 v[8:11], v[224:227], v[200:203], v[8:11]
	v_mfma_f32_16x16x32_bf16 v[4:7], v[216:219], v[208:211], v[4:7]
	v_mfma_f32_16x16x32_bf16 v[0:3], v[224:227], v[208:211], v[0:3]
	v_mfma_f32_16x16x32_bf16 v[28:31], v[220:223], v[188:191], v[28:31]
	v_mfma_f32_16x16x32_bf16 v[24:27], v[228:231], v[188:191], v[24:27]
	v_mfma_f32_16x16x32_bf16 v[20:23], v[220:223], v[196:199], v[20:23]
	v_mfma_f32_16x16x32_bf16 v[16:19], v[228:231], v[196:199], v[16:19]
	v_mfma_f32_16x16x32_bf16 v[12:15], v[220:223], v[204:207], v[12:15]
	v_mfma_f32_16x16x32_bf16 v[8:11], v[228:231], v[204:207], v[8:11]
	v_mfma_f32_16x16x32_bf16 v[4:7], v[220:223], v[212:215], v[4:7]
	v_mfma_f32_16x16x32_bf16 v[0:3], v[228:231], v[212:215], v[0:3]
	s_setprio 1
	v_add_u32_e32 v168, v152, v154
	v_add_u32_e32 v170, v152, v156
	s_barrier
	v_add_u32_e32 v169, v152, v155
	ds_read_b128 v[176:179], v168
	ds_read_b128 v[180:183], v169
	v_add_u32_e32 v171, v152, v157
	ds_read_b128 v[184:187], v170
	ds_read_b128 v[188:191], v171
	v_mov_b32_e32 v128, v140
	v_mov_b32_e32 v172, v142
	ds_read_b128 v[192:195], v130 offset:32768
	ds_read_b128 v[196:199], v131 offset:32768
	ds_read_b128 v[200:203], v134 offset:32768
	ds_read_b128 v[204:207], v135 offset:32768
	ds_read_b128 v[208:211], v136 offset:32768
	ds_read_b128 v[212:215], v137 offset:32768
	ds_read_b128 v[216:219], v138 offset:32768
	ds_read_b128 v[220:223], v139 offset:32768
	v_mov_b32_e32 v173, v129
	v_lshl_add_u64 v[174:175], s[40:41], 0, v[128:129]
	v_add_u32_e32 v128, 0x4000, v145
	v_lshl_add_u64 v[174:175], v[174:175], 0, s[26:27]
	v_readfirstlane_b32 s82, v128
	v_add_u32_e32 v128, 0x6000, v145
	s_mov_b32 m0, s82
	v_lshl_add_u64 v[172:173], s[40:41], 0, v[172:173]
	v_readfirstlane_b32 s82, v128
	global_load_lds_dwordx4 v[174:175], off
	v_lshl_add_u64 v[172:173], v[172:173], 0, s[26:27]
	s_mov_b32 m0, s82
	s_nop 0
	global_load_lds_dwordx4 v[172:173], off
	s_waitcnt lgkmcnt(8)
	s_barrier
	s_waitcnt lgkmcnt(0)
	s_setprio 0
	s_waitcnt lgkmcnt(0)
	v_mfma_f32_16x16x32_bf16 v[124:127], v[176:179], v[192:195], v[124:127]
	v_mfma_f32_16x16x32_bf16 v[120:123], v[184:187], v[192:195], v[120:123]
	v_mfma_f32_16x16x32_bf16 v[116:119], v[176:179], v[200:203], v[116:119]
	v_mfma_f32_16x16x32_bf16 v[112:115], v[184:187], v[200:203], v[112:115]
	v_mfma_f32_16x16x32_bf16 v[108:111], v[176:179], v[208:211], v[108:111]
	v_mfma_f32_16x16x32_bf16 v[104:107], v[184:187], v[208:211], v[104:107]
	v_mfma_f32_16x16x32_bf16 v[100:103], v[176:179], v[216:219], v[100:103]
	v_mfma_f32_16x16x32_bf16 v[96:99], v[184:187], v[216:219], v[96:99]
	v_mfma_f32_16x16x32_bf16 v[124:127], v[180:183], v[196:199], v[124:127]
	v_mfma_f32_16x16x32_bf16 v[120:123], v[188:191], v[196:199], v[120:123]
	v_mfma_f32_16x16x32_bf16 v[116:119], v[180:183], v[204:207], v[116:119]
	v_mfma_f32_16x16x32_bf16 v[112:115], v[188:191], v[204:207], v[112:115]
	v_mfma_f32_16x16x32_bf16 v[108:111], v[180:183], v[212:215], v[108:111]
	v_mfma_f32_16x16x32_bf16 v[104:107], v[188:191], v[212:215], v[104:107]
	v_mfma_f32_16x16x32_bf16 v[100:103], v[180:183], v[220:223], v[100:103]
	v_mfma_f32_16x16x32_bf16 v[96:99], v[188:191], v[220:223], v[96:99]
	s_setprio 1
	s_barrier
; #define LDA(dst, b, h) for (int m = 0; m < 4; ++m) for (int k = 0; k < 2; ++k) \
;     dst[m][k] = *reinterpret_cast<const bf16x8*>((char*)SA(b, h) + lds_byte(wr * 64 + m * 16 + fr, k * 32 + fq * 8))
; #define LDB(dst, b, h) for (int n = 0; n < 2; ++n) for (int k = 0; k < 2; ++k) \
;     dst[n][k] = *reinterpret_cast<const bf16x8*>((char*)SB(b, h) + lds_byte(wc * 32 + n * 16 + fr, k * 32 + fq * 8))
; #define MMA(ai, bj, At_, Bt_) do { __builtin_amdgcn_s_setprio(1); \
;     for (int m = 0; m < 4; ++m) for (int n = 0; n < 2; ++n) for (int k = 0; k < 2; ++k) \
;       acc[ai][bj][m][n] = MFMA16(Bt_[n][k], At_[m][k], acc[ai][bj][m][n]); \
;     __builtin_amdgcn_s_setprio(0); } while (0)
; #define WAIT_V(n) asm volatile("s_waitcnt vmcnt(" #n ")" ::: "memory")
; #define WAIT_L(n) asm volatile("s_waitcnt lgkmcnt(" #n ")" ::: "memory")
; #define BAR __builtin_amdgcn_s_barrier()
; #define SCHED __builtin_amdgcn_sched_barrier(0)
; template <int PART  , bool SYNC_FIRST = true>
; __device__ __forceinline__ void kloop_t(const u16* __restrict__ A, int lda, const u16* __restrict__ Bt, int ldb, int K, Acc& acc, const int wv) {
;     ...
;     LDB(B1, 1, 1); STAGE(SB(1, 0), Bt, ldb, 0, t + 3);
;     BAR; WAIT_L(0); MMA(0, 1, At, B1); BAR;
;     LDA(At, 1, 1); STAGE(SA(1, 0), A, lda, 0, t + 3);
;     BAR; WAIT_L(0); MMA(1, 0, At, B0); BAR; SCHED;
;     STAGE(SB(1, 1), Bt, ldb, HALF, t + 3);
;     WAIT_V(6); BAR; MMA(1, 1, At, B1); BAR;
;   }
	v_add_u32_e32 v172, v153, v154
	v_add_u32_e32 v174, v153, v156
	v_mov_b32_e32 v128, v140
	v_mov_b32_e32 v240, v142
	v_add_u32_e32 v173, v153, v155
	ds_read_b128 v[224:227], v172
	ds_read_b128 v[228:231], v173
	v_add_u32_e32 v175, v153, v157
	ds_read_b128 v[232:235], v174
	ds_read_b128 v[236:239], v175
	v_readfirstlane_b32 s82, v143
	v_lshl_add_u64 v[242:243], s[42:43], 0, v[128:129]
	v_mov_b32_e32 v241, v129
	v_lshl_add_u64 v[242:243], v[242:243], 0, s[28:29]
	s_mov_b32 m0, s82
	v_lshl_add_u64 v[240:241], s[42:43], 0, v[240:241]
	v_readfirstlane_b32 s82, v144
	global_load_lds_dwordx4 v[242:243], off
	v_lshl_add_u64 v[240:241], v[240:241], 0, s[28:29]
	s_mov_b32 m0, s82
	s_nop 0
	global_load_lds_dwordx4 v[240:241], off
	s_barrier
	s_waitcnt lgkmcnt(0)
	s_setprio 0
	s_waitcnt lgkmcnt(0)
	v_mfma_f32_16x16x32_bf16 v[92:95], v[224:227], v[192:195], v[92:95]
	v_mfma_f32_16x16x32_bf16 v[88:91], v[232:235], v[192:195], v[88:91]
	v_mfma_f32_16x16x32_bf16 v[84:87], v[224:227], v[200:203], v[84:87]
	v_mfma_f32_16x16x32_bf16 v[80:83], v[232:235], v[200:203], v[80:83]
	v_mfma_f32_16x16x32_bf16 v[76:79], v[224:227], v[208:211], v[76:79]
	v_mfma_f32_16x16x32_bf16 v[72:75], v[232:235], v[208:211], v[72:75]
	v_mfma_f32_16x16x32_bf16 v[68:71], v[224:227], v[216:219], v[68:71]
	v_mfma_f32_16x16x32_bf16 v[64:67], v[232:235], v[216:219], v[64:67]
	v_mfma_f32_16x16x32_bf16 v[92:95], v[228:231], v[196:199], v[92:95]
	v_mfma_f32_16x16x32_bf16 v[88:91], v[236:239], v[196:199], v[88:91]
	v_mfma_f32_16x16x32_bf16 v[84:87], v[228:231], v[204:207], v[84:87]
	v_mfma_f32_16x16x32_bf16 v[80:83], v[236:239], v[204:207], v[80:83]
	v_mfma_f32_16x16x32_bf16 v[76:79], v[228:231], v[212:215], v[76:79]
	v_mfma_f32_16x16x32_bf16 v[72:75], v[236:239], v[212:215], v[72:75]
	v_mfma_f32_16x16x32_bf16 v[68:71], v[228:231], v[220:223], v[68:71]
	v_mfma_f32_16x16x32_bf16 v[64:67], v[236:239], v[220:223], v[64:67]
	s_setprio 1
	v_mov_b32_e32 v128, v140
	v_mov_b32_e32 v240, v142
	s_barrier
	ds_read_b128 v[192:195], v130 offset:49152
	ds_read_b128 v[196:199], v131 offset:49152
	ds_read_b128 v[200:203], v134 offset:49152
	ds_read_b128 v[204:207], v135 offset:49152
	ds_read_b128 v[208:211], v136 offset:49152
	ds_read_b128 v[212:215], v137 offset:49152
	ds_read_b128 v[216:219], v138 offset:49152
	ds_read_b128 v[220:223], v139 offset:49152
	v_readfirstlane_b32 s82, v146
	v_lshl_add_u64 v[242:243], s[40:41], 0, v[128:129]
	v_mov_b32_e32 v241, v129
	v_lshl_add_u64 v[242:243], v[242:243], 0, s[30:31]
	s_mov_b32 m0, s82
	v_lshl_add_u64 v[240:241], s[40:41], 0, v[240:241]
	v_readfirstlane_b32 s40, v147
	global_load_lds_dwordx4 v[242:243], off
	v_lshl_add_u64 v[240:241], v[240:241], 0, s[30:31]
	s_mov_b32 m0, s40
	s_nop 0
	global_load_lds_dwordx4 v[240:241], off
	s_barrier
	s_waitcnt lgkmcnt(0)
	s_setprio 0
	s_waitcnt lgkmcnt(0)
	v_mfma_f32_16x16x32_bf16 v[60:63], v[176:179], v[192:195], v[60:63]
	v_mfma_f32_16x16x32_bf16 v[56:59], v[184:187], v[192:195], v[56:59]
	v_mfma_f32_16x16x32_bf16 v[52:55], v[176:179], v[200:203], v[52:55]
	v_mfma_f32_16x16x32_bf16 v[48:51], v[184:187], v[200:203], v[48:51]
	v_mfma_f32_16x16x32_bf16 v[44:47], v[176:179], v[208:211], v[44:47]
	v_mfma_f32_16x16x32_bf16 v[40:43], v[184:187], v[208:211], v[40:43]
	v_mfma_f32_16x16x32_bf16 v[36:39], v[176:179], v[216:219], v[36:39]
	v_mfma_f32_16x16x32_bf16 v[32:35], v[184:187], v[216:219], v[32:35]
	v_mfma_f32_16x16x32_bf16 v[60:63], v[180:183], v[196:199], v[60:63]
	v_mfma_f32_16x16x32_bf16 v[56:59], v[188:191], v[196:199], v[56:59]
	v_mfma_f32_16x16x32_bf16 v[52:55], v[180:183], v[204:207], v[52:55]
	v_mfma_f32_16x16x32_bf16 v[48:51], v[188:191], v[204:207], v[48:51]
	v_mfma_f32_16x16x32_bf16 v[44:47], v[180:183], v[212:215], v[44:47]
	v_mfma_f32_16x16x32_bf16 v[40:43], v[188:191], v[212:215], v[40:43]
	v_mfma_f32_16x16x32_bf16 v[36:39], v[180:183], v[220:223], v[36:39]
	v_mfma_f32_16x16x32_bf16 v[32:35], v[188:191], v[220:223], v[32:35]
	s_setprio 1
	s_barrier
	v_mov_b32_e32 v128, v140
	v_mov_b32_e32 v176, v142
	v_readfirstlane_b32 s40, v148
	v_lshl_add_u64 v[178:179], s[42:43], 0, v[128:129]
	v_mov_b32_e32 v177, v129
	v_lshl_add_u64 v[178:179], v[178:179], 0, s[34:35]
	s_mov_b32 m0, s40
	v_lshl_add_u64 v[176:177], s[42:43], 0, v[176:177]
	v_readfirstlane_b32 s40, v149
	global_load_lds_dwordx4 v[178:179], off
	v_lshl_add_u64 v[176:177], v[176:177], 0, s[34:35]
	s_mov_b32 m0, s40
	s_nop 0
	global_load_lds_dwordx4 v[176:177], off
	s_waitcnt vmcnt(6)
	s_barrier
	s_setprio 0
	v_mfma_f32_16x16x32_bf16 v[28:31], v[224:227], v[192:195], v[28:31]
	v_mfma_f32_16x16x32_bf16 v[24:27], v[232:235], v[192:195], v[24:27]
	v_mfma_f32_16x16x32_bf16 v[20:23], v[224:227], v[200:203], v[20:23]
	v_mfma_f32_16x16x32_bf16 v[16:19], v[232:235], v[200:203], v[16:19]
	v_mfma_f32_16x16x32_bf16 v[12:15], v[224:227], v[208:211], v[12:15]
	v_mfma_f32_16x16x32_bf16 v[8:11], v[232:235], v[208:211], v[8:11]
	v_mfma_f32_16x16x32_bf16 v[4:7], v[224:227], v[216:219], v[4:7]
	v_mfma_f32_16x16x32_bf16 v[0:3], v[232:235], v[216:219], v[0:3]
	v_mfma_f32_16x16x32_bf16 v[28:31], v[228:231], v[196:199], v[28:31]
	v_mfma_f32_16x16x32_bf16 v[24:27], v[236:239], v[196:199], v[24:27]
	v_mfma_f32_16x16x32_bf16 v[20:23], v[228:231], v[204:207], v[20:23]
	v_mfma_f32_16x16x32_bf16 v[16:19], v[236:239], v[204:207], v[16:19]
	v_mfma_f32_16x16x32_bf16 v[12:15], v[228:231], v[212:215], v[12:15]
	v_mfma_f32_16x16x32_bf16 v[8:11], v[236:239], v[212:215], v[8:11]
	v_mfma_f32_16x16x32_bf16 v[4:7], v[228:231], v[220:223], v[4:7]
	v_mfma_f32_16x16x32_bf16 v[0:3], v[236:239], v[220:223], v[0:3]
	s_setprio 1
	s_add_i32 s81, s81, 2
	s_add_u32 s38, s38, 0x100
	s_addc_u32 s39, s39, 0
	s_cmp_lt_u32 s81, 12
	s_barrier
; #define LDA(dst, b, h) for (int m = 0; m < 4; ++m) for (int k = 0; k < 2; ++k) \
;     dst[m][k] = *reinterpret_cast<const bf16x8*>((char*)SA(b, h) + lds_byte(wr * 64 + m * 16 + fr, k * 32 + fq * 8))
; #define LDB(dst, b, h) for (int n = 0; n < 2; ++n) for (int k = 0; k < 2; ++k) \
;     dst[n][k] = *reinterpret_cast<const bf16x8*>((char*)SB(b, h) + lds_byte(wc * 32 + n * 16 + fr, k * 32 + fq * 8))
; #define MMA(ai, bj, At_, Bt_) do { __builtin_amdgcn_s_setprio(1); \
;     for (int m = 0; m < 4; ++m) for (int n = 0; n < 2; ++n) for (int k = 0; k < 2; ++k) \
;       acc[ai][bj][m][n] = MFMA16(Bt_[n][k], At_[m][k], acc[ai][bj][m][n]); \
;     __builtin_amdgcn_s_setprio(0); } while (0)
; #define WAIT_V(n) asm volatile("s_waitcnt vmcnt(" #n ")" ::: "memory")
; #define WAIT_L(n) asm volatile("s_waitcnt lgkmcnt(" #n ")" ::: "memory")
; #define BAR __builtin_amdgcn_s_barrier()
; template <int PART  , bool SYNC_FIRST = true>
; __device__ __forceinline__ void kloop_t(const u16* __restrict__ A, int lda, const u16* __restrict__ Bt, int ldb, int K, Acc& acc, const int wv) {
;     ...
;   }
;   { LDB(B0, 0, 0); LDA(At, 0, 0); STAGE(SA(1, 1), A, lda, HALF, nt - 1);
;     BAR; WAIT_L(0); MMA(0, 0, At, B0); BAR;
;     LDB(B1, 0, 1); BAR; WAIT_L(0); MMA(0, 1, At, B1); BAR;
;     LDA(At, 0, 1); WAIT_V(4); BAR; WAIT_L(0); MMA(1, 0, At, B0); MMA(1, 1, At, B1); BAR; }
	s_cbranch_scc1 .LBB0_1069
	s_add_u32 s36, s36, 0x40780
	v_readfirstlane_b32 s38, v162
	s_addc_u32 s37, s37, 0
	s_mov_b32 m0, s38
	v_readfirstlane_b32 s38, v163
	ds_read_b128 v[144:147], v158
	ds_read_b128 v[148:151], v159
	ds_read_b128 v[152:155], v160
	ds_read_b128 v[156:159], v161
	ds_read_b128 v[176:179], v130
	ds_read_b128 v[180:183], v131
	ds_read_b128 v[184:187], v134
	ds_read_b128 v[188:191], v135
	ds_read_b128 v[192:195], v136
	ds_read_b128 v[196:199], v137
	ds_read_b128 v[200:203], v138
	ds_read_b128 v[204:207], v139
	s_nop 0
	global_load_lds_dwordx4 v140, s[36:37]
	s_mov_b32 m0, s38
	s_nop 0
	global_load_lds_dwordx4 v142, s[36:37]
	s_barrier
	s_waitcnt lgkmcnt(0)
	s_setprio 0
	s_waitcnt lgkmcnt(0)
	v_mfma_f32_16x16x32_bf16 v[124:127], v[144:147], v[176:179], v[124:127]
	v_mfma_f32_16x16x32_bf16 v[120:123], v[152:155], v[176:179], v[120:123]
	v_mfma_f32_16x16x32_bf16 v[116:119], v[144:147], v[184:187], v[116:119]
	v_mfma_f32_16x16x32_bf16 v[112:115], v[152:155], v[184:187], v[112:115]
	v_mfma_f32_16x16x32_bf16 v[100:103], v[144:147], v[200:203], v[100:103]
	v_mfma_f32_16x16x32_bf16 v[96:99], v[152:155], v[200:203], v[96:99]
	v_mfma_f32_16x16x32_bf16 v[124:127], v[148:151], v[180:183], v[124:127]
	v_mfma_f32_16x16x32_bf16 v[120:123], v[156:159], v[180:183], v[120:123]
	v_mfma_f32_16x16x32_bf16 v[116:119], v[148:151], v[188:191], v[116:119]
	v_mfma_f32_16x16x32_bf16 v[112:115], v[156:159], v[188:191], v[112:115]
	v_mfma_f32_16x16x32_bf16 v[108:111], v[144:147], v[192:195], v[108:111]
	v_mfma_f32_16x16x32_bf16 v[104:107], v[152:155], v[192:195], v[104:107]
	v_mfma_f32_16x16x32_bf16 v[100:103], v[148:151], v[204:207], v[100:103]
	v_mfma_f32_16x16x32_bf16 v[96:99], v[156:159], v[204:207], v[96:99]
	v_mfma_f32_16x16x32_bf16 v[140:143], v[148:151], v[196:199], v[108:111]
	v_mfma_f32_16x16x32_bf16 v[160:163], v[156:159], v[196:199], v[104:107]
	s_setprio 1
	s_barrier
	s_nop 1
	ds_read_b128 v[104:107], v164
	ds_read_b128 v[108:111], v165
	ds_read_b128 v[208:211], v166
	ds_read_b128 v[164:167], v167
	s_barrier
	s_waitcnt lgkmcnt(0)
	s_setprio 0
	s_waitcnt lgkmcnt(0)
	v_mfma_f32_16x16x32_bf16 v[84:87], v[104:107], v[184:187], v[84:87]
	v_mfma_f32_16x16x32_bf16 v[80:83], v[208:211], v[184:187], v[80:83]
	v_mfma_f32_16x16x32_bf16 v[68:71], v[104:107], v[200:203], v[68:71]
	v_mfma_f32_16x16x32_bf16 v[64:67], v[208:211], v[200:203], v[64:67]
	v_mfma_f32_16x16x32_bf16 v[92:95], v[104:107], v[176:179], v[92:95]
	v_mfma_f32_16x16x32_bf16 v[88:91], v[208:211], v[176:179], v[88:91]
	v_mfma_f32_16x16x32_bf16 v[84:87], v[108:111], v[188:191], v[84:87]
	v_mfma_f32_16x16x32_bf16 v[80:83], v[164:167], v[188:191], v[80:83]
	v_mfma_f32_16x16x32_bf16 v[76:79], v[104:107], v[192:195], v[76:79]
	v_mfma_f32_16x16x32_bf16 v[72:75], v[208:211], v[192:195], v[72:75]
	v_mfma_f32_16x16x32_bf16 v[68:71], v[108:111], v[204:207], v[68:71]
	v_mfma_f32_16x16x32_bf16 v[64:67], v[164:167], v[204:207], v[64:67]
	v_mfma_f32_16x16x32_bf16 v[212:215], v[108:111], v[180:183], v[92:95]
	v_mfma_f32_16x16x32_bf16 v[176:179], v[164:167], v[180:183], v[88:91]
	v_mfma_f32_16x16x32_bf16 v[180:183], v[108:111], v[196:199], v[76:79]
	v_mfma_f32_16x16x32_bf16 v[184:187], v[164:167], v[196:199], v[72:75]
	s_setprio 1
	s_barrier
	s_nop 0
	ds_read_b128 v[72:75], v130 offset:16384
	ds_read_b128 v[76:79], v131 offset:16384
	ds_read_b128 v[88:91], v134 offset:16384
	ds_read_b128 v[92:95], v135 offset:16384
	ds_read_b128 v[188:191], v136 offset:16384
	ds_read_b128 v[192:195], v137 offset:16384
	ds_read_b128 v[196:199], v138 offset:16384
	ds_read_b128 v[200:203], v139 offset:16384
	s_waitcnt vmcnt(4)
	s_barrier
	s_waitcnt lgkmcnt(0)
	s_setprio 0
	s_waitcnt lgkmcnt(0)
	v_mfma_f32_16x16x32_bf16 v[60:63], v[144:147], v[72:75], v[60:63]
	v_mfma_f32_16x16x32_bf16 v[56:59], v[152:155], v[72:75], v[56:59]
	v_mfma_f32_16x16x32_bf16 v[52:55], v[144:147], v[88:91], v[52:55]
	v_mfma_f32_16x16x32_bf16 v[48:51], v[152:155], v[88:91], v[48:51]
	v_mfma_f32_16x16x32_bf16 v[36:39], v[144:147], v[196:199], v[36:39]
	v_mfma_f32_16x16x32_bf16 v[32:35], v[152:155], v[196:199], v[32:35]
	v_mfma_f32_16x16x32_bf16 v[60:63], v[148:151], v[76:79], v[60:63]
	v_mfma_f32_16x16x32_bf16 v[56:59], v[156:159], v[76:79], v[56:59]
	v_mfma_f32_16x16x32_bf16 v[52:55], v[148:151], v[92:95], v[52:55]
	v_mfma_f32_16x16x32_bf16 v[48:51], v[156:159], v[92:95], v[48:51]
	v_mfma_f32_16x16x32_bf16 v[44:47], v[144:147], v[188:191], v[44:47]
	v_mfma_f32_16x16x32_bf16 v[40:43], v[152:155], v[188:191], v[40:43]
	v_mfma_f32_16x16x32_bf16 v[36:39], v[148:151], v[200:203], v[36:39]
	v_mfma_f32_16x16x32_bf16 v[32:35], v[156:159], v[200:203], v[32:35]
	v_mfma_f32_16x16x32_bf16 v[204:207], v[148:151], v[192:195], v[44:47]
	v_mfma_f32_16x16x32_bf16 v[216:219], v[156:159], v[192:195], v[40:43]
	s_setprio 1
	s_setprio 0
	v_mfma_f32_16x16x32_bf16 v[20:23], v[104:107], v[88:91], v[20:23]
	v_mfma_f32_16x16x32_bf16 v[16:19], v[208:211], v[88:91], v[16:19]
	v_mfma_f32_16x16x32_bf16 v[4:7], v[104:107], v[196:199], v[4:7]
	v_mfma_f32_16x16x32_bf16 v[0:3], v[208:211], v[196:199], v[0:3]
	v_mfma_f32_16x16x32_bf16 v[28:31], v[104:107], v[72:75], v[28:31]
	v_mfma_f32_16x16x32_bf16 v[24:27], v[208:211], v[72:75], v[24:27]
	v_mfma_f32_16x16x32_bf16 v[20:23], v[108:111], v[92:95], v[20:23]
	v_mfma_f32_16x16x32_bf16 v[16:19], v[164:167], v[92:95], v[16:19]
	v_mfma_f32_16x16x32_bf16 v[12:15], v[104:107], v[188:191], v[12:15]
	v_mfma_f32_16x16x32_bf16 v[8:11], v[208:211], v[188:191], v[8:11]
	v_mfma_f32_16x16x32_bf16 v[4:7], v[108:111], v[200:203], v[4:7]
	v_mfma_f32_16x16x32_bf16 v[0:3], v[164:167], v[200:203], v[0:3]
	v_mfma_f32_16x16x32_bf16 v[144:147], v[108:111], v[76:79], v[28:31]
	v_mfma_f32_16x16x32_bf16 v[148:151], v[164:167], v[76:79], v[24:27]
	v_mfma_f32_16x16x32_bf16 v[152:155], v[108:111], v[192:195], v[12:15]
	v_mfma_f32_16x16x32_bf16 v[156:159], v[164:167], v[192:195], v[8:11]
	s_setprio 1
	s_barrier
; #define LDA(dst, b, h) for (int m = 0; m < 4; ++m) for (int k = 0; k < 2; ++k) \
;     dst[m][k] = *reinterpret_cast<const bf16x8*>((char*)SA(b, h) + lds_byte(wr * 64 + m * 16 + fr, k * 32 + fq * 8))
; #define LDB(dst, b, h) for (int n = 0; n < 2; ++n) for (int k = 0; k < 2; ++k) \
;     dst[n][k] = *reinterpret_cast<const bf16x8*>((char*)SB(b, h) + lds_byte(wc * 32 + n * 16 + fr, k * 32 + fq * 8))
; #define MMA(ai, bj, At_, Bt_) do { __builtin_amdgcn_s_setprio(1); \
;     for (int m = 0; m < 4; ++m) for (int n = 0; n < 2; ++n) for (int k = 0; k < 2; ++k) \
;       acc[ai][bj][m][n] = MFMA16(Bt_[n][k], At_[m][k], acc[ai][bj][m][n]); \
;     __builtin_amdgcn_s_setprio(0); } while (0)
; #define WAIT_V(n) asm volatile("s_waitcnt vmcnt(" #n ")" ::: "memory")
; #define WAIT_L(n) asm volatile("s_waitcnt lgkmcnt(" #n ")" ::: "memory")
; #define BAR __builtin_amdgcn_s_barrier()
; template <int PART  , bool SYNC_FIRST = true>
; __device__ __forceinline__ void kloop_t(const u16* __restrict__ A, int lda, const u16* __restrict__ Bt, int ldb, int K, Acc& acc, const int wv) {
;     ...
;   { LDB(B0, 1, 0); LDA(At, 1, 0); WAIT_V(2); BAR; WAIT_L(0); MMA(0, 0, At, B0); BAR;
;     LDB(B1, 1, 1); WAIT_V(0); BAR; WAIT_L(0); MMA(0, 1, At, B1); BAR;
;     LDA(At, 1, 1); BAR; WAIT_L(0); MMA(1, 0, At, B0); MMA(1, 1, At, B1); BAR; }
;   if (wr == 0) BAR;
	s_nop 0
	ds_read_b128 v[8:11], v168
	ds_read_b128 v[12:15], v169
	ds_read_b128 v[164:167], v170
	ds_read_b128 v[168:171], v171
	ds_read_b128 v[24:27], v130 offset:32768
	ds_read_b128 v[28:31], v131 offset:32768
	ds_read_b128 v[40:43], v134 offset:32768
	ds_read_b128 v[44:47], v135 offset:32768
	ds_read_b128 v[188:191], v136 offset:32768
	ds_read_b128 v[192:195], v137 offset:32768
	ds_read_b128 v[196:199], v138 offset:32768
	ds_read_b128 v[200:203], v139 offset:32768
	s_waitcnt vmcnt(2)
	s_barrier
	s_waitcnt lgkmcnt(0)
	s_setprio 0
	s_waitcnt lgkmcnt(0)
	v_mfma_f32_16x16x32_bf16 v[72:75], v[8:11], v[24:27], v[124:127]
	v_mfma_f32_16x16x32_bf16 v[124:127], v[12:15], v[28:31], v[72:75]
	v_mfma_f32_16x16x32_bf16 v[72:75], v[164:167], v[24:27], v[120:123]
	v_mfma_f32_16x16x32_bf16 v[120:123], v[168:171], v[28:31], v[72:75]
	v_mfma_f32_16x16x32_bf16 v[72:75], v[8:11], v[40:43], v[116:119]
	v_mfma_f32_16x16x32_bf16 v[108:111], v[12:15], v[44:47], v[72:75]
	v_mfma_f32_16x16x32_bf16 v[72:75], v[164:167], v[40:43], v[112:115]
	v_mfma_f32_16x16x32_bf16 v[104:107], v[168:171], v[44:47], v[72:75]
	v_mfma_f32_16x16x32_bf16 v[72:75], v[8:11], v[188:191], v[140:143]
	v_mfma_f32_16x16x32_bf16 v[92:95], v[12:15], v[192:195], v[72:75]
	v_mfma_f32_16x16x32_bf16 v[72:75], v[164:167], v[188:191], v[160:163]
	v_mfma_f32_16x16x32_bf16 v[88:91], v[168:171], v[192:195], v[72:75]
	v_mfma_f32_16x16x32_bf16 v[72:75], v[8:11], v[196:199], v[100:103]
	v_mfma_f32_16x16x32_bf16 v[76:79], v[12:15], v[200:203], v[72:75]
	v_mfma_f32_16x16x32_bf16 v[72:75], v[164:167], v[196:199], v[96:99]
	v_mfma_f32_16x16x32_bf16 v[72:75], v[168:171], v[200:203], v[72:75]
	s_setprio 1
	s_barrier
	ds_read_b128 v[140:143], v172
	ds_read_b128 v[160:163], v173
	ds_read_b128 v[208:211], v174
	ds_read_b128 v[172:175], v175
	s_waitcnt vmcnt(0)
	s_barrier
	s_waitcnt lgkmcnt(0)
	s_setprio 0
	s_waitcnt lgkmcnt(0)
	v_mfma_f32_16x16x32_bf16 v[96:99], v[140:143], v[24:27], v[212:215]
	v_mfma_f32_16x16x32_bf16 v[24:27], v[208:211], v[24:27], v[176:179]
	v_mfma_f32_16x16x32_bf16 v[112:115], v[172:175], v[28:31], v[24:27]
	v_mfma_f32_16x16x32_bf16 v[24:27], v[140:143], v[40:43], v[84:87]
	v_mfma_f32_16x16x32_bf16 v[100:103], v[160:163], v[44:47], v[24:27]
	v_mfma_f32_16x16x32_bf16 v[24:27], v[208:211], v[40:43], v[80:83]
	v_mfma_f32_16x16x32_bf16 v[116:119], v[160:163], v[28:31], v[96:99]
	v_mfma_f32_16x16x32_bf16 v[96:99], v[172:175], v[44:47], v[24:27]
	v_mfma_f32_16x16x32_bf16 v[24:27], v[140:143], v[188:191], v[180:183]
	v_mfma_f32_16x16x32_bf16 v[84:87], v[160:163], v[192:195], v[24:27]
	v_mfma_f32_16x16x32_bf16 v[24:27], v[208:211], v[188:191], v[184:187]
	v_mfma_f32_16x16x32_bf16 v[80:83], v[172:175], v[192:195], v[24:27]
	v_mfma_f32_16x16x32_bf16 v[24:27], v[140:143], v[196:199], v[68:71]
	v_mfma_f32_16x16x32_bf16 v[68:71], v[160:163], v[200:203], v[24:27]
	v_mfma_f32_16x16x32_bf16 v[24:27], v[208:211], v[196:199], v[64:67]
	v_mfma_f32_16x16x32_bf16 v[64:67], v[172:175], v[200:203], v[24:27]
	s_setprio 1
	s_barrier
	ds_read_b128 v[176:179], v130 offset:49152
	ds_read_b128 v[180:183], v131 offset:49152
	ds_read_b128 v[184:187], v134 offset:49152
	ds_read_b128 v[188:191], v135 offset:49152
	ds_read_b128 v[192:195], v136 offset:49152
	ds_read_b128 v[134:137], v137 offset:49152
	ds_read_b128 v[196:199], v138 offset:49152
	ds_read_b128 v[200:203], v139 offset:49152
	s_barrier
	s_waitcnt lgkmcnt(0)
	s_setprio 0
	s_waitcnt lgkmcnt(0)
	v_mfma_f32_16x16x32_bf16 v[24:27], v[8:11], v[176:179], v[60:63]
	v_mfma_f32_16x16x32_bf16 v[60:63], v[12:15], v[180:183], v[24:27]
	v_mfma_f32_16x16x32_bf16 v[24:27], v[164:167], v[176:179], v[56:59]
	v_mfma_f32_16x16x32_bf16 v[56:59], v[168:171], v[180:183], v[24:27]
	v_mfma_f32_16x16x32_bf16 v[24:27], v[8:11], v[184:187], v[52:55]
	v_mfma_f32_16x16x32_bf16 v[44:47], v[12:15], v[188:191], v[24:27]
	v_mfma_f32_16x16x32_bf16 v[24:27], v[164:167], v[184:187], v[48:51]
	v_mfma_f32_16x16x32_bf16 v[40:43], v[168:171], v[188:191], v[24:27]
	v_mfma_f32_16x16x32_bf16 v[24:27], v[8:11], v[192:195], v[204:207]
	v_mfma_f32_16x16x32_bf16 v[8:11], v[8:11], v[196:199], v[36:39]
	v_mfma_f32_16x16x32_bf16 v[28:31], v[12:15], v[134:137], v[24:27]
	v_mfma_f32_16x16x32_bf16 v[24:27], v[164:167], v[192:195], v[216:219]
	v_mfma_f32_16x16x32_bf16 v[12:15], v[12:15], v[200:203], v[8:11]
	v_mfma_f32_16x16x32_bf16 v[8:11], v[164:167], v[196:199], v[32:35]
	v_mfma_f32_16x16x32_bf16 v[24:27], v[168:171], v[134:137], v[24:27]
	v_mfma_f32_16x16x32_bf16 v[8:11], v[168:171], v[200:203], v[8:11]
	s_setprio 1
	s_setprio 0
	v_mfma_f32_16x16x32_bf16 v[32:35], v[140:143], v[176:179], v[144:147]
	v_mfma_f32_16x16x32_bf16 v[52:55], v[160:163], v[180:183], v[32:35]
	v_mfma_f32_16x16x32_bf16 v[32:35], v[208:211], v[176:179], v[148:151]
	v_mfma_f32_16x16x32_bf16 v[16:19], v[208:211], v[184:187], v[16:19]
	v_mfma_f32_16x16x32_bf16 v[48:51], v[172:175], v[180:183], v[32:35]
	v_mfma_f32_16x16x32_bf16 v[20:23], v[140:143], v[184:187], v[20:23]
	v_mfma_f32_16x16x32_bf16 v[32:35], v[172:175], v[188:191], v[16:19]
	v_mfma_f32_16x16x32_bf16 v[16:19], v[140:143], v[192:195], v[152:155]
	v_mfma_f32_16x16x32_bf16 v[36:39], v[160:163], v[188:191], v[20:23]
	v_mfma_f32_16x16x32_bf16 v[20:23], v[160:163], v[134:137], v[16:19]
	v_mfma_f32_16x16x32_bf16 v[16:19], v[208:211], v[192:195], v[156:159]
	v_mfma_f32_16x16x32_bf16 v[4:7], v[140:143], v[196:199], v[4:7]
	v_mfma_f32_16x16x32_bf16 v[0:3], v[208:211], v[196:199], v[0:3]
	v_mfma_f32_16x16x32_bf16 v[16:19], v[172:175], v[134:137], v[16:19]
	v_mfma_f32_16x16x32_bf16 v[4:7], v[160:163], v[200:203], v[4:7]
	v_mfma_f32_16x16x32_bf16 v[0:3], v[172:175], v[200:203], v[0:3]
	s_setprio 1
	s_andn2_b64 vcc, exec, s[14:15]
	s_barrier
	s_cbranch_vccnz .LBB0_1072
	s_barrier

; #define LDA(dst, b, h) for (int m = 0; m < 4; ++m) for (int k = 0; k < 2; ++k) \
;     dst[m][k] = *reinterpret_cast<const bf16x8*>((char*)SA(b, h) + lds_byte(wr * 64 + m * 16 + fr, k * 32 + fq * 8))
; #define LDB(dst, b, h) for (int n = 0; n < 2; ++n) for (int k = 0; k < 2; ++k) \
;     dst[n][k] = *reinterpret_cast<const bf16x8*>((char*)SB(b, h) + lds_byte(wc * 32 + n * 16 + fr, k * 32 + fq * 8))
; #define MMA(ai, bj, At_, Bt_) do { __builtin_amdgcn_s_setprio(1); \
;     for (int m = 0; m < 4; ++m) for (int n = 0; n < 2; ++n) for (int k = 0; k < 2; ++k) \
;       acc[ai][bj][m][n] = MFMA16(Bt_[n][k], At_[m][k], acc[ai][bj][m][n]); \
;     __builtin_amdgcn_s_setprio(0); } while (0)
; #define WAIT_L(n) asm volatile("s_waitcnt lgkmcnt(" #n ")" ::: "memory")
; #define BAR __builtin_amdgcn_s_barrier()
; #define SCHED __builtin_amdgcn_sched_barrier(0)
; template <int PART  , bool SYNC_FIRST = true>
; __device__ __forceinline__ void kloop_t(const u16* __restrict__ A, int lda, const u16* __restrict__ Bt, int ldb, int K, Acc& acc, const int wv) {
;     ...
;     LDB(B0, 0, 0); SCHED; LDA(At, 0, 0); STAGE(SA(1, 1), A, lda, HALF, t + 1);
;     WAIT_L(8); BAR; WAIT_L(0); MMA(0, 0, At, B0); BAR; SCHED;
;     LDB(B1, 0, 1); STAGE(SB(0, 0), Bt, ldb, 0, t + 2);
;     BAR; WAIT_L(0); MMA(0, 1, At, B1); BAR;
;     LDA(At, 0, 1); STAGE(SA(0, 0), A, lda, 0, t + 2);
.LBB0_1139:
	v_add_u32_e32 v164, v156, v160
	v_add_u32_e32 v166, v156, v162
	v_add_u32_e32 v165, v156, v161
	ds_read_b128 v[174:177], v164
	ds_read_b128 v[178:181], v165
	v_add_u32_e32 v167, v156, v163
	ds_read_b128 v[182:185], v166
	ds_read_b128 v[186:189], v167
	s_add_u32 s44, s42, s56
	v_mov_b32_e32 v170, v131
	v_mov_b32_e32 v128, v130
	s_addc_u32 s45, s43, 0
	ds_read_b128 v[190:193], v132
	ds_read_b128 v[194:197], v133
	ds_read_b128 v[198:201], v134
	ds_read_b128 v[202:205], v135
	ds_read_b128 v[206:209], v136
	ds_read_b128 v[210:213], v137
	ds_read_b128 v[214:217], v138
	ds_read_b128 v[218:221], v139
	v_mov_b32_e32 v171, v129
	v_lshl_add_u64 v[168:169], s[44:45], 0, v[128:129]
	v_lshl_add_u64 v[172:173], v[168:169], 0, s[24:25]
	v_add_u32_e32 v168, 0xc000, v144
	v_add_u32_e32 v169, 0xe000, v144
	v_readfirstlane_b32 s52, v168
	s_mov_b32 m0, s52
	v_lshl_add_u64 v[170:171], s[44:45], 0, v[170:171]
	v_readfirstlane_b32 s52, v169
	global_load_lds_dwordx4 v[172:173], off
	v_lshl_add_u64 v[170:171], v[170:171], 0, s[24:25]
	s_mov_b32 m0, s52
	s_nop 0
	global_load_lds_dwordx4 v[170:171], off
	s_waitcnt lgkmcnt(8)
	s_barrier
	s_waitcnt lgkmcnt(0)
	s_setprio 0
	s_waitcnt lgkmcnt(0)
	v_mfma_f32_16x16x32_bf16 v[124:127], v[174:177], v[190:193], v[124:127]
	v_mfma_f32_16x16x32_bf16 v[120:123], v[182:185], v[190:193], v[120:123]
	v_mfma_f32_16x16x32_bf16 v[116:119], v[174:177], v[198:201], v[116:119]
	v_mfma_f32_16x16x32_bf16 v[112:115], v[182:185], v[198:201], v[112:115]
	v_mfma_f32_16x16x32_bf16 v[108:111], v[174:177], v[206:209], v[108:111]
	v_mfma_f32_16x16x32_bf16 v[104:107], v[182:185], v[206:209], v[104:107]
	v_mfma_f32_16x16x32_bf16 v[100:103], v[174:177], v[214:217], v[100:103]
	v_mfma_f32_16x16x32_bf16 v[96:99], v[182:185], v[214:217], v[96:99]
	v_mfma_f32_16x16x32_bf16 v[124:127], v[178:181], v[194:197], v[124:127]
	v_mfma_f32_16x16x32_bf16 v[120:123], v[186:189], v[194:197], v[120:123]
	v_mfma_f32_16x16x32_bf16 v[116:119], v[178:181], v[202:205], v[116:119]
	v_mfma_f32_16x16x32_bf16 v[112:115], v[186:189], v[202:205], v[112:115]
	v_mfma_f32_16x16x32_bf16 v[108:111], v[178:181], v[210:213], v[108:111]
	v_mfma_f32_16x16x32_bf16 v[104:107], v[186:189], v[210:213], v[104:107]
	v_mfma_f32_16x16x32_bf16 v[100:103], v[178:181], v[218:221], v[100:103]
	v_mfma_f32_16x16x32_bf16 v[96:99], v[186:189], v[218:221], v[96:99]
	s_setprio 1
	s_barrier
	s_add_u32 s52, s42, s55
	v_add_u32_e32 v170, v157, v160
	v_add_u32_e32 v172, v157, v162
	v_mov_b32_e32 v238, v131
	v_mov_b32_e32 v128, v130
	s_addc_u32 s53, s43, 0
	v_add_u32_e32 v171, v157, v161
	ds_read_b128 v[222:225], v170
	ds_read_b128 v[226:229], v171
	v_add_u32_e32 v173, v157, v163
	ds_read_b128 v[230:233], v172
	ds_read_b128 v[234:237], v173
	v_readfirstlane_b32 s87, v142
	v_lshl_add_u64 v[240:241], s[52:53], 0, v[128:129]
	v_mov_b32_e32 v239, v129
	v_lshl_add_u64 v[240:241], v[240:241], 0, s[26:27]
	s_mov_b32 m0, s87
	v_lshl_add_u64 v[238:239], s[52:53], 0, v[238:239]
	v_readfirstlane_b32 s87, v143
	global_load_lds_dwordx4 v[240:241], off
	v_lshl_add_u64 v[238:239], v[238:239], 0, s[26:27]
	s_mov_b32 m0, s87
	s_nop 0
	global_load_lds_dwordx4 v[238:239], off
	s_barrier
	s_waitcnt lgkmcnt(0)
	s_setprio 0
	s_waitcnt lgkmcnt(0)
	v_mfma_f32_16x16x32_bf16 v[92:95], v[222:225], v[190:193], v[92:95]
	v_mfma_f32_16x16x32_bf16 v[88:91], v[230:233], v[190:193], v[88:91]
	v_mfma_f32_16x16x32_bf16 v[84:87], v[222:225], v[198:201], v[84:87]
	v_mfma_f32_16x16x32_bf16 v[80:83], v[230:233], v[198:201], v[80:83]
	v_mfma_f32_16x16x32_bf16 v[76:79], v[222:225], v[206:209], v[76:79]
	v_mfma_f32_16x16x32_bf16 v[72:75], v[230:233], v[206:209], v[72:75]
	v_mfma_f32_16x16x32_bf16 v[68:71], v[222:225], v[214:217], v[68:71]
	v_mfma_f32_16x16x32_bf16 v[64:67], v[230:233], v[214:217], v[64:67]
	v_mfma_f32_16x16x32_bf16 v[92:95], v[226:229], v[194:197], v[92:95]
	v_mfma_f32_16x16x32_bf16 v[88:91], v[234:237], v[194:197], v[88:91]
	v_mfma_f32_16x16x32_bf16 v[84:87], v[226:229], v[202:205], v[84:87]
	v_mfma_f32_16x16x32_bf16 v[80:83], v[234:237], v[202:205], v[80:83]
	v_mfma_f32_16x16x32_bf16 v[76:79], v[226:229], v[210:213], v[76:79]
	v_mfma_f32_16x16x32_bf16 v[72:75], v[234:237], v[210:213], v[72:75]
	v_mfma_f32_16x16x32_bf16 v[68:71], v[226:229], v[218:221], v[68:71]
	v_mfma_f32_16x16x32_bf16 v[64:67], v[234:237], v[218:221], v[64:67]
	s_setprio 1
	v_mov_b32_e32 v238, v131
	v_mov_b32_e32 v128, v130
	s_barrier
	ds_read_b128 v[190:193], v132 offset:16384
	ds_read_b128 v[194:197], v133 offset:16384
	ds_read_b128 v[198:201], v134 offset:16384
	ds_read_b128 v[202:205], v135 offset:16384
	ds_read_b128 v[206:209], v136 offset:16384
	ds_read_b128 v[210:213], v137 offset:16384
	ds_read_b128 v[214:217], v138 offset:16384
	ds_read_b128 v[218:221], v139 offset:16384
	v_readfirstlane_b32 s87, v144
	v_lshl_add_u64 v[240:241], s[44:45], 0, v[128:129]
	v_mov_b32_e32 v239, v129
	v_lshl_add_u64 v[240:241], v[240:241], 0, s[28:29]
	s_mov_b32 m0, s87
	v_lshl_add_u64 v[238:239], s[44:45], 0, v[238:239]
	v_readfirstlane_b32 s87, v145
	global_load_lds_dwordx4 v[240:241], off
	v_lshl_add_u64 v[238:239], v[238:239], 0, s[28:29]
	s_mov_b32 m0, s87
	s_nop 0
	global_load_lds_dwordx4 v[238:239], off
	s_barrier
; #define LDA(dst, b, h) for (int m = 0; m < 4; ++m) for (int k = 0; k < 2; ++k) \
;     dst[m][k] = *reinterpret_cast<const bf16x8*>((char*)SA(b, h) + lds_byte(wr * 64 + m * 16 + fr, k * 32 + fq * 8))
; #define LDB(dst, b, h) for (int n = 0; n < 2; ++n) for (int k = 0; k < 2; ++k) \
;     dst[n][k] = *reinterpret_cast<const bf16x8*>((char*)SB(b, h) + lds_byte(wc * 32 + n * 16 + fr, k * 32 + fq * 8))
; #define MMA(ai, bj, At_, Bt_) do { __builtin_amdgcn_s_setprio(1); \
;     for (int m = 0; m < 4; ++m) for (int n = 0; n < 2; ++n) for (int k = 0; k < 2; ++k) \
;       acc[ai][bj][m][n] = MFMA16(Bt_[n][k], At_[m][k], acc[ai][bj][m][n]); \
;     __builtin_amdgcn_s_setprio(0); } while (0)
; #define WAIT_V(n) asm volatile("s_waitcnt vmcnt(" #n ")" ::: "memory")
; #define WAIT_L(n) asm volatile("s_waitcnt lgkmcnt(" #n ")" ::: "memory")
; #define BAR __builtin_amdgcn_s_barrier()
; #define SCHED __builtin_amdgcn_sched_barrier(0)
; template <int PART  , bool SYNC_FIRST = true>
; __device__ __forceinline__ void kloop_t(const u16* __restrict__ A, int lda, const u16* __restrict__ Bt, int ldb, int K, Acc& acc, const int wv) {
;     ...
;     BAR; WAIT_L(0); MMA(1, 0, At, B0); BAR; SCHED;
;     STAGE(SB(0, 1), Bt, ldb, HALF, t + 2);
;     WAIT_V(6); BAR; MMA(1, 1, At, B1); BAR;
;     LDB(B0, 1, 0); SCHED; LDA(At, 1, 0); STAGE(SA(0, 1), A, lda, HALF, t + 2);
;     WAIT_L(8); BAR; WAIT_L(0); MMA(0, 0, At, B0); BAR; SCHED;
;     LDB(B1, 1, 1); STAGE(SB(1, 0), Bt, ldb, 0, t + 3);
	s_waitcnt lgkmcnt(0)
	s_setprio 0
	s_waitcnt lgkmcnt(0)
	v_mfma_f32_16x16x32_bf16 v[60:63], v[174:177], v[190:193], v[60:63]
	v_mfma_f32_16x16x32_bf16 v[56:59], v[182:185], v[190:193], v[56:59]
	v_mfma_f32_16x16x32_bf16 v[52:55], v[174:177], v[198:201], v[52:55]
	v_mfma_f32_16x16x32_bf16 v[48:51], v[182:185], v[198:201], v[48:51]
	v_mfma_f32_16x16x32_bf16 v[44:47], v[174:177], v[206:209], v[44:47]
	v_mfma_f32_16x16x32_bf16 v[40:43], v[182:185], v[206:209], v[40:43]
	v_mfma_f32_16x16x32_bf16 v[36:39], v[174:177], v[214:217], v[36:39]
	v_mfma_f32_16x16x32_bf16 v[32:35], v[182:185], v[214:217], v[32:35]
	v_mfma_f32_16x16x32_bf16 v[60:63], v[178:181], v[194:197], v[60:63]
	v_mfma_f32_16x16x32_bf16 v[56:59], v[186:189], v[194:197], v[56:59]
	v_mfma_f32_16x16x32_bf16 v[52:55], v[178:181], v[202:205], v[52:55]
	v_mfma_f32_16x16x32_bf16 v[48:51], v[186:189], v[202:205], v[48:51]
	v_mfma_f32_16x16x32_bf16 v[44:47], v[178:181], v[210:213], v[44:47]
	v_mfma_f32_16x16x32_bf16 v[40:43], v[186:189], v[210:213], v[40:43]
	v_mfma_f32_16x16x32_bf16 v[36:39], v[178:181], v[218:221], v[36:39]
	v_mfma_f32_16x16x32_bf16 v[32:35], v[186:189], v[218:221], v[32:35]
	s_setprio 1
	s_barrier
	v_mov_b32_e32 v174, v131
	v_mov_b32_e32 v128, v130
	v_readfirstlane_b32 s87, v146
	v_lshl_add_u64 v[176:177], s[52:53], 0, v[128:129]
	v_mov_b32_e32 v175, v129
	v_lshl_add_u64 v[176:177], v[176:177], 0, s[30:31]
	s_mov_b32 m0, s87
	v_lshl_add_u64 v[174:175], s[52:53], 0, v[174:175]
	v_readfirstlane_b32 s87, v147
	global_load_lds_dwordx4 v[176:177], off
	v_lshl_add_u64 v[174:175], v[174:175], 0, s[30:31]
	s_mov_b32 m0, s87
	s_nop 0
	global_load_lds_dwordx4 v[174:175], off
	s_waitcnt vmcnt(6)
	s_barrier
	s_setprio 0
	v_mfma_f32_16x16x32_bf16 v[28:31], v[222:225], v[190:193], v[28:31]
	v_mfma_f32_16x16x32_bf16 v[24:27], v[230:233], v[190:193], v[24:27]
	v_mfma_f32_16x16x32_bf16 v[20:23], v[222:225], v[198:201], v[20:23]
	v_mfma_f32_16x16x32_bf16 v[16:19], v[230:233], v[198:201], v[16:19]
	v_mfma_f32_16x16x32_bf16 v[12:15], v[222:225], v[206:209], v[12:15]
	v_mfma_f32_16x16x32_bf16 v[8:11], v[230:233], v[206:209], v[8:11]
	v_mfma_f32_16x16x32_bf16 v[4:7], v[222:225], v[214:217], v[4:7]
	v_mfma_f32_16x16x32_bf16 v[0:3], v[230:233], v[214:217], v[0:3]
	v_mfma_f32_16x16x32_bf16 v[28:31], v[226:229], v[194:197], v[28:31]
	v_mfma_f32_16x16x32_bf16 v[24:27], v[234:237], v[194:197], v[24:27]
	v_mfma_f32_16x16x32_bf16 v[20:23], v[226:229], v[202:205], v[20:23]
	v_mfma_f32_16x16x32_bf16 v[16:19], v[234:237], v[202:205], v[16:19]
	v_mfma_f32_16x16x32_bf16 v[12:15], v[226:229], v[210:213], v[12:15]
	v_mfma_f32_16x16x32_bf16 v[8:11], v[234:237], v[210:213], v[8:11]
	v_mfma_f32_16x16x32_bf16 v[4:7], v[226:229], v[218:221], v[4:7]
	v_mfma_f32_16x16x32_bf16 v[0:3], v[234:237], v[218:221], v[0:3]
	s_setprio 1
	v_add_u32_e32 v174, v158, v160
	v_add_u32_e32 v176, v158, v162
	s_barrier
	v_add_u32_e32 v175, v158, v161
	ds_read_b128 v[182:185], v174
	ds_read_b128 v[186:189], v175
	v_add_u32_e32 v177, v158, v163
	ds_read_b128 v[190:193], v176
	ds_read_b128 v[194:197], v177
	v_mov_b32_e32 v178, v131
	v_mov_b32_e32 v128, v130
	ds_read_b128 v[198:201], v132 offset:32768
	ds_read_b128 v[202:205], v133 offset:32768
	ds_read_b128 v[206:209], v134 offset:32768
	ds_read_b128 v[210:213], v135 offset:32768
	ds_read_b128 v[214:217], v136 offset:32768
	ds_read_b128 v[218:221], v137 offset:32768
	ds_read_b128 v[222:225], v138 offset:32768
	ds_read_b128 v[226:229], v139 offset:32768
	v_readfirstlane_b32 s87, v148
	v_lshl_add_u64 v[180:181], s[44:45], 0, v[128:129]
	v_mov_b32_e32 v179, v129
	v_lshl_add_u64 v[180:181], v[180:181], 0, s[34:35]
	s_mov_b32 m0, s87
	v_lshl_add_u64 v[178:179], s[44:45], 0, v[178:179]
	v_readfirstlane_b32 s87, v149
	global_load_lds_dwordx4 v[180:181], off
	v_lshl_add_u64 v[178:179], v[178:179], 0, s[34:35]
	s_mov_b32 m0, s87
	s_nop 0
	global_load_lds_dwordx4 v[178:179], off
	s_waitcnt lgkmcnt(8)
	s_barrier
	s_waitcnt lgkmcnt(0)
	s_setprio 0
	s_waitcnt lgkmcnt(0)
	v_mfma_f32_16x16x32_bf16 v[124:127], v[182:185], v[198:201], v[124:127]
	v_mfma_f32_16x16x32_bf16 v[120:123], v[190:193], v[198:201], v[120:123]
	v_mfma_f32_16x16x32_bf16 v[116:119], v[182:185], v[206:209], v[116:119]
	v_mfma_f32_16x16x32_bf16 v[112:115], v[190:193], v[206:209], v[112:115]
	v_mfma_f32_16x16x32_bf16 v[108:111], v[182:185], v[214:217], v[108:111]
	v_mfma_f32_16x16x32_bf16 v[104:107], v[190:193], v[214:217], v[104:107]
	v_mfma_f32_16x16x32_bf16 v[100:103], v[182:185], v[222:225], v[100:103]
	v_mfma_f32_16x16x32_bf16 v[96:99], v[190:193], v[222:225], v[96:99]
	v_mfma_f32_16x16x32_bf16 v[124:127], v[186:189], v[202:205], v[124:127]
	v_mfma_f32_16x16x32_bf16 v[120:123], v[194:197], v[202:205], v[120:123]
	v_mfma_f32_16x16x32_bf16 v[116:119], v[186:189], v[210:213], v[116:119]
	v_mfma_f32_16x16x32_bf16 v[112:115], v[194:197], v[210:213], v[112:115]
	v_mfma_f32_16x16x32_bf16 v[108:111], v[186:189], v[218:221], v[108:111]
	v_mfma_f32_16x16x32_bf16 v[104:107], v[194:197], v[218:221], v[104:107]
	v_mfma_f32_16x16x32_bf16 v[100:103], v[186:189], v[226:229], v[100:103]
	v_mfma_f32_16x16x32_bf16 v[96:99], v[194:197], v[226:229], v[96:99]
	s_setprio 1
	s_barrier
	v_add_u32_e32 v178, v159, v160
	v_add_u32_e32 v180, v159, v162
	v_mov_b32_e32 v246, v131
	v_mov_b32_e32 v128, v130
	v_add_u32_e32 v179, v159, v161
	ds_read_b128 v[230:233], v178
	ds_read_b128 v[234:237], v179
	v_add_u32_e32 v181, v159, v163
	ds_read_b128 v[238:241], v180
	ds_read_b128 v[242:245], v181
	v_readfirstlane_b32 s87, v150
	v_lshl_add_u64 v[248:249], s[52:53], 0, v[128:129]
	v_mov_b32_e32 v247, v129
	v_lshl_add_u64 v[248:249], v[248:249], 0, s[36:37]
	s_mov_b32 m0, s87
	v_lshl_add_u64 v[246:247], s[52:53], 0, v[246:247]
	v_readfirstlane_b32 s87, v151
	global_load_lds_dwordx4 v[248:249], off
	v_lshl_add_u64 v[246:247], v[246:247], 0, s[36:37]
	s_mov_b32 m0, s87
	s_nop 0
	global_load_lds_dwordx4 v[246:247], off
	s_barrier
; #define LDA(dst, b, h) for (int m = 0; m < 4; ++m) for (int k = 0; k < 2; ++k) \
;     dst[m][k] = *reinterpret_cast<const bf16x8*>((char*)SA(b, h) + lds_byte(wr * 64 + m * 16 + fr, k * 32 + fq * 8))
; #define LDB(dst, b, h) for (int n = 0; n < 2; ++n) for (int k = 0; k < 2; ++k) \
;     dst[n][k] = *reinterpret_cast<const bf16x8*>((char*)SB(b, h) + lds_byte(wc * 32 + n * 16 + fr, k * 32 + fq * 8))
; #define MMA(ai, bj, At_, Bt_) do { __builtin_amdgcn_s_setprio(1); \
;     for (int m = 0; m < 4; ++m) for (int n = 0; n < 2; ++n) for (int k = 0; k < 2; ++k) \
;       acc[ai][bj][m][n] = MFMA16(Bt_[n][k], At_[m][k], acc[ai][bj][m][n]); \
;     __builtin_amdgcn_s_setprio(0); } while (0)
; #define WAIT_V(n) asm volatile("s_waitcnt vmcnt(" #n ")" ::: "memory")
; #define WAIT_L(n) asm volatile("s_waitcnt lgkmcnt(" #n ")" ::: "memory")
; #define BAR __builtin_amdgcn_s_barrier()
; #define SCHED __builtin_amdgcn_sched_barrier(0)
; template <int PART  , bool SYNC_FIRST = true>
; __device__ __forceinline__ void kloop_t(const u16* __restrict__ A, int lda, const u16* __restrict__ Bt, int ldb, int K, Acc& acc, const int wv) {
;     ...
;     BAR; WAIT_L(0); MMA(0, 1, At, B1); BAR;
;     LDA(At, 1, 1); STAGE(SA(1, 0), A, lda, 0, t + 3);
;     BAR; WAIT_L(0); MMA(1, 0, At, B0); BAR; SCHED;
;     STAGE(SB(1, 1), Bt, ldb, HALF, t + 3);
;     WAIT_V(6); BAR; MMA(1, 1, At, B1); BAR;
;   }
;   { LDB(B0, 0, 0); LDA(At, 0, 0); STAGE(SA(1, 1), A, lda, HALF, nt - 1);
;     BAR; WAIT_L(0); MMA(0, 0, At, B0); BAR;
	s_waitcnt lgkmcnt(0)
	s_setprio 0
	s_waitcnt lgkmcnt(0)
	v_mfma_f32_16x16x32_bf16 v[92:95], v[230:233], v[198:201], v[92:95]
	v_mfma_f32_16x16x32_bf16 v[88:91], v[238:241], v[198:201], v[88:91]
	v_mfma_f32_16x16x32_bf16 v[84:87], v[230:233], v[206:209], v[84:87]
	v_mfma_f32_16x16x32_bf16 v[80:83], v[238:241], v[206:209], v[80:83]
	v_mfma_f32_16x16x32_bf16 v[76:79], v[230:233], v[214:217], v[76:79]
	v_mfma_f32_16x16x32_bf16 v[72:75], v[238:241], v[214:217], v[72:75]
	v_mfma_f32_16x16x32_bf16 v[68:71], v[230:233], v[222:225], v[68:71]
	v_mfma_f32_16x16x32_bf16 v[64:67], v[238:241], v[222:225], v[64:67]
	v_mfma_f32_16x16x32_bf16 v[92:95], v[234:237], v[202:205], v[92:95]
	v_mfma_f32_16x16x32_bf16 v[88:91], v[242:245], v[202:205], v[88:91]
	v_mfma_f32_16x16x32_bf16 v[84:87], v[234:237], v[210:213], v[84:87]
	v_mfma_f32_16x16x32_bf16 v[80:83], v[242:245], v[210:213], v[80:83]
	v_mfma_f32_16x16x32_bf16 v[76:79], v[234:237], v[218:221], v[76:79]
	v_mfma_f32_16x16x32_bf16 v[72:75], v[242:245], v[218:221], v[72:75]
	v_mfma_f32_16x16x32_bf16 v[68:71], v[234:237], v[226:229], v[68:71]
	v_mfma_f32_16x16x32_bf16 v[64:67], v[242:245], v[226:229], v[64:67]
	s_setprio 1
	v_mov_b32_e32 v246, v131
	v_mov_b32_e32 v128, v130
	s_barrier
	ds_read_b128 v[198:201], v132 offset:49152
	ds_read_b128 v[202:205], v133 offset:49152
	ds_read_b128 v[206:209], v134 offset:49152
	ds_read_b128 v[210:213], v135 offset:49152
	ds_read_b128 v[214:217], v136 offset:49152
	ds_read_b128 v[218:221], v137 offset:49152
	ds_read_b128 v[222:225], v138 offset:49152
	ds_read_b128 v[226:229], v139 offset:49152
	v_readfirstlane_b32 s87, v152
	v_lshl_add_u64 v[248:249], s[44:45], 0, v[128:129]
	v_mov_b32_e32 v247, v129
	v_lshl_add_u64 v[248:249], v[248:249], 0, s[38:39]
	s_mov_b32 m0, s87
	v_lshl_add_u64 v[246:247], s[44:45], 0, v[246:247]
	v_readfirstlane_b32 s44, v153
	global_load_lds_dwordx4 v[248:249], off
	v_lshl_add_u64 v[246:247], v[246:247], 0, s[38:39]
	s_mov_b32 m0, s44
	s_nop 0
	global_load_lds_dwordx4 v[246:247], off
	s_barrier
	s_waitcnt lgkmcnt(0)
	s_setprio 0
	s_waitcnt lgkmcnt(0)
	v_mfma_f32_16x16x32_bf16 v[60:63], v[182:185], v[198:201], v[60:63]
	v_mfma_f32_16x16x32_bf16 v[56:59], v[190:193], v[198:201], v[56:59]
	v_mfma_f32_16x16x32_bf16 v[52:55], v[182:185], v[206:209], v[52:55]
	v_mfma_f32_16x16x32_bf16 v[48:51], v[190:193], v[206:209], v[48:51]
	v_mfma_f32_16x16x32_bf16 v[44:47], v[182:185], v[214:217], v[44:47]
	v_mfma_f32_16x16x32_bf16 v[40:43], v[190:193], v[214:217], v[40:43]
	v_mfma_f32_16x16x32_bf16 v[36:39], v[182:185], v[222:225], v[36:39]
	v_mfma_f32_16x16x32_bf16 v[32:35], v[190:193], v[222:225], v[32:35]
	v_mfma_f32_16x16x32_bf16 v[60:63], v[186:189], v[202:205], v[60:63]
	v_mfma_f32_16x16x32_bf16 v[56:59], v[194:197], v[202:205], v[56:59]
	v_mfma_f32_16x16x32_bf16 v[52:55], v[186:189], v[210:213], v[52:55]
	v_mfma_f32_16x16x32_bf16 v[48:51], v[194:197], v[210:213], v[48:51]
	v_mfma_f32_16x16x32_bf16 v[44:47], v[186:189], v[218:221], v[44:47]
	v_mfma_f32_16x16x32_bf16 v[40:43], v[194:197], v[218:221], v[40:43]
	v_mfma_f32_16x16x32_bf16 v[36:39], v[186:189], v[226:229], v[36:39]
	v_mfma_f32_16x16x32_bf16 v[32:35], v[194:197], v[226:229], v[32:35]
	s_setprio 1
	s_barrier
	v_mov_b32_e32 v182, v131
	v_mov_b32_e32 v128, v130
	v_readfirstlane_b32 s44, v154
	v_lshl_add_u64 v[184:185], s[52:53], 0, v[128:129]
	v_mov_b32_e32 v183, v129
	v_lshl_add_u64 v[184:185], v[184:185], 0, s[40:41]
	s_mov_b32 m0, s44
	v_lshl_add_u64 v[182:183], s[52:53], 0, v[182:183]
	v_readfirstlane_b32 s44, v155
	global_load_lds_dwordx4 v[184:185], off
	v_lshl_add_u64 v[182:183], v[182:183], 0, s[40:41]
	s_mov_b32 m0, s44
	s_nop 0
	global_load_lds_dwordx4 v[182:183], off
	s_waitcnt vmcnt(6)
	s_barrier
	s_setprio 0
	v_mfma_f32_16x16x32_bf16 v[28:31], v[230:233], v[198:201], v[28:31]
	v_mfma_f32_16x16x32_bf16 v[24:27], v[238:241], v[198:201], v[24:27]
	v_mfma_f32_16x16x32_bf16 v[20:23], v[230:233], v[206:209], v[20:23]
	v_mfma_f32_16x16x32_bf16 v[16:19], v[238:241], v[206:209], v[16:19]
	v_mfma_f32_16x16x32_bf16 v[12:15], v[230:233], v[214:217], v[12:15]
	v_mfma_f32_16x16x32_bf16 v[8:11], v[238:241], v[214:217], v[8:11]
	v_mfma_f32_16x16x32_bf16 v[4:7], v[230:233], v[222:225], v[4:7]
	v_mfma_f32_16x16x32_bf16 v[0:3], v[238:241], v[222:225], v[0:3]
	v_mfma_f32_16x16x32_bf16 v[28:31], v[234:237], v[202:205], v[28:31]
	v_mfma_f32_16x16x32_bf16 v[24:27], v[242:245], v[202:205], v[24:27]
	v_mfma_f32_16x16x32_bf16 v[20:23], v[234:237], v[210:213], v[20:23]
	v_mfma_f32_16x16x32_bf16 v[16:19], v[242:245], v[210:213], v[16:19]
	v_mfma_f32_16x16x32_bf16 v[12:15], v[234:237], v[218:221], v[12:15]
	v_mfma_f32_16x16x32_bf16 v[8:11], v[242:245], v[218:221], v[8:11]
	v_mfma_f32_16x16x32_bf16 v[4:7], v[234:237], v[226:229], v[4:7]
	v_mfma_f32_16x16x32_bf16 v[0:3], v[242:245], v[226:229], v[0:3]
	s_setprio 1
	s_add_i32 s57, s57, 2
	s_add_u32 s42, s42, 0x100
	s_addc_u32 s43, s43, 0
	s_cmp_lt_u32 s57, 60
	s_barrier
	s_cbranch_scc1 .LBB0_1139
	s_add_u32 s4, s4, 0x101f80
	v_readfirstlane_b32 s42, v168
	s_addc_u32 s5, s5, 0
	s_mov_b32 m0, s42
	v_readfirstlane_b32 s42, v169
	ds_read_b128 v[142:145], v164
	ds_read_b128 v[146:149], v165
	ds_read_b128 v[150:153], v166
	ds_read_b128 v[154:157], v167
	ds_read_b128 v[158:161], v132
	ds_read_b128 v[162:165], v133
	ds_read_b128 v[182:185], v134
	ds_read_b128 v[186:189], v135
	ds_read_b128 v[190:193], v136
	ds_read_b128 v[194:197], v137
	ds_read_b128 v[198:201], v138
	ds_read_b128 v[202:205], v139
	s_nop 0
	global_load_lds_dwordx4 v130, s[4:5]
	s_mov_b32 m0, s42
	s_nop 0
	global_load_lds_dwordx4 v131, s[4:5]
	s_barrier
; #define LDA(dst, b, h) for (int m = 0; m < 4; ++m) for (int k = 0; k < 2; ++k) \
;     dst[m][k] = *reinterpret_cast<const bf16x8*>((char*)SA(b, h) + lds_byte(wr * 64 + m * 16 + fr, k * 32 + fq * 8))
; #define LDB(dst, b, h) for (int n = 0; n < 2; ++n) for (int k = 0; k < 2; ++k) \
;     dst[n][k] = *reinterpret_cast<const bf16x8*>((char*)SB(b, h) + lds_byte(wc * 32 + n * 16 + fr, k * 32 + fq * 8))
; #define MMA(ai, bj, At_, Bt_) do { __builtin_amdgcn_s_setprio(1); \
;     for (int m = 0; m < 4; ++m) for (int n = 0; n < 2; ++n) for (int k = 0; k < 2; ++k) \
;       acc[ai][bj][m][n] = MFMA16(Bt_[n][k], At_[m][k], acc[ai][bj][m][n]); \
;     __builtin_amdgcn_s_setprio(0); } while (0)
; #define WAIT_V(n) asm volatile("s_waitcnt vmcnt(" #n ")" ::: "memory")
; #define WAIT_L(n) asm volatile("s_waitcnt lgkmcnt(" #n ")" ::: "memory")
; #define BAR __builtin_amdgcn_s_barrier()
; template <int PART  , bool SYNC_FIRST = true>
; __device__ __forceinline__ void kloop_t(const u16* __restrict__ A, int lda, const u16* __restrict__ Bt, int ldb, int K, Acc& acc, const int wv) {
;     ...
;     BAR; WAIT_L(0); MMA(0, 0, At, B0); BAR;
;     LDB(B1, 0, 1); BAR; WAIT_L(0); MMA(0, 1, At, B1); BAR;
;     LDA(At, 0, 1); WAIT_V(4); BAR; WAIT_L(0); MMA(1, 0, At, B0); MMA(1, 1, At, B1); BAR; }
	s_waitcnt lgkmcnt(0)
	s_setprio 0
	s_waitcnt lgkmcnt(0)
	v_mfma_f32_16x16x32_bf16 v[124:127], v[142:145], v[158:161], v[124:127]
	v_mfma_f32_16x16x32_bf16 v[120:123], v[150:153], v[158:161], v[120:123]
	v_mfma_f32_16x16x32_bf16 v[108:111], v[142:145], v[190:193], v[108:111]
	v_mfma_f32_16x16x32_bf16 v[104:107], v[150:153], v[190:193], v[104:107]
	v_mfma_f32_16x16x32_bf16 v[124:127], v[146:149], v[162:165], v[124:127]
	v_mfma_f32_16x16x32_bf16 v[120:123], v[154:157], v[162:165], v[120:123]
	v_mfma_f32_16x16x32_bf16 v[116:119], v[142:145], v[182:185], v[116:119]
	v_mfma_f32_16x16x32_bf16 v[112:115], v[150:153], v[182:185], v[112:115]
	v_mfma_f32_16x16x32_bf16 v[108:111], v[146:149], v[194:197], v[108:111]
	v_mfma_f32_16x16x32_bf16 v[104:107], v[154:157], v[194:197], v[104:107]
	v_mfma_f32_16x16x32_bf16 v[100:103], v[142:145], v[198:201], v[100:103]
	v_mfma_f32_16x16x32_bf16 v[96:99], v[150:153], v[198:201], v[96:99]
	v_mfma_f32_16x16x32_bf16 v[166:169], v[146:149], v[186:189], v[116:119]
	v_mfma_f32_16x16x32_bf16 v[206:209], v[154:157], v[186:189], v[112:115]
	v_mfma_f32_16x16x32_bf16 v[210:213], v[146:149], v[202:205], v[100:103]
	v_mfma_f32_16x16x32_bf16 v[214:217], v[154:157], v[202:205], v[96:99]
	s_setprio 1
	s_barrier
	s_nop 1
	ds_read_b128 v[96:99], v170
	ds_read_b128 v[100:103], v171
	ds_read_b128 v[112:115], v172
	ds_read_b128 v[116:119], v173
	s_barrier
	s_waitcnt lgkmcnt(0)
	s_setprio 0
	s_waitcnt lgkmcnt(0)
	v_mfma_f32_16x16x32_bf16 v[92:95], v[96:99], v[158:161], v[92:95]
	v_mfma_f32_16x16x32_bf16 v[88:91], v[112:115], v[158:161], v[88:91]
	v_mfma_f32_16x16x32_bf16 v[76:79], v[96:99], v[190:193], v[76:79]
	v_mfma_f32_16x16x32_bf16 v[72:75], v[112:115], v[190:193], v[72:75]
	v_mfma_f32_16x16x32_bf16 v[92:95], v[100:103], v[162:165], v[92:95]
	v_mfma_f32_16x16x32_bf16 v[88:91], v[116:119], v[162:165], v[88:91]
	v_mfma_f32_16x16x32_bf16 v[84:87], v[96:99], v[182:185], v[84:87]
	v_mfma_f32_16x16x32_bf16 v[80:83], v[112:115], v[182:185], v[80:83]
	v_mfma_f32_16x16x32_bf16 v[76:79], v[100:103], v[194:197], v[76:79]
	v_mfma_f32_16x16x32_bf16 v[72:75], v[116:119], v[194:197], v[72:75]
	v_mfma_f32_16x16x32_bf16 v[68:71], v[96:99], v[198:201], v[68:71]
	v_mfma_f32_16x16x32_bf16 v[64:67], v[112:115], v[198:201], v[64:67]
	v_mfma_f32_16x16x32_bf16 v[158:161], v[100:103], v[186:189], v[84:87]
	v_mfma_f32_16x16x32_bf16 v[162:165], v[116:119], v[186:189], v[80:83]
	v_mfma_f32_16x16x32_bf16 v[170:173], v[100:103], v[202:205], v[68:71]
	v_mfma_f32_16x16x32_bf16 v[182:185], v[116:119], v[202:205], v[64:67]
	s_setprio 1
	s_barrier
	s_nop 1
	ds_read_b128 v[64:67], v132 offset:16384
	ds_read_b128 v[68:71], v133 offset:16384
	ds_read_b128 v[80:83], v134 offset:16384
	ds_read_b128 v[84:87], v135 offset:16384
	ds_read_b128 v[186:189], v136 offset:16384
	ds_read_b128 v[190:193], v137 offset:16384
	ds_read_b128 v[194:197], v138 offset:16384
	ds_read_b128 v[198:201], v139 offset:16384
	s_waitcnt vmcnt(4)
	s_barrier
	s_waitcnt lgkmcnt(0)
	s_setprio 0
	s_waitcnt lgkmcnt(0)
	v_mfma_f32_16x16x32_bf16 v[60:63], v[142:145], v[64:67], v[60:63]
	v_mfma_f32_16x16x32_bf16 v[56:59], v[150:153], v[64:67], v[56:59]
	v_mfma_f32_16x16x32_bf16 v[44:47], v[142:145], v[186:189], v[44:47]
	v_mfma_f32_16x16x32_bf16 v[40:43], v[150:153], v[186:189], v[40:43]
	v_mfma_f32_16x16x32_bf16 v[60:63], v[146:149], v[68:71], v[60:63]
	v_mfma_f32_16x16x32_bf16 v[56:59], v[154:157], v[68:71], v[56:59]
	v_mfma_f32_16x16x32_bf16 v[52:55], v[142:145], v[80:83], v[52:55]
	v_mfma_f32_16x16x32_bf16 v[48:51], v[150:153], v[80:83], v[48:51]
	v_mfma_f32_16x16x32_bf16 v[44:47], v[146:149], v[190:193], v[44:47]
	v_mfma_f32_16x16x32_bf16 v[40:43], v[154:157], v[190:193], v[40:43]
	v_mfma_f32_16x16x32_bf16 v[36:39], v[142:145], v[194:197], v[36:39]
	v_mfma_f32_16x16x32_bf16 v[32:35], v[150:153], v[194:197], v[32:35]
	v_mfma_f32_16x16x32_bf16 v[202:205], v[146:149], v[84:87], v[52:55]
	v_mfma_f32_16x16x32_bf16 v[218:221], v[154:157], v[84:87], v[48:51]
	v_mfma_f32_16x16x32_bf16 v[142:145], v[146:149], v[198:201], v[36:39]
	v_mfma_f32_16x16x32_bf16 v[146:149], v[154:157], v[198:201], v[32:35]
	s_setprio 1
	s_setprio 0
	v_mfma_f32_16x16x32_bf16 v[28:31], v[96:99], v[64:67], v[28:31]
	v_mfma_f32_16x16x32_bf16 v[24:27], v[112:115], v[64:67], v[24:27]
	v_mfma_f32_16x16x32_bf16 v[12:15], v[96:99], v[186:189], v[12:15]
	v_mfma_f32_16x16x32_bf16 v[8:11], v[112:115], v[186:189], v[8:11]
	v_mfma_f32_16x16x32_bf16 v[28:31], v[100:103], v[68:71], v[28:31]
	v_mfma_f32_16x16x32_bf16 v[24:27], v[116:119], v[68:71], v[24:27]
	v_mfma_f32_16x16x32_bf16 v[20:23], v[96:99], v[80:83], v[20:23]
	v_mfma_f32_16x16x32_bf16 v[16:19], v[112:115], v[80:83], v[16:19]
	v_mfma_f32_16x16x32_bf16 v[12:15], v[100:103], v[190:193], v[12:15]
	v_mfma_f32_16x16x32_bf16 v[8:11], v[116:119], v[190:193], v[8:11]
	v_mfma_f32_16x16x32_bf16 v[4:7], v[96:99], v[194:197], v[4:7]
	v_mfma_f32_16x16x32_bf16 v[0:3], v[112:115], v[194:197], v[0:3]
	v_mfma_f32_16x16x32_bf16 v[150:153], v[100:103], v[84:87], v[20:23]
	v_mfma_f32_16x16x32_bf16 v[154:157], v[116:119], v[84:87], v[16:19]
	v_mfma_f32_16x16x32_bf16 v[186:189], v[100:103], v[198:201], v[4:7]
	v_mfma_f32_16x16x32_bf16 v[190:193], v[116:119], v[198:201], v[0:3]
	s_setprio 1
	s_barrier
; #define LDA(dst, b, h) for (int m = 0; m < 4; ++m) for (int k = 0; k < 2; ++k) \
;     dst[m][k] = *reinterpret_cast<const bf16x8*>((char*)SA(b, h) + lds_byte(wr * 64 + m * 16 + fr, k * 32 + fq * 8))
; #define LDB(dst, b, h) for (int n = 0; n < 2; ++n) for (int k = 0; k < 2; ++k) \
;     dst[n][k] = *reinterpret_cast<const bf16x8*>((char*)SB(b, h) + lds_byte(wc * 32 + n * 16 + fr, k * 32 + fq * 8))
; #define MMA(ai, bj, At_, Bt_) do { __builtin_amdgcn_s_setprio(1); \
;     for (int m = 0; m < 4; ++m) for (int n = 0; n < 2; ++n) for (int k = 0; k < 2; ++k) \
;       acc[ai][bj][m][n] = MFMA16(Bt_[n][k], At_[m][k], acc[ai][bj][m][n]); \
;     __builtin_amdgcn_s_setprio(0); } while (0)
; #define WAIT_V(n) asm volatile("s_waitcnt vmcnt(" #n ")" ::: "memory")
; #define WAIT_L(n) asm volatile("s_waitcnt lgkmcnt(" #n ")" ::: "memory")
; #define BAR __builtin_amdgcn_s_barrier()
; template <int PART  , bool SYNC_FIRST = true>
; __device__ __forceinline__ void kloop_t(const u16* __restrict__ A, int lda, const u16* __restrict__ Bt, int ldb, int K, Acc& acc, const int wv) {
;     ...
;   { LDB(B0, 1, 0); LDA(At, 1, 0); WAIT_V(2); BAR; WAIT_L(0); MMA(0, 0, At, B0); BAR;
;     LDB(B1, 1, 1); WAIT_V(0); BAR; WAIT_L(0); MMA(0, 1, At, B1); BAR;
;     LDA(At, 1, 1); BAR; WAIT_L(0); MMA(1, 0, At, B0); MMA(1, 1, At, B1); BAR; }
;   if (wr == 0) BAR;
	s_nop 1
	ds_read_b128 v[0:3], v174
	ds_read_b128 v[4:7], v175
	ds_read_b128 v[194:197], v176
	ds_read_b128 v[174:177], v177
	ds_read_b128 v[16:19], v132 offset:32768
	ds_read_b128 v[20:23], v133 offset:32768
	ds_read_b128 v[32:35], v134 offset:32768
	ds_read_b128 v[36:39], v135 offset:32768
	ds_read_b128 v[48:51], v136 offset:32768
	ds_read_b128 v[52:55], v137 offset:32768
	ds_read_b128 v[198:201], v138 offset:32768
	ds_read_b128 v[222:225], v139 offset:32768
	s_waitcnt vmcnt(2)
	s_barrier
	s_waitcnt lgkmcnt(0)
	s_setprio 0
	s_waitcnt lgkmcnt(0)
	v_mfma_f32_16x16x32_bf16 v[64:67], v[0:3], v[16:19], v[124:127]
	v_mfma_f32_16x16x32_bf16 v[112:115], v[4:7], v[20:23], v[64:67]
	v_mfma_f32_16x16x32_bf16 v[64:67], v[194:197], v[16:19], v[120:123]
	v_mfma_f32_16x16x32_bf16 v[116:119], v[174:177], v[20:23], v[64:67]
	v_mfma_f32_16x16x32_bf16 v[64:67], v[0:3], v[32:35], v[166:169]
	v_mfma_f32_16x16x32_bf16 v[96:99], v[4:7], v[36:39], v[64:67]
	v_mfma_f32_16x16x32_bf16 v[64:67], v[194:197], v[32:35], v[206:209]
	v_mfma_f32_16x16x32_bf16 v[100:103], v[174:177], v[36:39], v[64:67]
	v_mfma_f32_16x16x32_bf16 v[64:67], v[0:3], v[48:51], v[108:111]
	v_mfma_f32_16x16x32_bf16 v[80:83], v[4:7], v[52:55], v[64:67]
	v_mfma_f32_16x16x32_bf16 v[64:67], v[194:197], v[48:51], v[104:107]
	v_mfma_f32_16x16x32_bf16 v[84:87], v[174:177], v[52:55], v[64:67]
	v_mfma_f32_16x16x32_bf16 v[64:67], v[0:3], v[198:201], v[210:213]
	v_mfma_f32_16x16x32_bf16 v[68:71], v[194:197], v[198:201], v[214:217]
	v_mfma_f32_16x16x32_bf16 v[64:67], v[4:7], v[222:225], v[64:67]
	v_mfma_f32_16x16x32_bf16 v[68:71], v[174:177], v[222:225], v[68:71]
	s_setprio 1
	s_barrier
	ds_read_b128 v[166:169], v178
	ds_read_b128 v[206:209], v179
	ds_read_b128 v[210:213], v180
	ds_read_b128 v[178:181], v181
	s_waitcnt vmcnt(0)
	s_barrier
	s_waitcnt lgkmcnt(0)
	s_setprio 0
	s_waitcnt lgkmcnt(0)
	v_mfma_f32_16x16x32_bf16 v[92:95], v[166:169], v[16:19], v[92:95]
	v_mfma_f32_16x16x32_bf16 v[16:19], v[210:213], v[16:19], v[88:91]
	v_mfma_f32_16x16x32_bf16 v[124:127], v[178:181], v[20:23], v[16:19]
	v_mfma_f32_16x16x32_bf16 v[16:19], v[166:169], v[32:35], v[158:161]
	v_mfma_f32_16x16x32_bf16 v[104:107], v[206:209], v[36:39], v[16:19]
	v_mfma_f32_16x16x32_bf16 v[16:19], v[210:213], v[32:35], v[162:165]
	v_mfma_f32_16x16x32_bf16 v[108:111], v[178:181], v[36:39], v[16:19]
	v_mfma_f32_16x16x32_bf16 v[16:19], v[166:169], v[48:51], v[76:79]
	v_mfma_f32_16x16x32_bf16 v[88:91], v[206:209], v[52:55], v[16:19]
	v_mfma_f32_16x16x32_bf16 v[16:19], v[210:213], v[48:51], v[72:75]
	v_mfma_f32_16x16x32_bf16 v[120:123], v[206:209], v[20:23], v[92:95]
	v_mfma_f32_16x16x32_bf16 v[92:95], v[178:181], v[52:55], v[16:19]
	v_mfma_f32_16x16x32_bf16 v[16:19], v[166:169], v[198:201], v[170:173]
	v_mfma_f32_16x16x32_bf16 v[72:75], v[206:209], v[222:225], v[16:19]
	v_mfma_f32_16x16x32_bf16 v[16:19], v[210:213], v[198:201], v[182:185]
	v_mfma_f32_16x16x32_bf16 v[76:79], v[178:181], v[222:225], v[16:19]
	s_setprio 1
	s_barrier
	ds_read_b128 v[158:161], v132 offset:49152
	ds_read_b128 v[130:133], v133 offset:49152
	ds_read_b128 v[162:165], v134 offset:49152
	ds_read_b128 v[170:173], v135 offset:49152
	ds_read_b128 v[182:185], v136 offset:49152
	ds_read_b128 v[134:137], v137 offset:49152
	ds_read_b128 v[198:201], v138 offset:49152
	ds_read_b128 v[214:217], v139 offset:49152
	s_barrier
	s_waitcnt lgkmcnt(0)
	s_setprio 0
	s_waitcnt lgkmcnt(0)
	v_mfma_f32_16x16x32_bf16 v[16:19], v[0:3], v[158:161], v[60:63]
	v_mfma_f32_16x16x32_bf16 v[48:51], v[4:7], v[130:133], v[16:19]
	v_mfma_f32_16x16x32_bf16 v[16:19], v[194:197], v[158:161], v[56:59]
	v_mfma_f32_16x16x32_bf16 v[52:55], v[174:177], v[130:133], v[16:19]
	v_mfma_f32_16x16x32_bf16 v[16:19], v[0:3], v[162:165], v[202:205]
	v_mfma_f32_16x16x32_bf16 v[32:35], v[4:7], v[170:173], v[16:19]
	v_mfma_f32_16x16x32_bf16 v[16:19], v[194:197], v[162:165], v[218:221]
	v_mfma_f32_16x16x32_bf16 v[36:39], v[174:177], v[170:173], v[16:19]
	v_mfma_f32_16x16x32_bf16 v[16:19], v[0:3], v[182:185], v[44:47]
	v_mfma_f32_16x16x32_bf16 v[0:3], v[0:3], v[198:201], v[142:145]
	v_mfma_f32_16x16x32_bf16 v[16:19], v[4:7], v[134:137], v[16:19]
	v_mfma_f32_16x16x32_bf16 v[20:23], v[194:197], v[182:185], v[40:43]
	v_mfma_f32_16x16x32_bf16 v[0:3], v[4:7], v[214:217], v[0:3]
	v_mfma_f32_16x16x32_bf16 v[4:7], v[194:197], v[198:201], v[146:149]
	v_mfma_f32_16x16x32_bf16 v[20:23], v[174:177], v[134:137], v[20:23]
	v_mfma_f32_16x16x32_bf16 v[4:7], v[174:177], v[214:217], v[4:7]
	s_setprio 1
	s_setprio 0
	v_mfma_f32_16x16x32_bf16 v[24:27], v[210:213], v[158:161], v[24:27]
	v_mfma_f32_16x16x32_bf16 v[60:63], v[178:181], v[130:133], v[24:27]
	v_mfma_f32_16x16x32_bf16 v[24:27], v[166:169], v[162:165], v[150:153]
	v_mfma_f32_16x16x32_bf16 v[28:31], v[166:169], v[158:161], v[28:31]
	v_mfma_f32_16x16x32_bf16 v[40:43], v[206:209], v[170:173], v[24:27]
	v_mfma_f32_16x16x32_bf16 v[24:27], v[210:213], v[162:165], v[154:157]
	v_mfma_f32_16x16x32_bf16 v[12:15], v[166:169], v[182:185], v[12:15]
	v_mfma_f32_16x16x32_bf16 v[8:11], v[210:213], v[182:185], v[8:11]
	v_mfma_f32_16x16x32_bf16 v[56:59], v[206:209], v[130:133], v[28:31]
	v_mfma_f32_16x16x32_bf16 v[44:47], v[178:181], v[170:173], v[24:27]
	v_mfma_f32_16x16x32_bf16 v[24:27], v[206:209], v[134:137], v[12:15]
	v_mfma_f32_16x16x32_bf16 v[28:31], v[178:181], v[134:137], v[8:11]
	v_mfma_f32_16x16x32_bf16 v[8:11], v[166:169], v[198:201], v[186:189]
	v_mfma_f32_16x16x32_bf16 v[12:15], v[210:213], v[198:201], v[190:193]
	v_mfma_f32_16x16x32_bf16 v[8:11], v[206:209], v[214:217], v[8:11]
	v_mfma_f32_16x16x32_bf16 v[12:15], v[178:181], v[214:217], v[12:15]
	s_setprio 1
	s_andn2_b64 vcc, exec, s[16:17]
	s_barrier
	s_cbranch_vccnz .LBB0_1142
	s_barrier
